# GEMM loops rotated (7.11): counter update, exit test and back branch moved in front of the last barrier, MMA8 block becomes the loop head with an exit-path copy
# speedup vs baseline: 1.0100x; 1.0100x over previous
.LBB0_36:
	s_add_u32 s8, s8, 0x100
	s_addc_u32 s9, s9, 0
	s_add_u32 s46, s6, 0x160080
	v_mov_b32_e32 v2, 0
	s_addc_u32 s47, s7, 0
	s_mov_b32 s6, -2
	v_mov_b32_e32 v3, v2
	v_mov_b32_e32 v4, v2
	v_mov_b32_e32 v5, v2
	v_mov_b32_e32 v6, v2
	v_mov_b32_e32 v7, v2
	v_mov_b32_e32 v8, v2
	v_mov_b32_e32 v9, v2
	v_mov_b32_e32 v10, v2
	v_mov_b32_e32 v11, v2
	v_mov_b32_e32 v12, v2
	v_mov_b32_e32 v13, v2
	v_mov_b32_e32 v18, v2
	v_mov_b32_e32 v19, v2
	v_mov_b32_e32 v20, v2
	v_mov_b32_e32 v21, v2
	v_mov_b32_e32 v26, v2
	v_mov_b32_e32 v27, v2
	v_mov_b32_e32 v28, v2
	v_mov_b32_e32 v29, v2
	v_mov_b32_e32 v34, v2
	v_mov_b32_e32 v35, v2
	v_mov_b32_e32 v36, v2
	v_mov_b32_e32 v37, v2
	v_mov_b32_e32 v42, v2
	v_mov_b32_e32 v43, v2
	v_mov_b32_e32 v44, v2
	v_mov_b32_e32 v45, v2
	v_mov_b32_e32 v50, v2
	v_mov_b32_e32 v51, v2
	v_mov_b32_e32 v52, v2
	v_mov_b32_e32 v53, v2
	v_mov_b32_e32 v14, v2
	v_mov_b32_e32 v15, v2
	v_mov_b32_e32 v16, v2
	v_mov_b32_e32 v17, v2
	v_mov_b32_e32 v22, v2
	v_mov_b32_e32 v23, v2
	v_mov_b32_e32 v24, v2
	v_mov_b32_e32 v25, v2
	v_mov_b32_e32 v30, v2
	v_mov_b32_e32 v31, v2
	v_mov_b32_e32 v32, v2
	v_mov_b32_e32 v33, v2
	v_mov_b32_e32 v38, v2
	v_mov_b32_e32 v39, v2
	v_mov_b32_e32 v40, v2
	v_mov_b32_e32 v41, v2
	v_mov_b32_e32 v46, v2
	v_mov_b32_e32 v47, v2
	v_mov_b32_e32 v48, v2
	v_mov_b32_e32 v49, v2
	v_mov_b32_e32 v54, v2
	v_mov_b32_e32 v55, v2
	v_mov_b32_e32 v56, v2
	v_mov_b32_e32 v57, v2
	v_mov_b32_e32 v58, v2
	v_mov_b32_e32 v59, v2
	v_mov_b32_e32 v60, v2
	v_mov_b32_e32 v61, v2
	v_mov_b32_e32 v62, v2
	v_mov_b32_e32 v63, v2
	v_mov_b32_e32 v64, v2
	v_mov_b32_e32 v65, v2
	v_mov_b32_e32 v66, v2
	v_mov_b32_e32 v67, v2
	v_mov_b32_e32 v68, v2
	v_mov_b32_e32 v69, v2
	v_mov_b32_e32 v70, v2
	v_mov_b32_e32 v71, v2
	v_mov_b32_e32 v72, v2
	v_mov_b32_e32 v73, v2
	v_mov_b32_e32 v74, v2
	v_mov_b32_e32 v75, v2
	v_mov_b32_e32 v76, v2
	v_mov_b32_e32 v77, v2
	v_mov_b32_e32 v82, v2
	v_mov_b32_e32 v83, v2
	v_mov_b32_e32 v84, v2
	v_mov_b32_e32 v85, v2
	v_mov_b32_e32 v90, v2
	v_mov_b32_e32 v91, v2
	v_mov_b32_e32 v92, v2
	v_mov_b32_e32 v93, v2
	v_mov_b32_e32 v98, v2
	v_mov_b32_e32 v99, v2
	v_mov_b32_e32 v100, v2
	v_mov_b32_e32 v101, v2
	v_mov_b32_e32 v106, v2
	v_mov_b32_e32 v107, v2
	v_mov_b32_e32 v108, v2
	v_mov_b32_e32 v109, v2
	v_mov_b32_e32 v114, v2
	v_mov_b32_e32 v115, v2
	v_mov_b32_e32 v116, v2
	v_mov_b32_e32 v117, v2
	v_mov_b32_e32 v78, v2
	v_mov_b32_e32 v79, v2
	v_mov_b32_e32 v80, v2
	v_mov_b32_e32 v81, v2
	v_mov_b32_e32 v86, v2
	v_mov_b32_e32 v87, v2
	v_mov_b32_e32 v88, v2
	v_mov_b32_e32 v89, v2
	v_mov_b32_e32 v94, v2
	v_mov_b32_e32 v95, v2
	v_mov_b32_e32 v96, v2
	v_mov_b32_e32 v97, v2
	v_mov_b32_e32 v102, v2
	v_mov_b32_e32 v103, v2
	v_mov_b32_e32 v104, v2
	v_mov_b32_e32 v105, v2
	v_mov_b32_e32 v110, v2
	v_mov_b32_e32 v111, v2
	v_mov_b32_e32 v112, v2
	v_mov_b32_e32 v113, v2
	v_mov_b32_e32 v118, v2
	v_mov_b32_e32 v119, v2
	v_mov_b32_e32 v120, v2
	v_mov_b32_e32 v121, v2
	v_mov_b32_e32 v122, v2
	v_mov_b32_e32 v123, v2
	v_mov_b32_e32 v124, v2
	v_mov_b32_e32 v125, v2
	v_mov_b32_e32 v126, v2
	v_mov_b32_e32 v127, v2
	v_mov_b32_e32 v128, v2
	v_mov_b32_e32 v129, v2
	s_branch .Lrot_enter_10
.LBB0_37:
	s_setprio 1
	s_barrier
	v_mfma_f32_16x16x32_bf16 v[50:53], v[188:191], v[156:159], v[50:53]
	v_mfma_f32_16x16x32_bf16 v[42:45], v[196:199], v[156:159], v[42:45]
	v_mfma_f32_16x16x32_bf16 v[34:37], v[188:191], v[164:167], v[34:37]
	v_mfma_f32_16x16x32_bf16 v[26:29], v[196:199], v[164:167], v[26:29]
	v_mfma_f32_16x16x32_bf16 v[18:21], v[188:191], v[172:175], v[18:21]
	v_mfma_f32_16x16x32_bf16 v[10:13], v[196:199], v[172:175], v[10:13]
	v_mfma_f32_16x16x32_bf16 v[6:9], v[188:191], v[180:183], v[6:9]
	v_mfma_f32_16x16x32_bf16 v[2:5], v[196:199], v[180:183], v[2:5]
	v_mfma_f32_16x16x32_bf16 v[50:53], v[192:195], v[160:163], v[50:53]
	v_mfma_f32_16x16x32_bf16 v[42:45], v[200:203], v[160:163], v[42:45]
	v_mfma_f32_16x16x32_bf16 v[34:37], v[192:195], v[168:171], v[34:37]
	v_mfma_f32_16x16x32_bf16 v[26:29], v[200:203], v[168:171], v[26:29]
	v_mfma_f32_16x16x32_bf16 v[18:21], v[192:195], v[176:179], v[18:21]
	v_mfma_f32_16x16x32_bf16 v[10:13], v[200:203], v[176:179], v[10:13]
	v_mfma_f32_16x16x32_bf16 v[6:9], v[192:195], v[184:187], v[6:9]
	v_mfma_f32_16x16x32_bf16 v[2:5], v[200:203], v[184:187], v[2:5]
	s_barrier
	s_setprio 0
.Lrot_enter_10:
	s_add_u32 s7, s46, 0xffea0080
	s_addc_u32 s78, s47, -1
	s_add_i32 s87, 0, 0x10000
	v_add_u32_e32 v132, s87, v135
	ds_read_b128 v[138:141], v132
	ds_read_b128 v[142:145], v132 offset:1024
	ds_read_b128 v[148:151], v132 offset:2048
	ds_read_b128 v[152:155], v132 offset:3072
	s_cmpk_eq_i32 s6, 0x54
	s_cselect_b32 s79, s43, s78
	s_cselect_b32 s78, s42, s7
	s_cselect_b32 s89, s45, s9
	s_cselect_b32 s88, s44, s8
	v_lshl_add_u64 v[132:133], s[46:47], 0, v[130:131]
	s_add_i32 m0, s54, 0xc000
	ds_read_b128 v[156:159], v136
	ds_read_b128 v[160:163], v136 offset:1024
	ds_read_b128 v[164:167], v136 offset:2048
	ds_read_b128 v[168:171], v136 offset:3072
	ds_read_b128 v[172:175], v136 offset:4096
	ds_read_b128 v[176:179], v136 offset:5120
	ds_read_b128 v[180:183], v136 offset:6144
	ds_read_b128 v[184:187], v136 offset:7168
	global_load_lds_dwordx4 v[132:133], off
	v_lshl_add_u64 v[132:133], v[132:133], 0, s[26:27]
	s_add_i32 m0, s54, 0xe000
	s_nop 0
	global_load_lds_dwordx4 v[132:133], off
	s_waitcnt lgkmcnt(8)
	s_setprio 1
	s_barrier
	s_waitcnt lgkmcnt(0)
	v_mfma_f32_16x16x32_bf16 v[126:129], v[138:141], v[156:159], v[126:129]
	v_mfma_f32_16x16x32_bf16 v[122:125], v[148:151], v[156:159], v[122:125]
	v_mfma_f32_16x16x32_bf16 v[118:121], v[138:141], v[164:167], v[118:121]
	v_mfma_f32_16x16x32_bf16 v[110:113], v[148:151], v[164:167], v[110:113]
	v_mfma_f32_16x16x32_bf16 v[102:105], v[138:141], v[172:175], v[102:105]
	v_mfma_f32_16x16x32_bf16 v[94:97], v[148:151], v[172:175], v[94:97]
	v_mfma_f32_16x16x32_bf16 v[86:89], v[138:141], v[180:183], v[86:89]
	v_mfma_f32_16x16x32_bf16 v[78:81], v[148:151], v[180:183], v[78:81]
	v_mfma_f32_16x16x32_bf16 v[126:129], v[142:145], v[160:163], v[126:129]
	v_mfma_f32_16x16x32_bf16 v[122:125], v[152:155], v[160:163], v[122:125]
	v_mfma_f32_16x16x32_bf16 v[118:121], v[142:145], v[168:171], v[118:121]
	v_mfma_f32_16x16x32_bf16 v[110:113], v[152:155], v[168:171], v[110:113]
	v_mfma_f32_16x16x32_bf16 v[102:105], v[142:145], v[176:179], v[102:105]
	v_mfma_f32_16x16x32_bf16 v[94:97], v[152:155], v[176:179], v[94:97]
	v_mfma_f32_16x16x32_bf16 v[86:89], v[142:145], v[184:187], v[86:89]
	v_mfma_f32_16x16x32_bf16 v[78:81], v[152:155], v[184:187], v[78:81]
	s_barrier
	s_setprio 0
	s_add_i32 s7, 0, 0x14000
	v_add_u32_e32 v132, s7, v135
	s_add_i32 s87, s87, s53
	ds_read_b128 v[188:191], v132
	ds_read_b128 v[192:195], v132 offset:1024
	ds_read_b128 v[196:199], v132 offset:2048
	ds_read_b128 v[200:203], v132 offset:3072
	v_lshl_add_u64 v[132:133], s[88:89], 0, v[0:1]
	s_mov_b32 m0, s87
	v_lshl_add_u64 v[204:205], v[132:133], 0, s[26:27]
	global_load_lds_dwordx4 v[132:133], off
	s_add_i32 m0, s87, 0x2000
	s_nop 0
	global_load_lds_dwordx4 v[204:205], off
	s_setprio 1
	s_barrier
	s_waitcnt lgkmcnt(0)
	v_mfma_f32_16x16x32_bf16 v[114:117], v[188:191], v[156:159], v[114:117]
	v_mfma_f32_16x16x32_bf16 v[106:109], v[196:199], v[156:159], v[106:109]
	v_mfma_f32_16x16x32_bf16 v[98:101], v[188:191], v[164:167], v[98:101]
	v_mfma_f32_16x16x32_bf16 v[90:93], v[196:199], v[164:167], v[90:93]
	v_mfma_f32_16x16x32_bf16 v[82:85], v[188:191], v[172:175], v[82:85]
	v_mfma_f32_16x16x32_bf16 v[74:77], v[196:199], v[172:175], v[74:77]
	v_mfma_f32_16x16x32_bf16 v[70:73], v[188:191], v[180:183], v[70:73]
	v_mfma_f32_16x16x32_bf16 v[66:69], v[196:199], v[180:183], v[66:69]
	v_mfma_f32_16x16x32_bf16 v[114:117], v[192:195], v[160:163], v[114:117]
	v_mfma_f32_16x16x32_bf16 v[106:109], v[200:203], v[160:163], v[106:109]
	v_mfma_f32_16x16x32_bf16 v[98:101], v[192:195], v[168:171], v[98:101]
	v_mfma_f32_16x16x32_bf16 v[90:93], v[200:203], v[168:171], v[90:93]
	v_mfma_f32_16x16x32_bf16 v[82:85], v[192:195], v[176:179], v[82:85]
	v_mfma_f32_16x16x32_bf16 v[74:77], v[200:203], v[176:179], v[74:77]
	v_mfma_f32_16x16x32_bf16 v[70:73], v[192:195], v[184:187], v[70:73]
	v_mfma_f32_16x16x32_bf16 v[66:69], v[200:203], v[184:187], v[66:69]
	s_barrier
	s_setprio 0
	s_mov_b32 m0, s54
	v_lshl_add_u64 v[204:205], s[78:79], 0, v[0:1]
	ds_read_b128 v[156:159], v136 offset:16384
	ds_read_b128 v[160:163], v136 offset:17408
	ds_read_b128 v[164:167], v136 offset:18432
	ds_read_b128 v[168:171], v136 offset:19456
	ds_read_b128 v[172:175], v136 offset:20480
	ds_read_b128 v[176:179], v136 offset:21504
	ds_read_b128 v[180:183], v136 offset:22528
	ds_read_b128 v[184:187], v136 offset:23552
	global_load_lds_dwordx4 v[204:205], off
	v_lshl_add_u64 v[206:207], v[204:205], 0, s[26:27]
	s_mov_b32 m0, s55
	s_nop 0
	global_load_lds_dwordx4 v[206:207], off
	s_setprio 1
	s_barrier
	s_waitcnt lgkmcnt(0)
	v_mfma_f32_16x16x32_bf16 v[62:65], v[138:141], v[156:159], v[62:65]
	v_mfma_f32_16x16x32_bf16 v[58:61], v[148:151], v[156:159], v[58:61]
	v_mfma_f32_16x16x32_bf16 v[54:57], v[138:141], v[164:167], v[54:57]
	v_mfma_f32_16x16x32_bf16 v[46:49], v[148:151], v[164:167], v[46:49]
	v_mfma_f32_16x16x32_bf16 v[38:41], v[138:141], v[172:175], v[38:41]
	v_mfma_f32_16x16x32_bf16 v[30:33], v[148:151], v[172:175], v[30:33]
	v_mfma_f32_16x16x32_bf16 v[22:25], v[138:141], v[180:183], v[22:25]
	v_mfma_f32_16x16x32_bf16 v[14:17], v[148:151], v[180:183], v[14:17]
	v_mfma_f32_16x16x32_bf16 v[62:65], v[142:145], v[160:163], v[62:65]
	v_mfma_f32_16x16x32_bf16 v[58:61], v[152:155], v[160:163], v[58:61]
	v_mfma_f32_16x16x32_bf16 v[54:57], v[142:145], v[168:171], v[54:57]
	v_mfma_f32_16x16x32_bf16 v[46:49], v[152:155], v[168:171], v[46:49]
	v_mfma_f32_16x16x32_bf16 v[38:41], v[142:145], v[176:179], v[38:41]
	v_mfma_f32_16x16x32_bf16 v[30:33], v[152:155], v[176:179], v[30:33]
	v_mfma_f32_16x16x32_bf16 v[22:25], v[142:145], v[184:187], v[22:25]
	v_mfma_f32_16x16x32_bf16 v[14:17], v[152:155], v[184:187], v[14:17]
	s_barrier
	s_setprio 0
	s_add_i32 s7, s7, s53
	v_lshl_add_u64 v[138:139], v[132:133], 0, s[28:29]
	s_mov_b32 m0, s7
	s_nop 0
	global_load_lds_dwordx4 v[138:139], off
	v_lshl_add_u64 v[138:139], v[132:133], 0, s[30:31]
	s_add_i32 m0, s7, 0x2000
	s_nop 0
	global_load_lds_dwordx4 v[138:139], off
	v_lshl_add_u64 v[230:231], v[204:205], 0, s[28:29]
	s_mov_b32 m0, s56
	s_nop 0
	global_load_lds_dwordx4 v[230:231], off
	v_lshl_add_u64 v[230:231], v[204:205], 0, s[30:31]
	s_mov_b32 m0, s57
	s_nop 0
	global_load_lds_dwordx4 v[230:231], off
	s_waitcnt vmcnt(8)
	s_setprio 1
	s_barrier
	v_mfma_f32_16x16x32_bf16 v[50:53], v[188:191], v[156:159], v[50:53]
	v_mfma_f32_16x16x32_bf16 v[42:45], v[196:199], v[156:159], v[42:45]
	v_mfma_f32_16x16x32_bf16 v[34:37], v[188:191], v[164:167], v[34:37]
	v_mfma_f32_16x16x32_bf16 v[26:29], v[196:199], v[164:167], v[26:29]
	v_mfma_f32_16x16x32_bf16 v[18:21], v[188:191], v[172:175], v[18:21]
	v_mfma_f32_16x16x32_bf16 v[10:13], v[196:199], v[172:175], v[10:13]
	v_mfma_f32_16x16x32_bf16 v[6:9], v[188:191], v[180:183], v[6:9]
	v_mfma_f32_16x16x32_bf16 v[2:5], v[196:199], v[180:183], v[2:5]
	v_mfma_f32_16x16x32_bf16 v[50:53], v[192:195], v[160:163], v[50:53]
	v_mfma_f32_16x16x32_bf16 v[42:45], v[200:203], v[160:163], v[42:45]
	v_mfma_f32_16x16x32_bf16 v[34:37], v[192:195], v[168:171], v[34:37]
	v_mfma_f32_16x16x32_bf16 v[26:29], v[200:203], v[168:171], v[26:29]
	v_mfma_f32_16x16x32_bf16 v[18:21], v[192:195], v[176:179], v[18:21]
	v_mfma_f32_16x16x32_bf16 v[10:13], v[200:203], v[176:179], v[10:13]
	v_mfma_f32_16x16x32_bf16 v[6:9], v[192:195], v[184:187], v[6:9]
	v_mfma_f32_16x16x32_bf16 v[2:5], v[200:203], v[184:187], v[2:5]
	s_barrier
	s_setprio 0
	s_add_i32 s7, 0, 0x18000
	v_add_u32_e32 v137, s7, v135
	ds_read_b128 v[138:141], v137
	ds_read_b128 v[142:145], v137 offset:1024
	ds_read_b128 v[148:151], v137 offset:2048
	ds_read_b128 v[152:155], v137 offset:3072
	ds_read_b128 v[156:159], v136 offset:32768
	ds_read_b128 v[160:163], v136 offset:33792
	ds_read_b128 v[164:167], v136 offset:34816
	ds_read_b128 v[168:171], v136 offset:35840
	ds_read_b128 v[172:175], v136 offset:36864
	ds_read_b128 v[176:179], v136 offset:37888
	ds_read_b128 v[180:183], v136 offset:38912
	ds_read_b128 v[184:187], v136 offset:39936
	s_waitcnt lgkmcnt(8)
	s_setprio 1
	s_barrier
	s_waitcnt lgkmcnt(0)
	v_mfma_f32_16x16x32_bf16 v[126:129], v[138:141], v[156:159], v[126:129]
	v_mfma_f32_16x16x32_bf16 v[122:125], v[148:151], v[156:159], v[122:125]
	v_mfma_f32_16x16x32_bf16 v[118:121], v[138:141], v[164:167], v[118:121]
	v_mfma_f32_16x16x32_bf16 v[110:113], v[148:151], v[164:167], v[110:113]
	v_mfma_f32_16x16x32_bf16 v[102:105], v[138:141], v[172:175], v[102:105]
	v_mfma_f32_16x16x32_bf16 v[94:97], v[148:151], v[172:175], v[94:97]
	v_mfma_f32_16x16x32_bf16 v[86:89], v[138:141], v[180:183], v[86:89]
	v_mfma_f32_16x16x32_bf16 v[78:81], v[148:151], v[180:183], v[78:81]
	v_mfma_f32_16x16x32_bf16 v[126:129], v[142:145], v[160:163], v[126:129]
	v_mfma_f32_16x16x32_bf16 v[122:125], v[152:155], v[160:163], v[122:125]
	v_mfma_f32_16x16x32_bf16 v[118:121], v[142:145], v[168:171], v[118:121]
	v_mfma_f32_16x16x32_bf16 v[110:113], v[152:155], v[168:171], v[110:113]
	v_mfma_f32_16x16x32_bf16 v[102:105], v[142:145], v[176:179], v[102:105]
	v_mfma_f32_16x16x32_bf16 v[94:97], v[152:155], v[176:179], v[94:97]
	v_mfma_f32_16x16x32_bf16 v[86:89], v[142:145], v[184:187], v[86:89]
	v_mfma_f32_16x16x32_bf16 v[78:81], v[152:155], v[184:187], v[78:81]
	s_barrier
	s_setprio 0
	s_add_i32 s78, 0, 0x1c000
	s_add_i32 s7, s7, s53
	v_add_u32_e32 v137, s78, v135
	v_lshl_add_u64 v[206:207], v[132:133], 0, s[34:35]
	s_mov_b32 m0, s7
	ds_read_b128 v[188:191], v137
	ds_read_b128 v[192:195], v137 offset:1024
	ds_read_b128 v[196:199], v137 offset:2048
	ds_read_b128 v[200:203], v137 offset:3072
	global_load_lds_dwordx4 v[206:207], off
	v_lshl_add_u64 v[206:207], v[132:133], 0, s[36:37]
	s_add_i32 m0, s7, 0x2000
	s_nop 0
	global_load_lds_dwordx4 v[206:207], off
	s_setprio 1
	s_barrier
	s_waitcnt lgkmcnt(0)
	v_mfma_f32_16x16x32_bf16 v[114:117], v[188:191], v[156:159], v[114:117]
	v_mfma_f32_16x16x32_bf16 v[106:109], v[196:199], v[156:159], v[106:109]
	v_mfma_f32_16x16x32_bf16 v[98:101], v[188:191], v[164:167], v[98:101]
	v_mfma_f32_16x16x32_bf16 v[90:93], v[196:199], v[164:167], v[90:93]
	v_mfma_f32_16x16x32_bf16 v[82:85], v[188:191], v[172:175], v[82:85]
	v_mfma_f32_16x16x32_bf16 v[74:77], v[196:199], v[172:175], v[74:77]
	v_mfma_f32_16x16x32_bf16 v[70:73], v[188:191], v[180:183], v[70:73]
	v_mfma_f32_16x16x32_bf16 v[66:69], v[196:199], v[180:183], v[66:69]
	v_mfma_f32_16x16x32_bf16 v[114:117], v[192:195], v[160:163], v[114:117]
	v_mfma_f32_16x16x32_bf16 v[106:109], v[200:203], v[160:163], v[106:109]
	v_mfma_f32_16x16x32_bf16 v[98:101], v[192:195], v[168:171], v[98:101]
	v_mfma_f32_16x16x32_bf16 v[90:93], v[200:203], v[168:171], v[90:93]
	v_mfma_f32_16x16x32_bf16 v[82:85], v[192:195], v[176:179], v[82:85]
	v_mfma_f32_16x16x32_bf16 v[74:77], v[200:203], v[176:179], v[74:77]
	v_mfma_f32_16x16x32_bf16 v[70:73], v[192:195], v[184:187], v[70:73]
	v_mfma_f32_16x16x32_bf16 v[66:69], v[200:203], v[184:187], v[66:69]
	s_barrier
	s_setprio 0
	s_mov_b32 m0, s62
	v_lshl_add_u64 v[206:207], v[204:205], 0, s[34:35]
	ds_read_b128 v[156:159], v136 offset:49152
	ds_read_b128 v[160:163], v136 offset:50176
	ds_read_b128 v[164:167], v136 offset:51200
	ds_read_b128 v[168:171], v136 offset:52224
	ds_read_b128 v[172:175], v136 offset:53248
	ds_read_b128 v[176:179], v136 offset:54272
	ds_read_b128 v[180:183], v136 offset:55296
	ds_read_b128 v[184:187], v136 offset:56320
	global_load_lds_dwordx4 v[206:207], off
	v_lshl_add_u64 v[204:205], v[204:205], 0, s[36:37]
	s_mov_b32 m0, s63
	s_nop 0
	global_load_lds_dwordx4 v[204:205], off
	s_setprio 1
	s_barrier
	s_waitcnt lgkmcnt(0)
	v_mfma_f32_16x16x32_bf16 v[62:65], v[138:141], v[156:159], v[62:65]
	v_mfma_f32_16x16x32_bf16 v[58:61], v[148:151], v[156:159], v[58:61]
	v_mfma_f32_16x16x32_bf16 v[54:57], v[138:141], v[164:167], v[54:57]
	v_mfma_f32_16x16x32_bf16 v[46:49], v[148:151], v[164:167], v[46:49]
	v_mfma_f32_16x16x32_bf16 v[38:41], v[138:141], v[172:175], v[38:41]
	v_mfma_f32_16x16x32_bf16 v[30:33], v[148:151], v[172:175], v[30:33]
	v_mfma_f32_16x16x32_bf16 v[22:25], v[138:141], v[180:183], v[22:25]
	v_mfma_f32_16x16x32_bf16 v[14:17], v[148:151], v[180:183], v[14:17]
	v_mfma_f32_16x16x32_bf16 v[62:65], v[142:145], v[160:163], v[62:65]
	v_mfma_f32_16x16x32_bf16 v[58:61], v[152:155], v[160:163], v[58:61]
	v_mfma_f32_16x16x32_bf16 v[54:57], v[142:145], v[168:171], v[54:57]
	v_mfma_f32_16x16x32_bf16 v[46:49], v[152:155], v[168:171], v[46:49]
	v_mfma_f32_16x16x32_bf16 v[38:41], v[142:145], v[176:179], v[38:41]
	v_mfma_f32_16x16x32_bf16 v[30:33], v[152:155], v[176:179], v[30:33]
	v_mfma_f32_16x16x32_bf16 v[22:25], v[142:145], v[184:187], v[22:25]
	v_mfma_f32_16x16x32_bf16 v[14:17], v[152:155], v[184:187], v[14:17]
	s_barrier
	s_setprio 0
	s_add_i32 s7, s78, s53
	v_lshl_add_u64 v[138:139], v[132:133], 0, s[18:19]
	s_mov_b32 m0, s7
	v_lshl_add_u64 v[132:133], v[132:133], 0, s[14:15]
	global_load_lds_dwordx4 v[138:139], off
	s_add_i32 m0, s7, 0x2000
	s_nop 0
	global_load_lds_dwordx4 v[132:133], off
	s_waitcnt vmcnt(6)
	s_add_i32 s6, s6, 2
	s_add_u32 s8, s8, 0x100
	s_addc_u32 s9, s9, 0
	s_add_u32 s46, s46, 0x100
	s_addc_u32 s47, s47, 0
	s_cmpk_gt_u32 s6, 0x55
	s_cbranch_scc0 .LBB0_37
	s_setprio 1
	s_barrier
	v_mfma_f32_16x16x32_bf16 v[50:53], v[188:191], v[156:159], v[50:53]
	v_mfma_f32_16x16x32_bf16 v[42:45], v[196:199], v[156:159], v[42:45]
	v_mfma_f32_16x16x32_bf16 v[34:37], v[188:191], v[164:167], v[34:37]
	v_mfma_f32_16x16x32_bf16 v[26:29], v[196:199], v[164:167], v[26:29]
	v_mfma_f32_16x16x32_bf16 v[18:21], v[188:191], v[172:175], v[18:21]
	v_mfma_f32_16x16x32_bf16 v[10:13], v[196:199], v[172:175], v[10:13]
	v_mfma_f32_16x16x32_bf16 v[6:9], v[188:191], v[180:183], v[6:9]
	v_mfma_f32_16x16x32_bf16 v[2:5], v[196:199], v[180:183], v[2:5]
	v_mfma_f32_16x16x32_bf16 v[50:53], v[192:195], v[160:163], v[50:53]
	v_mfma_f32_16x16x32_bf16 v[42:45], v[200:203], v[160:163], v[42:45]
	v_mfma_f32_16x16x32_bf16 v[34:37], v[192:195], v[168:171], v[34:37]
	v_mfma_f32_16x16x32_bf16 v[26:29], v[200:203], v[168:171], v[26:29]
	v_mfma_f32_16x16x32_bf16 v[18:21], v[192:195], v[176:179], v[18:21]
	v_mfma_f32_16x16x32_bf16 v[10:13], v[200:203], v[176:179], v[10:13]
	v_mfma_f32_16x16x32_bf16 v[6:9], v[192:195], v[184:187], v[6:9]
	v_mfma_f32_16x16x32_bf16 v[2:5], v[200:203], v[184:187], v[2:5]
	s_barrier
	s_setprio 0
	v_mov_b32_e32 v137, v134
	s_lshl_b32 s6, s86, 8
	v_ashrrev_i32_e32 v132, 2, v137
	s_or_b32 s6, s6, s59
	v_and_b32_e32 v132, -4, v132
	v_add_u32_e32 v132, s6, v132
	s_lshl_b32 s6, s85, 8
	s_add_i32 s6, s6, s58
	v_and_or_b32 v188, v137, 15, s6
	v_ashrrev_i32_e32 v189, 31, v188
	v_ashrrev_i32_e32 v133, 31, v132
	v_lshlrev_b64 v[206:207], 13, v[188:189]
	v_or_b32_e32 v156, 16, v188
	v_or_b32_e32 v172, 32, v188
	v_or_b32_e32 v188, 48, v188
	v_lshlrev_b64 v[132:133], 2, v[132:133]
	v_ashrrev_i32_e32 v157, 31, v156
	v_ashrrev_i32_e32 v173, 31, v172
	v_ashrrev_i32_e32 v189, 31, v188
	v_lshl_add_u64 v[204:205], s[4:5], 0, v[132:133]
	v_lshlrev_b64 v[208:209], 13, v[156:157]
	v_lshlrev_b64 v[210:211], 13, v[172:173]
	v_lshlrev_b64 v[212:213], 13, v[188:189]
	v_lshl_add_u64 v[152:153], v[204:205], 0, v[206:207]
	v_lshl_add_u64 v[168:169], v[204:205], 0, v[208:209]
	v_lshl_add_u64 v[184:185], v[204:205], 0, v[210:211]
	v_lshl_add_u64 v[200:201], v[204:205], 0, v[212:213]
	global_load_dwordx4 v[138:141], v[152:153], off
	global_load_dwordx4 v[142:145], v[152:153], off offset:64
	global_load_dwordx4 v[148:151], v[152:153], off offset:512
	s_nop 0
	global_load_dwordx4 v[152:155], v[152:153], off offset:576
	s_nop 0
	global_load_dwordx4 v[156:159], v[168:169], off
	global_load_dwordx4 v[160:163], v[168:169], off offset:64
	global_load_dwordx4 v[164:167], v[168:169], off offset:512
	s_nop 0
	global_load_dwordx4 v[168:171], v[168:169], off offset:576
	s_nop 0
	global_load_dwordx4 v[172:175], v[184:185], off
	global_load_dwordx4 v[176:179], v[184:185], off offset:64
	global_load_dwordx4 v[180:183], v[184:185], off offset:512
	s_nop 0
	global_load_dwordx4 v[184:187], v[184:185], off offset:576
	s_nop 0
	global_load_dwordx4 v[188:191], v[200:201], off
	global_load_dwordx4 v[192:195], v[200:201], off offset:64
	global_load_dwordx4 v[196:199], v[200:201], off offset:512
	s_nop 0
	global_load_dwordx4 v[200:203], v[200:201], off offset:576
	s_waitcnt vmcnt(0) lgkmcnt(0)
	v_pk_fma_f32 v[126:127], v[126:127], 0.5, v[138:139] op_sel_hi:[1,0,1]
	v_lshl_add_u64 v[138:139], s[4:5], 0, v[206:207]
	v_lshl_add_u64 v[138:139], v[138:139], 0, v[132:133]
	v_pk_fma_f32 v[116:117], v[116:117], 0.5, v[150:151] op_sel_hi:[1,0,1]
	v_pk_fma_f32 v[114:115], v[114:115], 0.5, v[148:149] op_sel_hi:[1,0,1]
	global_store_dwordx4 v[138:139], v[114:117], off offset:512
	v_pk_fma_f32 v[100:101], v[100:101], 0.5, v[166:167] op_sel_hi:[1,0,1]
	v_pk_fma_f32 v[98:99], v[98:99], 0.5, v[164:165] op_sel_hi:[1,0,1]
	v_lshl_add_u64 v[114:115], s[4:5], 0, v[208:209]
	v_lshl_add_u64 v[114:115], v[114:115], 0, v[132:133]
	global_store_dwordx4 v[114:115], v[98:101], off offset:512
	v_pk_fma_f32 v[84:85], v[84:85], 0.5, v[182:183] op_sel_hi:[1,0,1]
	v_pk_fma_f32 v[82:83], v[82:83], 0.5, v[180:181] op_sel_hi:[1,0,1]
	v_lshl_add_u64 v[98:99], s[4:5], 0, v[210:211]
	v_lshl_add_u64 v[98:99], v[98:99], 0, v[132:133]
	v_pk_fma_f32 v[108:109], v[108:109], 0.5, v[154:155] op_sel_hi:[1,0,1]
	v_pk_fma_f32 v[106:107], v[106:107], 0.5, v[152:153] op_sel_hi:[1,0,1]
	v_pk_fma_f32 v[92:93], v[92:93], 0.5, v[170:171] op_sel_hi:[1,0,1]
	v_pk_fma_f32 v[90:91], v[90:91], 0.5, v[168:169] op_sel_hi:[1,0,1]
	global_store_dwordx4 v[98:99], v[82:85], off offset:512
	v_pk_fma_f32 v[76:77], v[76:77], 0.5, v[186:187] op_sel_hi:[1,0,1]
	v_pk_fma_f32 v[74:75], v[74:75], 0.5, v[184:185] op_sel_hi:[1,0,1]
	v_lshl_add_u64 v[82:83], s[4:5], 0, v[212:213]
	global_store_dwordx4 v[138:139], v[106:109], off offset:576
	global_store_dwordx4 v[114:115], v[90:93], off offset:576
	global_store_dwordx4 v[98:99], v[74:77], off offset:576
	v_pk_fma_f32 v[108:109], v[120:121], 0.5, v[158:159] op_sel_hi:[1,0,1]
	v_pk_fma_f32 v[106:107], v[118:119], 0.5, v[156:157] op_sel_hi:[1,0,1]
	v_pk_fma_f32 v[92:93], v[104:105], 0.5, v[174:175] op_sel_hi:[1,0,1]
	v_pk_fma_f32 v[90:91], v[102:103], 0.5, v[172:173] op_sel_hi:[1,0,1]
	v_pk_fma_f32 v[76:77], v[88:89], 0.5, v[190:191] op_sel_hi:[1,0,1]
	v_pk_fma_f32 v[74:75], v[86:87], 0.5, v[188:189] op_sel_hi:[1,0,1]
	v_lshl_add_u64 v[82:83], v[82:83], 0, v[132:133]
	v_pk_fma_f32 v[128:129], v[128:129], 0.5, v[140:141] op_sel_hi:[1,0,1]
	v_pk_fma_f32 v[124:125], v[124:125], 0.5, v[144:145] op_sel_hi:[1,0,1]
	v_pk_fma_f32 v[122:123], v[122:123], 0.5, v[142:143] op_sel_hi:[1,0,1]
	global_store_dwordx4 v[114:115], v[106:109], off
	global_store_dwordx4 v[98:99], v[90:93], off
	global_store_dwordx4 v[82:83], v[74:77], off
	v_pk_fma_f32 v[108:109], v[112:113], 0.5, v[162:163] op_sel_hi:[1,0,1]
	v_pk_fma_f32 v[106:107], v[110:111], 0.5, v[160:161] op_sel_hi:[1,0,1]
	v_pk_fma_f32 v[92:93], v[96:97], 0.5, v[178:179] op_sel_hi:[1,0,1]
	v_pk_fma_f32 v[90:91], v[94:95], 0.5, v[176:177] op_sel_hi:[1,0,1]
	v_pk_fma_f32 v[76:77], v[80:81], 0.5, v[194:195] op_sel_hi:[1,0,1]
	v_pk_fma_f32 v[74:75], v[78:79], 0.5, v[192:193] op_sel_hi:[1,0,1]
	v_pk_fma_f32 v[72:73], v[72:73], 0.5, v[198:199] op_sel_hi:[1,0,1]
	v_pk_fma_f32 v[70:71], v[70:71], 0.5, v[196:197] op_sel_hi:[1,0,1]
	v_pk_fma_f32 v[68:69], v[68:69], 0.5, v[202:203] op_sel_hi:[1,0,1]
	v_pk_fma_f32 v[66:67], v[66:67], 0.5, v[200:201] op_sel_hi:[1,0,1]
	global_store_dwordx4 v[138:139], v[126:129], off
	global_store_dwordx4 v[138:139], v[122:125], off offset:64
	global_store_dwordx4 v[114:115], v[106:109], off offset:64
	global_store_dwordx4 v[98:99], v[90:93], off offset:64
	global_store_dwordx4 v[82:83], v[74:77], off offset:64
	global_store_dwordx4 v[82:83], v[70:73], off offset:512
	global_store_dwordx4 v[82:83], v[66:69], off offset:576
	s_mov_b64 s[6:7], 0x120000
	v_lshl_add_u64 v[140:141], v[206:207], 0, s[6:7]
	s_mov_b64 s[6:7], 0x140000
	v_lshl_add_u64 v[138:139], v[206:207], 0, s[0:1]
	v_lshl_add_u64 v[142:143], v[206:207], 0, s[6:7]
	v_lshl_add_u64 v[144:145], v[206:207], 0, s[28:29]
	v_lshl_add_u64 v[78:79], v[204:205], 0, v[138:139]
	v_lshl_add_u64 v[94:95], v[204:205], 0, v[140:141]
	v_lshl_add_u64 v[110:111], v[204:205], 0, v[142:143]
	v_lshl_add_u64 v[126:127], v[204:205], 0, v[144:145]
	global_load_dwordx4 v[66:69], v[78:79], off
	global_load_dwordx4 v[70:73], v[78:79], off offset:64
	global_load_dwordx4 v[74:77], v[78:79], off offset:512
	s_nop 0
	global_load_dwordx4 v[78:81], v[78:79], off offset:576
	s_nop 0
	global_load_dwordx4 v[82:85], v[94:95], off
	global_load_dwordx4 v[86:89], v[94:95], off offset:64
	global_load_dwordx4 v[90:93], v[94:95], off offset:512
	s_nop 0
	global_load_dwordx4 v[94:97], v[94:95], off offset:576
	s_nop 0
	global_load_dwordx4 v[98:101], v[110:111], off
	global_load_dwordx4 v[102:105], v[110:111], off offset:64
	global_load_dwordx4 v[106:109], v[110:111], off offset:512
	s_nop 0
	global_load_dwordx4 v[110:113], v[110:111], off offset:576
	s_nop 0
	global_load_dwordx4 v[114:117], v[126:127], off
	global_load_dwordx4 v[118:121], v[126:127], off offset:64
	global_load_dwordx4 v[122:125], v[126:127], off offset:512
	s_nop 0
	global_load_dwordx4 v[126:129], v[126:127], off offset:576
	s_waitcnt vmcnt(0) lgkmcnt(0)
	v_pk_fma_f32 v[62:63], v[62:63], 0.5, v[66:67] op_sel_hi:[1,0,1]
	v_lshl_add_u64 v[66:67], s[4:5], 0, v[138:139]
	v_lshl_add_u64 v[66:67], v[66:67], 0, v[132:133]
	v_pk_fma_f32 v[52:53], v[52:53], 0.5, v[76:77] op_sel_hi:[1,0,1]
	v_pk_fma_f32 v[50:51], v[50:51], 0.5, v[74:75] op_sel_hi:[1,0,1]
	global_store_dwordx4 v[66:67], v[50:53], off offset:512
	v_pk_fma_f32 v[36:37], v[36:37], 0.5, v[92:93] op_sel_hi:[1,0,1]
	v_pk_fma_f32 v[34:35], v[34:35], 0.5, v[90:91] op_sel_hi:[1,0,1]
	v_lshl_add_u64 v[50:51], s[4:5], 0, v[140:141]
	v_lshl_add_u64 v[50:51], v[50:51], 0, v[132:133]
	global_store_dwordx4 v[50:51], v[34:37], off offset:512
	v_pk_fma_f32 v[20:21], v[20:21], 0.5, v[108:109] op_sel_hi:[1,0,1]
	v_pk_fma_f32 v[18:19], v[18:19], 0.5, v[106:107] op_sel_hi:[1,0,1]
	v_lshl_add_u64 v[34:35], s[4:5], 0, v[142:143]
	v_lshl_add_u64 v[34:35], v[34:35], 0, v[132:133]
	v_pk_fma_f32 v[44:45], v[44:45], 0.5, v[80:81] op_sel_hi:[1,0,1]
	v_pk_fma_f32 v[42:43], v[42:43], 0.5, v[78:79] op_sel_hi:[1,0,1]
	v_pk_fma_f32 v[28:29], v[28:29], 0.5, v[96:97] op_sel_hi:[1,0,1]
	v_pk_fma_f32 v[26:27], v[26:27], 0.5, v[94:95] op_sel_hi:[1,0,1]
	global_store_dwordx4 v[34:35], v[18:21], off offset:512
	v_pk_fma_f32 v[12:13], v[12:13], 0.5, v[112:113] op_sel_hi:[1,0,1]
	v_pk_fma_f32 v[10:11], v[10:11], 0.5, v[110:111] op_sel_hi:[1,0,1]
	v_lshl_add_u64 v[18:19], s[4:5], 0, v[144:145]
	global_store_dwordx4 v[66:67], v[42:45], off offset:576
	global_store_dwordx4 v[50:51], v[26:29], off offset:576
	global_store_dwordx4 v[34:35], v[10:13], off offset:576
	v_pk_fma_f32 v[44:45], v[56:57], 0.5, v[84:85] op_sel_hi:[1,0,1]
	v_pk_fma_f32 v[42:43], v[54:55], 0.5, v[82:83] op_sel_hi:[1,0,1]
	v_pk_fma_f32 v[28:29], v[40:41], 0.5, v[100:101] op_sel_hi:[1,0,1]
	v_pk_fma_f32 v[26:27], v[38:39], 0.5, v[98:99] op_sel_hi:[1,0,1]
	v_pk_fma_f32 v[12:13], v[24:25], 0.5, v[116:117] op_sel_hi:[1,0,1]
	v_pk_fma_f32 v[10:11], v[22:23], 0.5, v[114:115] op_sel_hi:[1,0,1]
	v_lshl_add_u64 v[18:19], v[18:19], 0, v[132:133]
	v_pk_fma_f32 v[64:65], v[64:65], 0.5, v[68:69] op_sel_hi:[1,0,1]
	v_pk_fma_f32 v[60:61], v[60:61], 0.5, v[72:73] op_sel_hi:[1,0,1]
	v_pk_fma_f32 v[58:59], v[58:59], 0.5, v[70:71] op_sel_hi:[1,0,1]
	global_store_dwordx4 v[50:51], v[42:45], off
	global_store_dwordx4 v[34:35], v[26:29], off
	global_store_dwordx4 v[18:19], v[10:13], off
	v_pk_fma_f32 v[44:45], v[48:49], 0.5, v[88:89] op_sel_hi:[1,0,1]
	v_pk_fma_f32 v[42:43], v[46:47], 0.5, v[86:87] op_sel_hi:[1,0,1]
	v_pk_fma_f32 v[28:29], v[32:33], 0.5, v[104:105] op_sel_hi:[1,0,1]
	v_pk_fma_f32 v[26:27], v[30:31], 0.5, v[102:103] op_sel_hi:[1,0,1]
	v_pk_fma_f32 v[12:13], v[16:17], 0.5, v[120:121] op_sel_hi:[1,0,1]
	v_pk_fma_f32 v[10:11], v[14:15], 0.5, v[118:119] op_sel_hi:[1,0,1]
	v_pk_fma_f32 v[8:9], v[8:9], 0.5, v[124:125] op_sel_hi:[1,0,1]
	v_pk_fma_f32 v[6:7], v[6:7], 0.5, v[122:123] op_sel_hi:[1,0,1]
	v_pk_fma_f32 v[4:5], v[4:5], 0.5, v[128:129] op_sel_hi:[1,0,1]
	v_pk_fma_f32 v[2:3], v[2:3], 0.5, v[126:127] op_sel_hi:[1,0,1]
	global_store_dwordx4 v[66:67], v[62:65], off
	global_store_dwordx4 v[66:67], v[58:61], off offset:64
	global_store_dwordx4 v[50:51], v[42:45], off offset:64
	global_store_dwordx4 v[34:35], v[26:29], off offset:64
	global_store_dwordx4 v[18:19], v[10:13], off offset:64
	global_store_dwordx4 v[18:19], v[6:9], off offset:512
	global_store_dwordx4 v[18:19], v[2:5], off offset:576
	s_and_b64 vcc, exec, s[40:41]
	s_mov_b32 s85, s10
	s_mov_b32 s86, s11
	s_mov_b64 s[8:9], s[44:45]
	s_mov_b64 s[6:7], s[42:43]
	s_movk_i32 s89, 0x37ff
	s_mov_b32 s88, 0x16000
	s_cbranch_vccz .LBB0_30
	s_waitcnt vmcnt(0)
	s_cmpk_gt_u32 s48, 0xff
	s_cbranch_scc1 .LBB0_41
	s_barrier

.LBB0_50:
	s_add_u32 s41, s8, 0x100
	v_mov_b32_e32 v2, 0
	s_addc_u32 s86, s9, 0
	s_mov_b32 s87, -2
	v_mov_b32_e32 v3, v2
	v_mov_b32_e32 v4, v2
	v_mov_b32_e32 v5, v2
	v_mov_b32_e32 v10, v2
	v_mov_b32_e32 v11, v2
	v_mov_b32_e32 v12, v2
	v_mov_b32_e32 v13, v2
	v_mov_b32_e32 v18, v2
	v_mov_b32_e32 v19, v2
	v_mov_b32_e32 v20, v2
	v_mov_b32_e32 v21, v2
	v_mov_b32_e32 v26, v2
	v_mov_b32_e32 v27, v2
	v_mov_b32_e32 v28, v2
	v_mov_b32_e32 v29, v2
	v_mov_b32_e32 v34, v2
	v_mov_b32_e32 v35, v2
	v_mov_b32_e32 v36, v2
	v_mov_b32_e32 v37, v2
	v_mov_b32_e32 v42, v2
	v_mov_b32_e32 v43, v2
	v_mov_b32_e32 v44, v2
	v_mov_b32_e32 v45, v2
	v_mov_b32_e32 v50, v2
	v_mov_b32_e32 v51, v2
	v_mov_b32_e32 v52, v2
	v_mov_b32_e32 v53, v2
	v_mov_b32_e32 v58, v2
	v_mov_b32_e32 v59, v2
	v_mov_b32_e32 v60, v2
	v_mov_b32_e32 v61, v2
	v_mov_b32_e32 v6, v2
	v_mov_b32_e32 v7, v2
	v_mov_b32_e32 v8, v2
	v_mov_b32_e32 v9, v2
	v_mov_b32_e32 v14, v2
	v_mov_b32_e32 v15, v2
	v_mov_b32_e32 v16, v2
	v_mov_b32_e32 v17, v2
	v_mov_b32_e32 v22, v2
	v_mov_b32_e32 v23, v2
	v_mov_b32_e32 v24, v2
	v_mov_b32_e32 v25, v2
	v_mov_b32_e32 v30, v2
	v_mov_b32_e32 v31, v2
	v_mov_b32_e32 v32, v2
	v_mov_b32_e32 v33, v2
	v_mov_b32_e32 v38, v2
	v_mov_b32_e32 v39, v2
	v_mov_b32_e32 v40, v2
	v_mov_b32_e32 v41, v2
	v_mov_b32_e32 v46, v2
	v_mov_b32_e32 v47, v2
	v_mov_b32_e32 v48, v2
	v_mov_b32_e32 v49, v2
	v_mov_b32_e32 v54, v2
	v_mov_b32_e32 v55, v2
	v_mov_b32_e32 v56, v2
	v_mov_b32_e32 v57, v2
	v_mov_b32_e32 v62, v2
	v_mov_b32_e32 v63, v2
	v_mov_b32_e32 v64, v2
	v_mov_b32_e32 v65, v2
	v_mov_b32_e32 v66, v2
	v_mov_b32_e32 v67, v2
	v_mov_b32_e32 v68, v2
	v_mov_b32_e32 v69, v2
	v_mov_b32_e32 v74, v2
	v_mov_b32_e32 v75, v2
	v_mov_b32_e32 v76, v2
	v_mov_b32_e32 v77, v2
	v_mov_b32_e32 v82, v2
	v_mov_b32_e32 v83, v2
	v_mov_b32_e32 v84, v2
	v_mov_b32_e32 v85, v2
	v_mov_b32_e32 v90, v2
	v_mov_b32_e32 v91, v2
	v_mov_b32_e32 v92, v2
	v_mov_b32_e32 v93, v2
	v_mov_b32_e32 v98, v2
	v_mov_b32_e32 v99, v2
	v_mov_b32_e32 v100, v2
	v_mov_b32_e32 v101, v2
	v_mov_b32_e32 v106, v2
	v_mov_b32_e32 v107, v2
	v_mov_b32_e32 v108, v2
	v_mov_b32_e32 v109, v2
	v_mov_b32_e32 v114, v2
	v_mov_b32_e32 v115, v2
	v_mov_b32_e32 v116, v2
	v_mov_b32_e32 v117, v2
	v_mov_b32_e32 v122, v2
	v_mov_b32_e32 v123, v2
	v_mov_b32_e32 v124, v2
	v_mov_b32_e32 v125, v2
	v_mov_b32_e32 v70, v2
	v_mov_b32_e32 v71, v2
	v_mov_b32_e32 v72, v2
	v_mov_b32_e32 v73, v2
	v_mov_b32_e32 v78, v2
	v_mov_b32_e32 v79, v2
	v_mov_b32_e32 v80, v2
	v_mov_b32_e32 v81, v2
	v_mov_b32_e32 v86, v2
	v_mov_b32_e32 v87, v2
	v_mov_b32_e32 v88, v2
	v_mov_b32_e32 v89, v2
	v_mov_b32_e32 v94, v2
	v_mov_b32_e32 v95, v2
	v_mov_b32_e32 v96, v2
	v_mov_b32_e32 v97, v2
	v_mov_b32_e32 v102, v2
	v_mov_b32_e32 v103, v2
	v_mov_b32_e32 v104, v2
	v_mov_b32_e32 v105, v2
	v_mov_b32_e32 v110, v2
	v_mov_b32_e32 v111, v2
	v_mov_b32_e32 v112, v2
	v_mov_b32_e32 v113, v2
	v_mov_b32_e32 v118, v2
	v_mov_b32_e32 v119, v2
	v_mov_b32_e32 v120, v2
	v_mov_b32_e32 v121, v2
	v_mov_b32_e32 v126, v2
	v_mov_b32_e32 v127, v2
	v_mov_b32_e32 v128, v2
	v_mov_b32_e32 v129, v2
	s_branch .Lrot_enter_9
.LBB0_51:
	s_setprio 1
	s_barrier
	v_mfma_f32_16x16x32_bf16 v[58:61], v[192:195], v[160:163], v[58:61]
	v_mfma_f32_16x16x32_bf16 v[50:53], v[200:203], v[160:163], v[50:53]
	v_mfma_f32_16x16x32_bf16 v[42:45], v[192:195], v[168:171], v[42:45]
	v_mfma_f32_16x16x32_bf16 v[34:37], v[200:203], v[168:171], v[34:37]
	v_mfma_f32_16x16x32_bf16 v[26:29], v[192:195], v[176:179], v[26:29]
	v_mfma_f32_16x16x32_bf16 v[18:21], v[200:203], v[176:179], v[18:21]
	v_mfma_f32_16x16x32_bf16 v[10:13], v[192:195], v[184:187], v[10:13]
	v_mfma_f32_16x16x32_bf16 v[2:5], v[200:203], v[184:187], v[2:5]
	v_mfma_f32_16x16x32_bf16 v[58:61], v[196:199], v[164:167], v[58:61]
	v_mfma_f32_16x16x32_bf16 v[50:53], v[204:207], v[164:167], v[50:53]
	v_mfma_f32_16x16x32_bf16 v[42:45], v[196:199], v[172:175], v[42:45]
	v_mfma_f32_16x16x32_bf16 v[34:37], v[204:207], v[172:175], v[34:37]
	v_mfma_f32_16x16x32_bf16 v[26:29], v[196:199], v[180:183], v[26:29]
	v_mfma_f32_16x16x32_bf16 v[18:21], v[204:207], v[180:183], v[18:21]
	v_mfma_f32_16x16x32_bf16 v[10:13], v[196:199], v[188:191], v[10:13]
	v_mfma_f32_16x16x32_bf16 v[2:5], v[204:207], v[188:191], v[2:5]
	s_barrier
	s_setprio 0
.Lrot_enter_9:
	s_add_u32 s8, s6, 0x100
	s_addc_u32 s9, s7, 0
	s_add_i32 s90, 0, 0x10000
	v_add_u32_e32 v134, s90, v137
	ds_read_b128 v[140:143], v134
	ds_read_b128 v[148:151], v134 offset:1024
	ds_read_b128 v[152:155], v134 offset:2048
	ds_read_b128 v[156:159], v134 offset:3072
	s_cmp_eq_u32 s87, 28
	s_cselect_b32 s79, s43, s9
	s_cselect_b32 s78, s42, s8
	s_cselect_b32 s89, s47, s86
	s_cselect_b32 s88, s46, s41
	v_lshl_add_u64 v[134:135], s[6:7], 0, v[132:133]
	v_lshl_add_u64 v[144:145], v[134:135], 0, s[16:17]
	s_add_i32 m0, s49, 0xc000
	ds_read_b128 v[160:163], v138
	ds_read_b128 v[164:167], v138 offset:1024
	ds_read_b128 v[168:171], v138 offset:2048
	ds_read_b128 v[172:175], v138 offset:3072
	ds_read_b128 v[176:179], v138 offset:4096
	ds_read_b128 v[180:183], v138 offset:5120
	ds_read_b128 v[184:187], v138 offset:6144
	ds_read_b128 v[188:191], v138 offset:7168
	global_load_lds_dwordx4 v[144:145], off
	v_lshl_add_u64 v[134:135], v[134:135], 0, s[80:81]
	s_add_i32 m0, s49, 0xe000
	s_nop 0
	global_load_lds_dwordx4 v[134:135], off
	s_waitcnt lgkmcnt(8)
	s_setprio 1
	s_barrier
	s_waitcnt lgkmcnt(0)
	v_mfma_f32_16x16x32_bf16 v[126:129], v[140:143], v[160:163], v[126:129]
	v_mfma_f32_16x16x32_bf16 v[118:121], v[152:155], v[160:163], v[118:121]
	v_mfma_f32_16x16x32_bf16 v[110:113], v[140:143], v[168:171], v[110:113]
	v_mfma_f32_16x16x32_bf16 v[102:105], v[152:155], v[168:171], v[102:105]
	v_mfma_f32_16x16x32_bf16 v[94:97], v[140:143], v[176:179], v[94:97]
	v_mfma_f32_16x16x32_bf16 v[86:89], v[152:155], v[176:179], v[86:89]
	v_mfma_f32_16x16x32_bf16 v[78:81], v[140:143], v[184:187], v[78:81]
	v_mfma_f32_16x16x32_bf16 v[70:73], v[152:155], v[184:187], v[70:73]
	v_mfma_f32_16x16x32_bf16 v[126:129], v[148:151], v[164:167], v[126:129]
	v_mfma_f32_16x16x32_bf16 v[118:121], v[156:159], v[164:167], v[118:121]
	v_mfma_f32_16x16x32_bf16 v[110:113], v[148:151], v[172:175], v[110:113]
	v_mfma_f32_16x16x32_bf16 v[102:105], v[156:159], v[172:175], v[102:105]
	v_mfma_f32_16x16x32_bf16 v[94:97], v[148:151], v[180:183], v[94:97]
	v_mfma_f32_16x16x32_bf16 v[86:89], v[156:159], v[180:183], v[86:89]
	v_mfma_f32_16x16x32_bf16 v[78:81], v[148:151], v[188:191], v[78:81]
	v_mfma_f32_16x16x32_bf16 v[70:73], v[156:159], v[188:191], v[70:73]
	s_barrier
	s_setprio 0
	s_add_i32 s6, 0, 0x14000
	v_add_u32_e32 v134, s6, v137
	s_add_i32 s7, s90, s54
	ds_read_b128 v[192:195], v134
	ds_read_b128 v[196:199], v134 offset:1024
	ds_read_b128 v[200:203], v134 offset:2048
	ds_read_b128 v[204:207], v134 offset:3072
	v_lshl_add_u64 v[134:135], s[88:89], 0, v[0:1]
	s_mov_b32 m0, s7
	v_lshl_add_u64 v[144:145], v[134:135], 0, s[60:61]
	global_load_lds_dwordx4 v[134:135], off
	s_add_i32 m0, s7, 0x2000
	s_nop 0
	global_load_lds_dwordx4 v[144:145], off
	s_setprio 1
	s_barrier
	s_waitcnt lgkmcnt(0)
	v_mfma_f32_16x16x32_bf16 v[122:125], v[192:195], v[160:163], v[122:125]
	v_mfma_f32_16x16x32_bf16 v[114:117], v[200:203], v[160:163], v[114:117]
	v_mfma_f32_16x16x32_bf16 v[106:109], v[192:195], v[168:171], v[106:109]
	v_mfma_f32_16x16x32_bf16 v[98:101], v[200:203], v[168:171], v[98:101]
	v_mfma_f32_16x16x32_bf16 v[90:93], v[192:195], v[176:179], v[90:93]
	v_mfma_f32_16x16x32_bf16 v[82:85], v[200:203], v[176:179], v[82:85]
	v_mfma_f32_16x16x32_bf16 v[74:77], v[192:195], v[184:187], v[74:77]
	v_mfma_f32_16x16x32_bf16 v[66:69], v[200:203], v[184:187], v[66:69]
	v_mfma_f32_16x16x32_bf16 v[122:125], v[196:199], v[164:167], v[122:125]
	v_mfma_f32_16x16x32_bf16 v[114:117], v[204:207], v[164:167], v[114:117]
	v_mfma_f32_16x16x32_bf16 v[106:109], v[196:199], v[172:175], v[106:109]
	v_mfma_f32_16x16x32_bf16 v[98:101], v[204:207], v[172:175], v[98:101]
	v_mfma_f32_16x16x32_bf16 v[90:93], v[196:199], v[180:183], v[90:93]
	v_mfma_f32_16x16x32_bf16 v[82:85], v[204:207], v[180:183], v[82:85]
	v_mfma_f32_16x16x32_bf16 v[74:77], v[196:199], v[188:191], v[74:77]
	v_mfma_f32_16x16x32_bf16 v[66:69], v[204:207], v[188:191], v[66:69]
	s_barrier
	s_setprio 0
	s_mov_b32 m0, s49
	v_lshl_add_u64 v[144:145], s[78:79], 0, v[130:131]
	ds_read_b128 v[160:163], v138 offset:16384
	ds_read_b128 v[164:167], v138 offset:17408
	ds_read_b128 v[168:171], v138 offset:18432
	ds_read_b128 v[172:175], v138 offset:19456
	ds_read_b128 v[176:179], v138 offset:20480
	ds_read_b128 v[180:183], v138 offset:21504
	ds_read_b128 v[184:187], v138 offset:22528
	ds_read_b128 v[188:191], v138 offset:23552
	global_load_lds_dwordx4 v[144:145], off
	v_lshl_add_u64 v[208:209], v[144:145], 0, s[60:61]
	s_mov_b32 m0, s55
	s_nop 0
	global_load_lds_dwordx4 v[208:209], off
	s_setprio 1
	s_barrier
	s_waitcnt lgkmcnt(0)
	v_mfma_f32_16x16x32_bf16 v[62:65], v[140:143], v[160:163], v[62:65]
	v_mfma_f32_16x16x32_bf16 v[54:57], v[152:155], v[160:163], v[54:57]
	v_mfma_f32_16x16x32_bf16 v[46:49], v[140:143], v[168:171], v[46:49]
	v_mfma_f32_16x16x32_bf16 v[38:41], v[152:155], v[168:171], v[38:41]
	v_mfma_f32_16x16x32_bf16 v[30:33], v[140:143], v[176:179], v[30:33]
	v_mfma_f32_16x16x32_bf16 v[22:25], v[152:155], v[176:179], v[22:25]
	v_mfma_f32_16x16x32_bf16 v[14:17], v[140:143], v[184:187], v[14:17]
	v_mfma_f32_16x16x32_bf16 v[6:9], v[152:155], v[184:187], v[6:9]
	v_mfma_f32_16x16x32_bf16 v[62:65], v[148:151], v[164:167], v[62:65]
	v_mfma_f32_16x16x32_bf16 v[54:57], v[156:159], v[164:167], v[54:57]
	v_mfma_f32_16x16x32_bf16 v[46:49], v[148:151], v[172:175], v[46:49]
	v_mfma_f32_16x16x32_bf16 v[38:41], v[156:159], v[172:175], v[38:41]
	v_mfma_f32_16x16x32_bf16 v[30:33], v[148:151], v[180:183], v[30:33]
	v_mfma_f32_16x16x32_bf16 v[22:25], v[156:159], v[180:183], v[22:25]
	v_mfma_f32_16x16x32_bf16 v[14:17], v[148:151], v[188:191], v[14:17]
	v_mfma_f32_16x16x32_bf16 v[6:9], v[156:159], v[188:191], v[6:9]
	s_barrier
	s_setprio 0
	s_add_i32 s6, s6, s54
	v_lshl_add_u64 v[140:141], v[134:135], 0, s[20:21]
	s_mov_b32 m0, s6
	s_nop 0
	global_load_lds_dwordx4 v[140:141], off
	v_lshl_add_u64 v[140:141], v[134:135], 0, s[64:65]
	s_add_i32 m0, s6, 0x2000
	s_nop 0
	global_load_lds_dwordx4 v[140:141], off
	v_lshl_add_u64 v[230:231], v[144:145], 0, s[20:21]
	s_mov_b32 m0, s56
	s_nop 0
	global_load_lds_dwordx4 v[230:231], off
	v_lshl_add_u64 v[230:231], v[144:145], 0, s[64:65]
	s_mov_b32 m0, s57
	s_nop 0
	global_load_lds_dwordx4 v[230:231], off
	s_waitcnt vmcnt(8)
	s_setprio 1
	s_barrier
	v_mfma_f32_16x16x32_bf16 v[58:61], v[192:195], v[160:163], v[58:61]
	v_mfma_f32_16x16x32_bf16 v[50:53], v[200:203], v[160:163], v[50:53]
	v_mfma_f32_16x16x32_bf16 v[42:45], v[192:195], v[168:171], v[42:45]
	v_mfma_f32_16x16x32_bf16 v[34:37], v[200:203], v[168:171], v[34:37]
	v_mfma_f32_16x16x32_bf16 v[26:29], v[192:195], v[176:179], v[26:29]
	v_mfma_f32_16x16x32_bf16 v[18:21], v[200:203], v[176:179], v[18:21]
	v_mfma_f32_16x16x32_bf16 v[10:13], v[192:195], v[184:187], v[10:13]
	v_mfma_f32_16x16x32_bf16 v[2:5], v[200:203], v[184:187], v[2:5]
	v_mfma_f32_16x16x32_bf16 v[58:61], v[196:199], v[164:167], v[58:61]
	v_mfma_f32_16x16x32_bf16 v[50:53], v[204:207], v[164:167], v[50:53]
	v_mfma_f32_16x16x32_bf16 v[42:45], v[196:199], v[172:175], v[42:45]
	v_mfma_f32_16x16x32_bf16 v[34:37], v[204:207], v[172:175], v[34:37]
	v_mfma_f32_16x16x32_bf16 v[26:29], v[196:199], v[180:183], v[26:29]
	v_mfma_f32_16x16x32_bf16 v[18:21], v[204:207], v[180:183], v[18:21]
	v_mfma_f32_16x16x32_bf16 v[10:13], v[196:199], v[188:191], v[10:13]
	v_mfma_f32_16x16x32_bf16 v[2:5], v[204:207], v[188:191], v[2:5]
	s_barrier
	s_setprio 0
	s_add_i32 s6, 0, 0x18000
	v_add_u32_e32 v139, s6, v137
	ds_read_b128 v[140:143], v139
	ds_read_b128 v[148:151], v139 offset:1024
	ds_read_b128 v[152:155], v139 offset:2048
	ds_read_b128 v[156:159], v139 offset:3072
	ds_read_b128 v[160:163], v138 offset:32768
	ds_read_b128 v[164:167], v138 offset:33792
	ds_read_b128 v[168:171], v138 offset:34816
	ds_read_b128 v[172:175], v138 offset:35840
	ds_read_b128 v[176:179], v138 offset:36864
	ds_read_b128 v[180:183], v138 offset:37888
	ds_read_b128 v[184:187], v138 offset:38912
	ds_read_b128 v[188:191], v138 offset:39936
	s_waitcnt lgkmcnt(8)
	s_setprio 1
	s_barrier
	s_waitcnt lgkmcnt(0)
	v_mfma_f32_16x16x32_bf16 v[126:129], v[140:143], v[160:163], v[126:129]
	v_mfma_f32_16x16x32_bf16 v[118:121], v[152:155], v[160:163], v[118:121]
	v_mfma_f32_16x16x32_bf16 v[110:113], v[140:143], v[168:171], v[110:113]
	v_mfma_f32_16x16x32_bf16 v[102:105], v[152:155], v[168:171], v[102:105]
	v_mfma_f32_16x16x32_bf16 v[94:97], v[140:143], v[176:179], v[94:97]
	v_mfma_f32_16x16x32_bf16 v[86:89], v[152:155], v[176:179], v[86:89]
	v_mfma_f32_16x16x32_bf16 v[78:81], v[140:143], v[184:187], v[78:81]
	v_mfma_f32_16x16x32_bf16 v[70:73], v[152:155], v[184:187], v[70:73]
	v_mfma_f32_16x16x32_bf16 v[126:129], v[148:151], v[164:167], v[126:129]
	v_mfma_f32_16x16x32_bf16 v[118:121], v[156:159], v[164:167], v[118:121]
	v_mfma_f32_16x16x32_bf16 v[110:113], v[148:151], v[172:175], v[110:113]
	v_mfma_f32_16x16x32_bf16 v[102:105], v[156:159], v[172:175], v[102:105]
	v_mfma_f32_16x16x32_bf16 v[94:97], v[148:151], v[180:183], v[94:97]
	v_mfma_f32_16x16x32_bf16 v[86:89], v[156:159], v[180:183], v[86:89]
	v_mfma_f32_16x16x32_bf16 v[78:81], v[148:151], v[188:191], v[78:81]
	v_mfma_f32_16x16x32_bf16 v[70:73], v[156:159], v[188:191], v[70:73]
	s_barrier
	s_setprio 0
	s_add_i32 s7, 0, 0x1c000
	s_add_i32 s6, s6, s54
	v_add_u32_e32 v139, s7, v137
	v_lshl_add_u64 v[208:209], v[134:135], 0, s[34:35]
	s_mov_b32 m0, s6
	ds_read_b128 v[192:195], v139
	ds_read_b128 v[196:199], v139 offset:1024
	ds_read_b128 v[200:203], v139 offset:2048
	ds_read_b128 v[204:207], v139 offset:3072
	global_load_lds_dwordx4 v[208:209], off
	v_lshl_add_u64 v[208:209], v[134:135], 0, s[66:67]
	s_add_i32 m0, s6, 0x2000
	s_nop 0
	global_load_lds_dwordx4 v[208:209], off
	s_setprio 1
	s_barrier
	s_waitcnt lgkmcnt(0)
	v_mfma_f32_16x16x32_bf16 v[122:125], v[192:195], v[160:163], v[122:125]
	v_mfma_f32_16x16x32_bf16 v[114:117], v[200:203], v[160:163], v[114:117]
	v_mfma_f32_16x16x32_bf16 v[106:109], v[192:195], v[168:171], v[106:109]
	v_mfma_f32_16x16x32_bf16 v[98:101], v[200:203], v[168:171], v[98:101]
	v_mfma_f32_16x16x32_bf16 v[90:93], v[192:195], v[176:179], v[90:93]
	v_mfma_f32_16x16x32_bf16 v[82:85], v[200:203], v[176:179], v[82:85]
	v_mfma_f32_16x16x32_bf16 v[74:77], v[192:195], v[184:187], v[74:77]
	v_mfma_f32_16x16x32_bf16 v[66:69], v[200:203], v[184:187], v[66:69]
	v_mfma_f32_16x16x32_bf16 v[122:125], v[196:199], v[164:167], v[122:125]
	v_mfma_f32_16x16x32_bf16 v[114:117], v[204:207], v[164:167], v[114:117]
	v_mfma_f32_16x16x32_bf16 v[106:109], v[196:199], v[172:175], v[106:109]
	v_mfma_f32_16x16x32_bf16 v[98:101], v[204:207], v[172:175], v[98:101]
	v_mfma_f32_16x16x32_bf16 v[90:93], v[196:199], v[180:183], v[90:93]
	v_mfma_f32_16x16x32_bf16 v[82:85], v[204:207], v[180:183], v[82:85]
	v_mfma_f32_16x16x32_bf16 v[74:77], v[196:199], v[188:191], v[74:77]
	v_mfma_f32_16x16x32_bf16 v[66:69], v[204:207], v[188:191], v[66:69]
	s_barrier
	s_setprio 0
	s_mov_b32 m0, s59
	v_lshl_add_u64 v[208:209], v[144:145], 0, s[34:35]
	ds_read_b128 v[160:163], v138 offset:49152
	ds_read_b128 v[164:167], v138 offset:50176
	ds_read_b128 v[168:171], v138 offset:51200
	ds_read_b128 v[172:175], v138 offset:52224
	ds_read_b128 v[176:179], v138 offset:53248
	ds_read_b128 v[180:183], v138 offset:54272
	ds_read_b128 v[184:187], v138 offset:55296
	ds_read_b128 v[188:191], v138 offset:56320
	global_load_lds_dwordx4 v[208:209], off
	v_lshl_add_u64 v[144:145], v[144:145], 0, s[66:67]
	s_mov_b32 m0, s62
	s_nop 0
	global_load_lds_dwordx4 v[144:145], off
	s_setprio 1
	s_barrier
	s_waitcnt lgkmcnt(0)
	v_mfma_f32_16x16x32_bf16 v[62:65], v[140:143], v[160:163], v[62:65]
	v_mfma_f32_16x16x32_bf16 v[54:57], v[152:155], v[160:163], v[54:57]
	v_mfma_f32_16x16x32_bf16 v[46:49], v[140:143], v[168:171], v[46:49]
	v_mfma_f32_16x16x32_bf16 v[38:41], v[152:155], v[168:171], v[38:41]
	v_mfma_f32_16x16x32_bf16 v[30:33], v[140:143], v[176:179], v[30:33]
	v_mfma_f32_16x16x32_bf16 v[22:25], v[152:155], v[176:179], v[22:25]
	v_mfma_f32_16x16x32_bf16 v[14:17], v[140:143], v[184:187], v[14:17]
	v_mfma_f32_16x16x32_bf16 v[6:9], v[152:155], v[184:187], v[6:9]
	v_mfma_f32_16x16x32_bf16 v[62:65], v[148:151], v[164:167], v[62:65]
	v_mfma_f32_16x16x32_bf16 v[54:57], v[156:159], v[164:167], v[54:57]
	v_mfma_f32_16x16x32_bf16 v[46:49], v[148:151], v[172:175], v[46:49]
	v_mfma_f32_16x16x32_bf16 v[38:41], v[156:159], v[172:175], v[38:41]
	v_mfma_f32_16x16x32_bf16 v[30:33], v[148:151], v[180:183], v[30:33]
	v_mfma_f32_16x16x32_bf16 v[22:25], v[156:159], v[180:183], v[22:25]
	v_mfma_f32_16x16x32_bf16 v[14:17], v[148:151], v[188:191], v[14:17]
	v_mfma_f32_16x16x32_bf16 v[6:9], v[156:159], v[188:191], v[6:9]
	s_barrier
	s_setprio 0
	s_add_i32 s6, s7, s54
	v_lshl_add_u64 v[140:141], v[134:135], 0, s[16:17]
	s_mov_b32 m0, s6
	v_lshl_add_u64 v[134:135], v[134:135], 0, s[80:81]
	global_load_lds_dwordx4 v[140:141], off
	s_add_i32 m0, s6, 0x2000
	s_nop 0
	global_load_lds_dwordx4 v[134:135], off
	s_waitcnt vmcnt(6)
	s_add_i32 s87, s87, 2
	s_add_u32 s41, s41, 0x100
	s_addc_u32 s86, s86, 0
	s_cmp_gt_u32 s87, 29
	s_mov_b64 s[6:7], s[8:9]
	s_cbranch_scc0 .LBB0_51
	s_setprio 1
	s_barrier
	v_mfma_f32_16x16x32_bf16 v[58:61], v[192:195], v[160:163], v[58:61]
	v_mfma_f32_16x16x32_bf16 v[50:53], v[200:203], v[160:163], v[50:53]
	v_mfma_f32_16x16x32_bf16 v[42:45], v[192:195], v[168:171], v[42:45]
	v_mfma_f32_16x16x32_bf16 v[34:37], v[200:203], v[168:171], v[34:37]
	v_mfma_f32_16x16x32_bf16 v[26:29], v[192:195], v[176:179], v[26:29]
	v_mfma_f32_16x16x32_bf16 v[18:21], v[200:203], v[176:179], v[18:21]
	v_mfma_f32_16x16x32_bf16 v[10:13], v[192:195], v[184:187], v[10:13]
	v_mfma_f32_16x16x32_bf16 v[2:5], v[200:203], v[184:187], v[2:5]
	v_mfma_f32_16x16x32_bf16 v[58:61], v[196:199], v[164:167], v[58:61]
	v_mfma_f32_16x16x32_bf16 v[50:53], v[204:207], v[164:167], v[50:53]
	v_mfma_f32_16x16x32_bf16 v[42:45], v[196:199], v[172:175], v[42:45]
	v_mfma_f32_16x16x32_bf16 v[34:37], v[204:207], v[172:175], v[34:37]
	v_mfma_f32_16x16x32_bf16 v[26:29], v[196:199], v[180:183], v[26:29]
	v_mfma_f32_16x16x32_bf16 v[18:21], v[204:207], v[180:183], v[18:21]
	v_mfma_f32_16x16x32_bf16 v[10:13], v[196:199], v[188:191], v[10:13]
	v_mfma_f32_16x16x32_bf16 v[2:5], v[204:207], v[188:191], v[2:5]
	s_barrier
	s_setprio 0
	v_mul_f32_e32 v144, 0xbfb8aa3b, v126
	v_exp_f32_e32 v144, v144
	v_mov_b32_e32 v134, v136
	s_lshl_b32 s6, s48, 8
	v_add_f32_e32 v144, 1.0, v144
	v_rcp_f32_e32 v144, v144
	s_add_i32 s6, s6, s10
	v_and_or_b32 v139, v134, 15, s6
	s_lshl_b32 s6, s85, 7
	v_mul_f32_e32 v126, v126, v144
	v_mul_f32_e32 v122, v126, v122
	v_mul_f32_e32 v126, 0xbfb8aa3b, v127
	v_exp_f32_e32 v126, v126
	v_ashrrev_i32_e32 v134, 1, v134
	s_or_b32 s6, s6, s58
	v_and_b32_e32 v134, -8, v134
	v_add_f32_e32 v126, 1.0, v126
	v_rcp_f32_e32 v126, v126
	v_add_u32_e32 v140, s6, v134
	v_ashrrev_i32_e32 v141, 31, v140
	v_mov_b64_e32 v[134:135], s[4:5]
	v_mul_f32_e32 v126, v127, v126
	v_mul_f32_e32 v123, v126, v123
	v_mul_f32_e32 v126, 0xbfb8aa3b, v128
	v_exp_f32_e32 v126, v126
	v_mad_i64_i32 v[142:143], s[6:7], v139, s74, v[134:135]
	s_and_b64 vcc, exec, s[44:45]
	v_add_f32_e32 v126, 1.0, v126
	v_rcp_f32_e32 v126, v126
	s_mov_b32 s48, s40
	s_mov_b32 s85, s84
	s_mov_b64 s[8:9], s[46:47]
	v_mul_f32_e32 v126, v128, v126
	v_mul_f32_e32 v124, v126, v124
	v_mul_f32_e32 v126, 0xbfb8aa3b, v129
	v_exp_f32_e32 v126, v126
	s_nop 0
	v_add_f32_e32 v126, 1.0, v126
	v_rcp_f32_e32 v126, v126
	s_nop 0
	v_mul_f32_e32 v126, v129, v126
	v_mul_f32_e32 v125, v126, v125
	v_mul_f32_e32 v126, 0xbfb8aa3b, v118
	v_exp_f32_e32 v126, v126
	s_nop 0
	v_add_f32_e32 v126, 1.0, v126
	v_rcp_f32_e32 v126, v126
	s_nop 0
	v_mul_f32_e32 v118, v118, v126
	v_mul_f32_e32 v118, v118, v114
	v_mul_f32_e32 v114, 0xbfb8aa3b, v119
	v_exp_f32_e32 v114, v114
	s_nop 0
	v_add_f32_e32 v114, 1.0, v114
	v_rcp_f32_e32 v114, v114
	s_nop 0
	v_mul_f32_e32 v114, v119, v114
	v_mul_f32_e32 v119, v114, v115
	v_mul_f32_e32 v114, 0xbfb8aa3b, v120
	v_exp_f32_e32 v114, v114
	s_nop 0
	v_add_f32_e32 v114, 1.0, v114
	v_rcp_f32_e32 v114, v114
	s_nop 0
	v_mul_f32_e32 v114, v120, v114
	v_mul_f32_e32 v126, v114, v116
	v_mul_f32_e32 v114, 0xbfb8aa3b, v121
	v_exp_f32_e32 v114, v114
	v_cvt_pk_bf16_f32 v116, v122, v123
	s_nop 0
	v_add_f32_e32 v114, 1.0, v114
	v_rcp_f32_e32 v114, v114
	s_nop 0
	v_mul_f32_e32 v114, v121, v114
	v_mul_f32_e32 v127, v114, v117
	v_lshlrev_b64 v[114:115], 1, v[140:141]
	v_lshl_add_u64 v[120:121], v[142:143], 0, v[114:115]
	v_cvt_pk_bf16_f32 v117, v124, v125
	v_cvt_pk_bf16_f32 v118, v118, v119
	v_cvt_pk_bf16_f32 v119, v126, v127
	global_store_dwordx4 v[120:121], v[116:119], off
	s_nop 1
	v_mul_f32_e32 v118, 0xbfb8aa3b, v110
	v_exp_f32_e32 v118, v118
	v_or_b32_e32 v116, 16, v139
	v_mad_i64_i32 v[116:117], s[6:7], v116, s74, v[134:135]
	v_add_f32_e32 v118, 1.0, v118
	v_rcp_f32_e32 v118, v118
	s_nop 0
	v_mul_f32_e32 v110, v110, v118
	v_mul_f32_e32 v106, v110, v106
	v_mul_f32_e32 v110, 0xbfb8aa3b, v111
	v_exp_f32_e32 v110, v110
	s_nop 0
	v_add_f32_e32 v110, 1.0, v110
	v_rcp_f32_e32 v110, v110
	s_nop 0
	v_mul_f32_e32 v110, v111, v110
	v_mul_f32_e32 v107, v110, v107
	v_mul_f32_e32 v110, 0xbfb8aa3b, v112
	v_exp_f32_e32 v110, v110
	s_nop 0
	v_add_f32_e32 v110, 1.0, v110
	v_rcp_f32_e32 v110, v110
	s_nop 0
	v_mul_f32_e32 v110, v112, v110
	v_mul_f32_e32 v108, v110, v108
	v_mul_f32_e32 v110, 0xbfb8aa3b, v113
	v_exp_f32_e32 v110, v110
	s_nop 0
	v_add_f32_e32 v110, 1.0, v110
	v_rcp_f32_e32 v110, v110
	s_nop 0
	v_mul_f32_e32 v110, v113, v110
	v_mul_f32_e32 v109, v110, v109
	v_mul_f32_e32 v110, 0xbfb8aa3b, v102
	v_exp_f32_e32 v110, v110
	s_nop 0
	v_add_f32_e32 v110, 1.0, v110
	v_rcp_f32_e32 v110, v110
	s_nop 0
	v_mul_f32_e32 v102, v102, v110
	v_mul_f32_e32 v110, v102, v98
	v_mul_f32_e32 v98, 0xbfb8aa3b, v103
	v_exp_f32_e32 v98, v98
	s_nop 0
	v_add_f32_e32 v98, 1.0, v98
	v_rcp_f32_e32 v98, v98
	s_nop 0
	v_mul_f32_e32 v98, v103, v98
	v_mul_f32_e32 v111, v98, v99
	v_mul_f32_e32 v98, 0xbfb8aa3b, v104
	v_exp_f32_e32 v98, v98
	v_lshl_add_u64 v[102:103], v[116:117], 0, v[114:115]
	v_add_f32_e32 v98, 1.0, v98
	v_rcp_f32_e32 v98, v98
	s_nop 0
	v_mul_f32_e32 v98, v104, v98
	v_mul_f32_e32 v104, v98, v100
	v_mul_f32_e32 v98, 0xbfb8aa3b, v105
	v_exp_f32_e32 v98, v98
	s_nop 0
	v_add_f32_e32 v98, 1.0, v98
	v_rcp_f32_e32 v98, v98
	s_nop 0
	v_mul_f32_e32 v98, v105, v98
	v_mul_f32_e32 v101, v98, v101
	v_cvt_pk_bf16_f32 v98, v106, v107
	v_cvt_pk_bf16_f32 v99, v108, v109
	v_cvt_pk_bf16_f32 v100, v110, v111
	v_cvt_pk_bf16_f32 v101, v104, v101
	global_store_dwordx4 v[102:103], v[98:101], off
	s_nop 1
	v_mul_f32_e32 v100, 0xbfb8aa3b, v94
	v_exp_f32_e32 v100, v100
	v_or_b32_e32 v98, 32, v139
	v_mad_i64_i32 v[98:99], s[6:7], v98, s74, v[134:135]
	v_add_f32_e32 v100, 1.0, v100
	v_rcp_f32_e32 v100, v100
	s_nop 0
	v_mul_f32_e32 v94, v94, v100
	v_mul_f32_e32 v90, v94, v90
	v_mul_f32_e32 v94, 0xbfb8aa3b, v95
	v_exp_f32_e32 v94, v94
	s_nop 0
	v_add_f32_e32 v94, 1.0, v94
	v_rcp_f32_e32 v94, v94
	s_nop 0
	v_mul_f32_e32 v94, v95, v94
	v_mul_f32_e32 v91, v94, v91
	v_mul_f32_e32 v94, 0xbfb8aa3b, v96
	v_exp_f32_e32 v94, v94
	s_nop 0
	v_add_f32_e32 v94, 1.0, v94
	v_rcp_f32_e32 v94, v94
	s_nop 0
	v_mul_f32_e32 v94, v96, v94
	v_mul_f32_e32 v92, v94, v92
	v_mul_f32_e32 v94, 0xbfb8aa3b, v97
	v_exp_f32_e32 v94, v94
	s_nop 0
	v_add_f32_e32 v94, 1.0, v94
	v_rcp_f32_e32 v94, v94
	s_nop 0
	v_mul_f32_e32 v94, v97, v94
	v_mul_f32_e32 v93, v94, v93
	v_mul_f32_e32 v94, 0xbfb8aa3b, v86
	v_exp_f32_e32 v94, v94
	s_nop 0
	v_add_f32_e32 v94, 1.0, v94
	v_rcp_f32_e32 v94, v94
	s_nop 0
	v_mul_f32_e32 v86, v86, v94
	v_mul_f32_e32 v94, v86, v82
	v_mul_f32_e32 v82, 0xbfb8aa3b, v87
	v_exp_f32_e32 v82, v82
	s_nop 0
	v_add_f32_e32 v82, 1.0, v82
	v_rcp_f32_e32 v82, v82
	s_nop 0
	v_mul_f32_e32 v82, v87, v82
	v_mul_f32_e32 v95, v82, v83
	v_mul_f32_e32 v82, 0xbfb8aa3b, v88
	v_exp_f32_e32 v82, v82
	v_lshl_add_u64 v[86:87], v[98:99], 0, v[114:115]
	v_add_f32_e32 v82, 1.0, v82
	v_rcp_f32_e32 v82, v82
	s_nop 0
	v_mul_f32_e32 v82, v88, v82
	v_mul_f32_e32 v88, v82, v84
	v_mul_f32_e32 v82, 0xbfb8aa3b, v89
	v_exp_f32_e32 v82, v82
	s_nop 0
	v_add_f32_e32 v82, 1.0, v82
	v_rcp_f32_e32 v82, v82
	s_nop 0
	v_mul_f32_e32 v82, v89, v82
	v_mul_f32_e32 v85, v82, v85
	v_cvt_pk_bf16_f32 v82, v90, v91
	v_cvt_pk_bf16_f32 v83, v92, v93
	v_cvt_pk_bf16_f32 v84, v94, v95
	v_cvt_pk_bf16_f32 v85, v88, v85
	global_store_dwordx4 v[86:87], v[82:85], off
	s_nop 1
	v_mul_f32_e32 v84, 0xbfb8aa3b, v78
	v_exp_f32_e32 v84, v84
	v_or_b32_e32 v82, 48, v139
	v_mad_i64_i32 v[82:83], s[6:7], v82, s74, v[134:135]
	v_add_f32_e32 v84, 1.0, v84
	v_rcp_f32_e32 v84, v84
	s_nop 0
	v_mul_f32_e32 v78, v78, v84
	v_mul_f32_e32 v74, v78, v74
	v_mul_f32_e32 v78, 0xbfb8aa3b, v79
	v_exp_f32_e32 v78, v78
	s_nop 0
	v_add_f32_e32 v78, 1.0, v78
	v_rcp_f32_e32 v78, v78
	s_nop 0
	v_mul_f32_e32 v78, v79, v78
	v_mul_f32_e32 v75, v78, v75
	v_mul_f32_e32 v78, 0xbfb8aa3b, v80
	v_exp_f32_e32 v78, v78
	s_nop 0
	v_add_f32_e32 v78, 1.0, v78
	v_rcp_f32_e32 v78, v78
	s_nop 0
	v_mul_f32_e32 v78, v80, v78
	v_mul_f32_e32 v76, v78, v76
	v_mul_f32_e32 v78, 0xbfb8aa3b, v81
	v_exp_f32_e32 v78, v78
	s_nop 0
	v_add_f32_e32 v78, 1.0, v78
	v_rcp_f32_e32 v78, v78
	s_nop 0
	v_mul_f32_e32 v78, v81, v78
	v_mul_f32_e32 v77, v78, v77
	v_mul_f32_e32 v78, 0xbfb8aa3b, v70
	v_exp_f32_e32 v78, v78
	s_nop 0
	v_add_f32_e32 v78, 1.0, v78
	v_rcp_f32_e32 v78, v78
	s_nop 0
	v_mul_f32_e32 v70, v70, v78
	v_mul_f32_e32 v78, v70, v66
	v_mul_f32_e32 v66, 0xbfb8aa3b, v71
	v_exp_f32_e32 v66, v66
	s_nop 0
	v_add_f32_e32 v66, 1.0, v66
	v_rcp_f32_e32 v66, v66
	s_nop 0
	v_mul_f32_e32 v66, v71, v66
	v_mul_f32_e32 v79, v66, v67
	v_mul_f32_e32 v66, 0xbfb8aa3b, v72
	v_exp_f32_e32 v66, v66
	v_lshl_add_u64 v[70:71], v[82:83], 0, v[114:115]
	v_add_f32_e32 v66, 1.0, v66
	v_rcp_f32_e32 v66, v66
	s_nop 0
	v_mul_f32_e32 v66, v72, v66
	v_mul_f32_e32 v72, v66, v68
	v_mul_f32_e32 v66, 0xbfb8aa3b, v73
	v_exp_f32_e32 v66, v66
	s_nop 0
	v_add_f32_e32 v66, 1.0, v66
	v_rcp_f32_e32 v66, v66
	s_nop 0
	v_mul_f32_e32 v66, v73, v66
	v_mul_f32_e32 v69, v66, v69
	v_cvt_pk_bf16_f32 v66, v74, v75
	v_cvt_pk_bf16_f32 v67, v76, v77
	v_cvt_pk_bf16_f32 v68, v78, v79
	v_cvt_pk_bf16_f32 v69, v72, v69
	global_store_dwordx4 v[70:71], v[66:69], off
	s_nop 1
	v_mul_f32_e32 v68, 0xbfb8aa3b, v62
	v_exp_f32_e32 v68, v68
	v_add_u32_e32 v66, 0x80, v139
	v_mad_i64_i32 v[66:67], s[6:7], v66, s74, v[134:135]
	v_add_f32_e32 v68, 1.0, v68
	v_rcp_f32_e32 v68, v68
	s_nop 0
	v_mul_f32_e32 v62, v62, v68
	v_mul_f32_e32 v58, v62, v58
	v_mul_f32_e32 v62, 0xbfb8aa3b, v63
	v_exp_f32_e32 v62, v62
	s_nop 0
	v_add_f32_e32 v62, 1.0, v62
	v_rcp_f32_e32 v62, v62
	s_nop 0
	v_mul_f32_e32 v62, v63, v62
	v_mul_f32_e32 v59, v62, v59
	v_mul_f32_e32 v62, 0xbfb8aa3b, v64
	v_exp_f32_e32 v62, v62
	s_nop 0
	v_add_f32_e32 v62, 1.0, v62
	v_rcp_f32_e32 v62, v62
	s_nop 0
	v_mul_f32_e32 v62, v64, v62
	v_mul_f32_e32 v60, v62, v60
	v_mul_f32_e32 v62, 0xbfb8aa3b, v65
	v_exp_f32_e32 v62, v62
	s_nop 0
	v_add_f32_e32 v62, 1.0, v62
	v_rcp_f32_e32 v62, v62
	s_nop 0
	v_mul_f32_e32 v62, v65, v62
	v_mul_f32_e32 v61, v62, v61
	v_mul_f32_e32 v62, 0xbfb8aa3b, v54
	v_exp_f32_e32 v62, v62
	s_nop 0
	v_add_f32_e32 v62, 1.0, v62
	v_rcp_f32_e32 v62, v62
	s_nop 0
	v_mul_f32_e32 v54, v54, v62
	v_mul_f32_e32 v62, v54, v50
	v_mul_f32_e32 v50, 0xbfb8aa3b, v55
	v_exp_f32_e32 v50, v50
	s_nop 0
	v_add_f32_e32 v50, 1.0, v50
	v_rcp_f32_e32 v50, v50
	s_nop 0
	v_mul_f32_e32 v50, v55, v50
	v_mul_f32_e32 v63, v50, v51
	v_mul_f32_e32 v50, 0xbfb8aa3b, v56
	v_exp_f32_e32 v50, v50
	v_lshl_add_u64 v[54:55], v[66:67], 0, v[114:115]
	v_add_f32_e32 v50, 1.0, v50
	v_rcp_f32_e32 v50, v50
	s_nop 0
	v_mul_f32_e32 v50, v56, v50
	v_mul_f32_e32 v56, v50, v52
	v_mul_f32_e32 v50, 0xbfb8aa3b, v57
	v_exp_f32_e32 v50, v50
	s_nop 0
	v_add_f32_e32 v50, 1.0, v50
	v_rcp_f32_e32 v50, v50
	s_nop 0
	v_mul_f32_e32 v50, v57, v50
	v_mul_f32_e32 v53, v50, v53
	v_cvt_pk_bf16_f32 v50, v58, v59
	v_cvt_pk_bf16_f32 v51, v60, v61
	v_cvt_pk_bf16_f32 v52, v62, v63
	v_cvt_pk_bf16_f32 v53, v56, v53
	global_store_dwordx4 v[54:55], v[50:53], off
	s_nop 1
	v_mul_f32_e32 v52, 0xbfb8aa3b, v46
	v_exp_f32_e32 v52, v52
	v_add_u32_e32 v50, 0x90, v139
	v_mad_i64_i32 v[50:51], s[6:7], v50, s74, v[134:135]
	v_add_f32_e32 v52, 1.0, v52
	v_rcp_f32_e32 v52, v52
	s_nop 0
	v_mul_f32_e32 v46, v46, v52
	v_mul_f32_e32 v42, v46, v42
	v_mul_f32_e32 v46, 0xbfb8aa3b, v47
	v_exp_f32_e32 v46, v46
	s_nop 0
	v_add_f32_e32 v46, 1.0, v46
	v_rcp_f32_e32 v46, v46
	s_nop 0
	v_mul_f32_e32 v46, v47, v46
	v_mul_f32_e32 v43, v46, v43
	v_mul_f32_e32 v46, 0xbfb8aa3b, v48
	v_exp_f32_e32 v46, v46
	s_nop 0
	v_add_f32_e32 v46, 1.0, v46
	v_rcp_f32_e32 v46, v46
	s_nop 0
	v_mul_f32_e32 v46, v48, v46
	v_mul_f32_e32 v44, v46, v44
	v_mul_f32_e32 v46, 0xbfb8aa3b, v49
	v_exp_f32_e32 v46, v46
	s_nop 0
	v_add_f32_e32 v46, 1.0, v46
	v_rcp_f32_e32 v46, v46
	s_nop 0
	v_mul_f32_e32 v46, v49, v46
	v_mul_f32_e32 v45, v46, v45
	v_mul_f32_e32 v46, 0xbfb8aa3b, v38
	v_exp_f32_e32 v46, v46
	s_nop 0
	v_add_f32_e32 v46, 1.0, v46
	v_rcp_f32_e32 v46, v46
	s_nop 0
	v_mul_f32_e32 v38, v38, v46
	v_mul_f32_e32 v46, v38, v34
	v_mul_f32_e32 v34, 0xbfb8aa3b, v39
	v_exp_f32_e32 v34, v34
	s_nop 0
	v_add_f32_e32 v34, 1.0, v34
	v_rcp_f32_e32 v34, v34
	s_nop 0
	v_mul_f32_e32 v34, v39, v34
	v_mul_f32_e32 v47, v34, v35
	v_mul_f32_e32 v34, 0xbfb8aa3b, v40
	v_exp_f32_e32 v34, v34
	v_lshl_add_u64 v[38:39], v[50:51], 0, v[114:115]
	v_add_f32_e32 v34, 1.0, v34
	v_rcp_f32_e32 v34, v34
	s_nop 0
	v_mul_f32_e32 v34, v40, v34
	v_mul_f32_e32 v40, v34, v36
	v_mul_f32_e32 v34, 0xbfb8aa3b, v41
	v_exp_f32_e32 v34, v34
	s_nop 0
	v_add_f32_e32 v34, 1.0, v34
	v_rcp_f32_e32 v34, v34
	s_nop 0
	v_mul_f32_e32 v34, v41, v34
	v_mul_f32_e32 v37, v34, v37
	v_cvt_pk_bf16_f32 v34, v42, v43
	v_cvt_pk_bf16_f32 v35, v44, v45
	v_cvt_pk_bf16_f32 v36, v46, v47
	v_cvt_pk_bf16_f32 v37, v40, v37
	global_store_dwordx4 v[38:39], v[34:37], off
	s_nop 1
	v_mul_f32_e32 v36, 0xbfb8aa3b, v30
	v_exp_f32_e32 v36, v36
	v_add_u32_e32 v34, 0xa0, v139
	v_mad_i64_i32 v[34:35], s[6:7], v34, s74, v[134:135]
	v_add_f32_e32 v36, 1.0, v36
	v_rcp_f32_e32 v36, v36
	s_nop 0
	v_mul_f32_e32 v30, v30, v36
	v_mul_f32_e32 v26, v30, v26
	v_mul_f32_e32 v30, 0xbfb8aa3b, v31
	v_exp_f32_e32 v30, v30
	s_nop 0
	v_add_f32_e32 v30, 1.0, v30
	v_rcp_f32_e32 v30, v30
	s_nop 0
	v_mul_f32_e32 v30, v31, v30
	v_mul_f32_e32 v27, v30, v27
	v_mul_f32_e32 v30, 0xbfb8aa3b, v32
	v_exp_f32_e32 v30, v30
	s_nop 0
	v_add_f32_e32 v30, 1.0, v30
	v_rcp_f32_e32 v30, v30
	s_nop 0
	v_mul_f32_e32 v30, v32, v30
	v_mul_f32_e32 v28, v30, v28
	v_mul_f32_e32 v30, 0xbfb8aa3b, v33
	v_exp_f32_e32 v30, v30
	s_nop 0
	v_add_f32_e32 v30, 1.0, v30
	v_rcp_f32_e32 v30, v30
	s_nop 0
	v_mul_f32_e32 v30, v33, v30
	v_mul_f32_e32 v29, v30, v29
	v_mul_f32_e32 v30, 0xbfb8aa3b, v22
	v_exp_f32_e32 v30, v30
	s_nop 0
	v_add_f32_e32 v30, 1.0, v30
	v_rcp_f32_e32 v30, v30
	s_nop 0
	v_mul_f32_e32 v22, v22, v30
	v_mul_f32_e32 v30, v22, v18
	v_mul_f32_e32 v18, 0xbfb8aa3b, v23
	v_exp_f32_e32 v18, v18
	s_nop 0
	v_add_f32_e32 v18, 1.0, v18
	v_rcp_f32_e32 v18, v18
	s_nop 0
	v_mul_f32_e32 v18, v23, v18
	v_mul_f32_e32 v31, v18, v19
	v_mul_f32_e32 v18, 0xbfb8aa3b, v24
	v_exp_f32_e32 v18, v18
	v_lshl_add_u64 v[22:23], v[34:35], 0, v[114:115]
	v_add_f32_e32 v18, 1.0, v18
	v_rcp_f32_e32 v18, v18
	s_nop 0
	v_mul_f32_e32 v18, v24, v18
	v_mul_f32_e32 v24, v18, v20
	v_mul_f32_e32 v18, 0xbfb8aa3b, v25
	v_exp_f32_e32 v18, v18
	s_nop 0
	v_add_f32_e32 v18, 1.0, v18
	v_rcp_f32_e32 v18, v18
	s_nop 0
	v_mul_f32_e32 v18, v25, v18
	v_mul_f32_e32 v21, v18, v21
	v_cvt_pk_bf16_f32 v18, v26, v27
	v_cvt_pk_bf16_f32 v19, v28, v29
	v_cvt_pk_bf16_f32 v20, v30, v31
	v_cvt_pk_bf16_f32 v21, v24, v21
	global_store_dwordx4 v[22:23], v[18:21], off
	s_nop 1
	v_mul_f32_e32 v20, 0xbfb8aa3b, v14
	v_exp_f32_e32 v20, v20
	v_add_u32_e32 v18, 0xb0, v139
	v_mad_i64_i32 v[18:19], s[6:7], v18, s74, v[134:135]
	v_add_f32_e32 v20, 1.0, v20
	v_rcp_f32_e32 v20, v20
	s_mov_b64 s[6:7], s[42:43]
	v_mul_f32_e32 v14, v14, v20
	v_mul_f32_e32 v10, v14, v10
	v_mul_f32_e32 v14, 0xbfb8aa3b, v15
	v_exp_f32_e32 v14, v14
	s_nop 0
	v_add_f32_e32 v14, 1.0, v14
	v_rcp_f32_e32 v14, v14
	s_nop 0
	v_mul_f32_e32 v14, v15, v14
	v_mul_f32_e32 v11, v14, v11
	v_mul_f32_e32 v14, 0xbfb8aa3b, v16
	v_exp_f32_e32 v14, v14
	s_nop 0
	v_add_f32_e32 v14, 1.0, v14
	v_rcp_f32_e32 v14, v14
	s_nop 0
	v_mul_f32_e32 v14, v16, v14
	v_mul_f32_e32 v12, v14, v12
	v_mul_f32_e32 v14, 0xbfb8aa3b, v17
	v_exp_f32_e32 v14, v14
	s_nop 0
	v_add_f32_e32 v14, 1.0, v14
	v_rcp_f32_e32 v14, v14
	s_nop 0
	v_mul_f32_e32 v14, v17, v14
	v_mul_f32_e32 v13, v14, v13
	v_mul_f32_e32 v14, 0xbfb8aa3b, v6
	v_exp_f32_e32 v14, v14
	s_nop 0
	v_add_f32_e32 v14, 1.0, v14
	v_rcp_f32_e32 v14, v14
	s_nop 0
	v_mul_f32_e32 v6, v6, v14
	v_mul_f32_e32 v14, v6, v2
	v_mul_f32_e32 v2, 0xbfb8aa3b, v7
	v_exp_f32_e32 v2, v2
	s_nop 0
	v_add_f32_e32 v2, 1.0, v2
	v_rcp_f32_e32 v2, v2
	s_nop 0
	v_mul_f32_e32 v2, v7, v2
	v_mul_f32_e32 v15, v2, v3
	v_mul_f32_e32 v2, 0xbfb8aa3b, v8
	v_exp_f32_e32 v2, v2
	v_lshl_add_u64 v[6:7], v[18:19], 0, v[114:115]
	v_add_f32_e32 v2, 1.0, v2
	v_rcp_f32_e32 v2, v2
	s_nop 0
	v_mul_f32_e32 v2, v8, v2
	v_mul_f32_e32 v8, v2, v4
	v_mul_f32_e32 v2, 0xbfb8aa3b, v9
	v_exp_f32_e32 v2, v2
	s_nop 0
	v_add_f32_e32 v2, 1.0, v2
	v_rcp_f32_e32 v2, v2
	s_nop 0
	v_mul_f32_e32 v2, v9, v2
	v_mul_f32_e32 v5, v2, v5
	v_cvt_pk_bf16_f32 v2, v10, v11
	v_cvt_pk_bf16_f32 v3, v12, v13
	v_cvt_pk_bf16_f32 v4, v14, v15
	v_cvt_pk_bf16_f32 v5, v8, v5
	global_store_dwordx4 v[6:7], v[2:5], off
	s_cbranch_vccz .LBB0_48
	s_waitcnt vmcnt(0)
	v_readlane_b32 s0, v255, 8
	v_readlane_b32 s62, v255, 10
	v_readlane_b32 s84, v255, 12
	s_cmpk_gt_u32 s22, 0xff
	v_readlane_b32 s1, v255, 9
	s_mov_b64 s[58:59], s[92:93]
	v_readlane_b32 s63, v255, 11
	v_readlane_b32 s85, v255, 13
	s_cbranch_scc1 .LBB0_55
	s_barrier

.LBB0_96:
	s_add_u32 s8, s8, 0x100
	s_addc_u32 s9, s9, 0
	s_add_u32 s50, s6, 0x80080
	v_mov_b32_e32 v2, 0
	s_addc_u32 s51, s7, 0
	s_mov_b32 s6, -2
	v_mov_b32_e32 v3, v2
	v_mov_b32_e32 v4, v2
	v_mov_b32_e32 v5, v2
	v_mov_b32_e32 v6, v2
	v_mov_b32_e32 v7, v2
	v_mov_b32_e32 v8, v2
	v_mov_b32_e32 v9, v2
	v_mov_b32_e32 v10, v2
	v_mov_b32_e32 v11, v2
	v_mov_b32_e32 v12, v2
	v_mov_b32_e32 v13, v2
	v_mov_b32_e32 v18, v2
	v_mov_b32_e32 v19, v2
	v_mov_b32_e32 v20, v2
	v_mov_b32_e32 v21, v2
	v_mov_b32_e32 v26, v2
	v_mov_b32_e32 v27, v2
	v_mov_b32_e32 v28, v2
	v_mov_b32_e32 v29, v2
	v_mov_b32_e32 v34, v2
	v_mov_b32_e32 v35, v2
	v_mov_b32_e32 v36, v2
	v_mov_b32_e32 v37, v2
	v_mov_b32_e32 v42, v2
	v_mov_b32_e32 v43, v2
	v_mov_b32_e32 v44, v2
	v_mov_b32_e32 v45, v2
	v_mov_b32_e32 v50, v2
	v_mov_b32_e32 v51, v2
	v_mov_b32_e32 v52, v2
	v_mov_b32_e32 v53, v2
	v_mov_b32_e32 v14, v2
	v_mov_b32_e32 v15, v2
	v_mov_b32_e32 v16, v2
	v_mov_b32_e32 v17, v2
	v_mov_b32_e32 v22, v2
	v_mov_b32_e32 v23, v2
	v_mov_b32_e32 v24, v2
	v_mov_b32_e32 v25, v2
	v_mov_b32_e32 v30, v2
	v_mov_b32_e32 v31, v2
	v_mov_b32_e32 v32, v2
	v_mov_b32_e32 v33, v2
	v_mov_b32_e32 v38, v2
	v_mov_b32_e32 v39, v2
	v_mov_b32_e32 v40, v2
	v_mov_b32_e32 v41, v2
	v_mov_b32_e32 v46, v2
	v_mov_b32_e32 v47, v2
	v_mov_b32_e32 v48, v2
	v_mov_b32_e32 v49, v2
	v_mov_b32_e32 v54, v2
	v_mov_b32_e32 v55, v2
	v_mov_b32_e32 v56, v2
	v_mov_b32_e32 v57, v2
	v_mov_b32_e32 v58, v2
	v_mov_b32_e32 v59, v2
	v_mov_b32_e32 v60, v2
	v_mov_b32_e32 v61, v2
	v_mov_b32_e32 v62, v2
	v_mov_b32_e32 v63, v2
	v_mov_b32_e32 v64, v2
	v_mov_b32_e32 v65, v2
	v_mov_b32_e32 v66, v2
	v_mov_b32_e32 v67, v2
	v_mov_b32_e32 v68, v2
	v_mov_b32_e32 v69, v2
	v_mov_b32_e32 v70, v2
	v_mov_b32_e32 v71, v2
	v_mov_b32_e32 v72, v2
	v_mov_b32_e32 v73, v2
	v_mov_b32_e32 v74, v2
	v_mov_b32_e32 v75, v2
	v_mov_b32_e32 v76, v2
	v_mov_b32_e32 v77, v2
	v_mov_b32_e32 v82, v2
	v_mov_b32_e32 v83, v2
	v_mov_b32_e32 v84, v2
	v_mov_b32_e32 v85, v2
	v_mov_b32_e32 v90, v2
	v_mov_b32_e32 v91, v2
	v_mov_b32_e32 v92, v2
	v_mov_b32_e32 v93, v2
	v_mov_b32_e32 v98, v2
	v_mov_b32_e32 v99, v2
	v_mov_b32_e32 v100, v2
	v_mov_b32_e32 v101, v2
	v_mov_b32_e32 v106, v2
	v_mov_b32_e32 v107, v2
	v_mov_b32_e32 v108, v2
	v_mov_b32_e32 v109, v2
	v_mov_b32_e32 v114, v2
	v_mov_b32_e32 v115, v2
	v_mov_b32_e32 v116, v2
	v_mov_b32_e32 v117, v2
	v_mov_b32_e32 v78, v2
	v_mov_b32_e32 v79, v2
	v_mov_b32_e32 v80, v2
	v_mov_b32_e32 v81, v2
	v_mov_b32_e32 v86, v2
	v_mov_b32_e32 v87, v2
	v_mov_b32_e32 v88, v2
	v_mov_b32_e32 v89, v2
	v_mov_b32_e32 v94, v2
	v_mov_b32_e32 v95, v2
	v_mov_b32_e32 v96, v2
	v_mov_b32_e32 v97, v2
	v_mov_b32_e32 v102, v2
	v_mov_b32_e32 v103, v2
	v_mov_b32_e32 v104, v2
	v_mov_b32_e32 v105, v2
	v_mov_b32_e32 v110, v2
	v_mov_b32_e32 v111, v2
	v_mov_b32_e32 v112, v2
	v_mov_b32_e32 v113, v2
	v_mov_b32_e32 v118, v2
	v_mov_b32_e32 v119, v2
	v_mov_b32_e32 v120, v2
	v_mov_b32_e32 v121, v2
	v_mov_b32_e32 v122, v2
	v_mov_b32_e32 v123, v2
	v_mov_b32_e32 v124, v2
	v_mov_b32_e32 v125, v2
	v_mov_b32_e32 v126, v2
	v_mov_b32_e32 v127, v2
	v_mov_b32_e32 v128, v2
	v_mov_b32_e32 v129, v2
	s_branch .Lrot_enter_8

.Lrot_enter_8:
	s_add_u32 s7, s50, 0xfff80080
	s_addc_u32 s11, s51, -1
	s_add_i32 s43, 0, 0x10000
	v_add_u32_e32 v132, s43, v135
	ds_read_b128 v[138:141], v132
	ds_read_b128 v[142:145], v132 offset:1024
	ds_read_b128 v[148:151], v132 offset:2048
	ds_read_b128 v[152:155], v132 offset:3072
	s_cmp_eq_u32 s6, 28
	s_cselect_b32 s79, s45, s11
	s_cselect_b32 s78, s44, s7
	s_cselect_b32 s91, s47, s9
	s_cselect_b32 s90, s46, s8
	v_lshl_add_u64 v[132:133], s[50:51], 0, v[130:131]
	s_add_i32 m0, s49, 0xc000
	ds_read_b128 v[156:159], v136
	ds_read_b128 v[160:163], v136 offset:1024
	ds_read_b128 v[164:167], v136 offset:2048
	ds_read_b128 v[168:171], v136 offset:3072
	ds_read_b128 v[172:175], v136 offset:4096
	ds_read_b128 v[176:179], v136 offset:5120
	ds_read_b128 v[180:183], v136 offset:6144
	ds_read_b128 v[184:187], v136 offset:7168
	global_load_lds_dwordx4 v[132:133], off
	v_lshl_add_u64 v[132:133], v[132:133], 0, s[60:61]
	s_add_i32 m0, s49, 0xe000
	s_nop 0
	global_load_lds_dwordx4 v[132:133], off
	s_waitcnt lgkmcnt(8)
	s_setprio 1
	s_barrier
	s_waitcnt lgkmcnt(0)
	v_mfma_f32_16x16x32_bf16 v[126:129], v[138:141], v[156:159], v[126:129]
	v_mfma_f32_16x16x32_bf16 v[122:125], v[148:151], v[156:159], v[122:125]
	v_mfma_f32_16x16x32_bf16 v[118:121], v[138:141], v[164:167], v[118:121]
	v_mfma_f32_16x16x32_bf16 v[110:113], v[148:151], v[164:167], v[110:113]
	v_mfma_f32_16x16x32_bf16 v[102:105], v[138:141], v[172:175], v[102:105]
	v_mfma_f32_16x16x32_bf16 v[94:97], v[148:151], v[172:175], v[94:97]
	v_mfma_f32_16x16x32_bf16 v[86:89], v[138:141], v[180:183], v[86:89]
	v_mfma_f32_16x16x32_bf16 v[78:81], v[148:151], v[180:183], v[78:81]
	v_mfma_f32_16x16x32_bf16 v[126:129], v[142:145], v[160:163], v[126:129]
	v_mfma_f32_16x16x32_bf16 v[122:125], v[152:155], v[160:163], v[122:125]
	v_mfma_f32_16x16x32_bf16 v[118:121], v[142:145], v[168:171], v[118:121]
	v_mfma_f32_16x16x32_bf16 v[110:113], v[152:155], v[168:171], v[110:113]
	v_mfma_f32_16x16x32_bf16 v[102:105], v[142:145], v[176:179], v[102:105]
	v_mfma_f32_16x16x32_bf16 v[94:97], v[152:155], v[176:179], v[94:97]
	v_mfma_f32_16x16x32_bf16 v[86:89], v[142:145], v[184:187], v[86:89]
	v_mfma_f32_16x16x32_bf16 v[78:81], v[152:155], v[184:187], v[78:81]
	s_barrier
	s_setprio 0
	s_add_i32 s7, 0, 0x14000
	v_add_u32_e32 v132, s7, v135
	s_add_i32 s11, s43, s57
	ds_read_b128 v[188:191], v132
	ds_read_b128 v[192:195], v132 offset:1024
	ds_read_b128 v[196:199], v132 offset:2048
	ds_read_b128 v[200:203], v132 offset:3072
	v_lshl_add_u64 v[132:133], s[90:91], 0, v[0:1]
	s_mov_b32 m0, s11
	v_lshl_add_u64 v[204:205], v[132:133], 0, s[60:61]
	global_load_lds_dwordx4 v[132:133], off
	s_add_i32 m0, s11, 0x2000
	s_nop 0
	global_load_lds_dwordx4 v[204:205], off
	s_setprio 1
	s_barrier
	s_waitcnt lgkmcnt(0)
	v_mfma_f32_16x16x32_bf16 v[114:117], v[188:191], v[156:159], v[114:117]
	v_mfma_f32_16x16x32_bf16 v[106:109], v[196:199], v[156:159], v[106:109]
	v_mfma_f32_16x16x32_bf16 v[98:101], v[188:191], v[164:167], v[98:101]
	v_mfma_f32_16x16x32_bf16 v[90:93], v[196:199], v[164:167], v[90:93]
	v_mfma_f32_16x16x32_bf16 v[82:85], v[188:191], v[172:175], v[82:85]
	v_mfma_f32_16x16x32_bf16 v[74:77], v[196:199], v[172:175], v[74:77]
	v_mfma_f32_16x16x32_bf16 v[70:73], v[188:191], v[180:183], v[70:73]
	v_mfma_f32_16x16x32_bf16 v[66:69], v[196:199], v[180:183], v[66:69]
	v_mfma_f32_16x16x32_bf16 v[114:117], v[192:195], v[160:163], v[114:117]
	v_mfma_f32_16x16x32_bf16 v[106:109], v[200:203], v[160:163], v[106:109]
	v_mfma_f32_16x16x32_bf16 v[98:101], v[192:195], v[168:171], v[98:101]
	v_mfma_f32_16x16x32_bf16 v[90:93], v[200:203], v[168:171], v[90:93]
	v_mfma_f32_16x16x32_bf16 v[82:85], v[192:195], v[176:179], v[82:85]
	v_mfma_f32_16x16x32_bf16 v[74:77], v[200:203], v[176:179], v[74:77]
	v_mfma_f32_16x16x32_bf16 v[70:73], v[192:195], v[184:187], v[70:73]
	v_mfma_f32_16x16x32_bf16 v[66:69], v[200:203], v[184:187], v[66:69]
	s_barrier
	s_setprio 0
	s_mov_b32 m0, s49
	v_lshl_add_u64 v[204:205], s[78:79], 0, v[0:1]
	ds_read_b128 v[156:159], v136 offset:16384
	ds_read_b128 v[160:163], v136 offset:17408
	ds_read_b128 v[164:167], v136 offset:18432
	ds_read_b128 v[168:171], v136 offset:19456
	ds_read_b128 v[172:175], v136 offset:20480
	ds_read_b128 v[176:179], v136 offset:21504
	ds_read_b128 v[180:183], v136 offset:22528
	ds_read_b128 v[184:187], v136 offset:23552
	global_load_lds_dwordx4 v[204:205], off
	v_lshl_add_u64 v[206:207], v[204:205], 0, s[60:61]
	s_mov_b32 m0, s58
	s_nop 0
	global_load_lds_dwordx4 v[206:207], off
	s_setprio 1
	s_barrier
	s_waitcnt lgkmcnt(0)
	v_mfma_f32_16x16x32_bf16 v[62:65], v[138:141], v[156:159], v[62:65]
	v_mfma_f32_16x16x32_bf16 v[58:61], v[148:151], v[156:159], v[58:61]
	v_mfma_f32_16x16x32_bf16 v[54:57], v[138:141], v[164:167], v[54:57]
	v_mfma_f32_16x16x32_bf16 v[46:49], v[148:151], v[164:167], v[46:49]
	v_mfma_f32_16x16x32_bf16 v[38:41], v[138:141], v[172:175], v[38:41]
	v_mfma_f32_16x16x32_bf16 v[30:33], v[148:151], v[172:175], v[30:33]
	v_mfma_f32_16x16x32_bf16 v[22:25], v[138:141], v[180:183], v[22:25]
	v_mfma_f32_16x16x32_bf16 v[14:17], v[148:151], v[180:183], v[14:17]
	v_mfma_f32_16x16x32_bf16 v[62:65], v[142:145], v[160:163], v[62:65]
	v_mfma_f32_16x16x32_bf16 v[58:61], v[152:155], v[160:163], v[58:61]
	v_mfma_f32_16x16x32_bf16 v[54:57], v[142:145], v[168:171], v[54:57]
	v_mfma_f32_16x16x32_bf16 v[46:49], v[152:155], v[168:171], v[46:49]
	v_mfma_f32_16x16x32_bf16 v[38:41], v[142:145], v[176:179], v[38:41]
	v_mfma_f32_16x16x32_bf16 v[30:33], v[152:155], v[176:179], v[30:33]
	v_mfma_f32_16x16x32_bf16 v[22:25], v[142:145], v[184:187], v[22:25]
	v_mfma_f32_16x16x32_bf16 v[14:17], v[152:155], v[184:187], v[14:17]
	s_barrier
	s_setprio 0
	s_add_i32 s7, s7, s57
	v_lshl_add_u64 v[138:139], v[132:133], 0, s[20:21]
	s_mov_b32 m0, s7
	s_nop 0
	global_load_lds_dwordx4 v[138:139], off
	v_lshl_add_u64 v[138:139], v[132:133], 0, s[64:65]
	s_add_i32 m0, s7, 0x2000
	s_nop 0
	global_load_lds_dwordx4 v[138:139], off
	v_lshl_add_u64 v[230:231], v[204:205], 0, s[20:21]
	s_mov_b32 m0, s59
	s_nop 0
	global_load_lds_dwordx4 v[230:231], off
	v_lshl_add_u64 v[230:231], v[204:205], 0, s[64:65]
	s_mov_b32 m0, s62
	s_nop 0
	global_load_lds_dwordx4 v[230:231], off
	s_waitcnt vmcnt(8)
	s_setprio 1
	s_barrier
	v_mfma_f32_16x16x32_bf16 v[50:53], v[188:191], v[156:159], v[50:53]
	v_mfma_f32_16x16x32_bf16 v[42:45], v[196:199], v[156:159], v[42:45]
	v_mfma_f32_16x16x32_bf16 v[34:37], v[188:191], v[164:167], v[34:37]
	v_mfma_f32_16x16x32_bf16 v[26:29], v[196:199], v[164:167], v[26:29]
	v_mfma_f32_16x16x32_bf16 v[18:21], v[188:191], v[172:175], v[18:21]
	v_mfma_f32_16x16x32_bf16 v[10:13], v[196:199], v[172:175], v[10:13]
	v_mfma_f32_16x16x32_bf16 v[6:9], v[188:191], v[180:183], v[6:9]
	v_mfma_f32_16x16x32_bf16 v[2:5], v[196:199], v[180:183], v[2:5]
	v_mfma_f32_16x16x32_bf16 v[50:53], v[192:195], v[160:163], v[50:53]
	v_mfma_f32_16x16x32_bf16 v[42:45], v[200:203], v[160:163], v[42:45]
	v_mfma_f32_16x16x32_bf16 v[34:37], v[192:195], v[168:171], v[34:37]
	v_mfma_f32_16x16x32_bf16 v[26:29], v[200:203], v[168:171], v[26:29]
	v_mfma_f32_16x16x32_bf16 v[18:21], v[192:195], v[176:179], v[18:21]
	v_mfma_f32_16x16x32_bf16 v[10:13], v[200:203], v[176:179], v[10:13]
	v_mfma_f32_16x16x32_bf16 v[6:9], v[192:195], v[184:187], v[6:9]
	v_mfma_f32_16x16x32_bf16 v[2:5], v[200:203], v[184:187], v[2:5]
	s_barrier
	s_setprio 0
	s_add_i32 s7, 0, 0x18000
	v_add_u32_e32 v137, s7, v135
	ds_read_b128 v[138:141], v137
	ds_read_b128 v[142:145], v137 offset:1024
	ds_read_b128 v[148:151], v137 offset:2048
	ds_read_b128 v[152:155], v137 offset:3072
	ds_read_b128 v[156:159], v136 offset:32768
	ds_read_b128 v[160:163], v136 offset:33792
	ds_read_b128 v[164:167], v136 offset:34816
	ds_read_b128 v[168:171], v136 offset:35840
	ds_read_b128 v[172:175], v136 offset:36864
	ds_read_b128 v[176:179], v136 offset:37888
	ds_read_b128 v[180:183], v136 offset:38912
	ds_read_b128 v[184:187], v136 offset:39936
	s_waitcnt lgkmcnt(8)
	s_setprio 1
	s_barrier
	s_waitcnt lgkmcnt(0)
	v_mfma_f32_16x16x32_bf16 v[126:129], v[138:141], v[156:159], v[126:129]
	v_mfma_f32_16x16x32_bf16 v[122:125], v[148:151], v[156:159], v[122:125]
	v_mfma_f32_16x16x32_bf16 v[118:121], v[138:141], v[164:167], v[118:121]
	v_mfma_f32_16x16x32_bf16 v[110:113], v[148:151], v[164:167], v[110:113]
	v_mfma_f32_16x16x32_bf16 v[102:105], v[138:141], v[172:175], v[102:105]
	v_mfma_f32_16x16x32_bf16 v[94:97], v[148:151], v[172:175], v[94:97]
	v_mfma_f32_16x16x32_bf16 v[86:89], v[138:141], v[180:183], v[86:89]
	v_mfma_f32_16x16x32_bf16 v[78:81], v[148:151], v[180:183], v[78:81]
	v_mfma_f32_16x16x32_bf16 v[126:129], v[142:145], v[160:163], v[126:129]
	v_mfma_f32_16x16x32_bf16 v[122:125], v[152:155], v[160:163], v[122:125]
	v_mfma_f32_16x16x32_bf16 v[118:121], v[142:145], v[168:171], v[118:121]
	v_mfma_f32_16x16x32_bf16 v[110:113], v[152:155], v[168:171], v[110:113]
	v_mfma_f32_16x16x32_bf16 v[102:105], v[142:145], v[176:179], v[102:105]
	v_mfma_f32_16x16x32_bf16 v[94:97], v[152:155], v[176:179], v[94:97]
	v_mfma_f32_16x16x32_bf16 v[86:89], v[142:145], v[184:187], v[86:89]
	v_mfma_f32_16x16x32_bf16 v[78:81], v[152:155], v[184:187], v[78:81]
	s_barrier
	s_setprio 0
	s_add_i32 s11, 0, 0x1c000
	s_add_i32 s7, s7, s57
	v_add_u32_e32 v137, s11, v135
	v_lshl_add_u64 v[206:207], v[132:133], 0, s[34:35]
	s_mov_b32 m0, s7
	ds_read_b128 v[188:191], v137
	ds_read_b128 v[192:195], v137 offset:1024
	ds_read_b128 v[196:199], v137 offset:2048
	ds_read_b128 v[200:203], v137 offset:3072
	global_load_lds_dwordx4 v[206:207], off
	v_lshl_add_u64 v[206:207], v[132:133], 0, s[66:67]
	s_add_i32 m0, s7, 0x2000
	s_nop 0
	global_load_lds_dwordx4 v[206:207], off
	s_setprio 1
	s_barrier
	s_waitcnt lgkmcnt(0)
	v_mfma_f32_16x16x32_bf16 v[114:117], v[188:191], v[156:159], v[114:117]
	v_mfma_f32_16x16x32_bf16 v[106:109], v[196:199], v[156:159], v[106:109]
	v_mfma_f32_16x16x32_bf16 v[98:101], v[188:191], v[164:167], v[98:101]
	v_mfma_f32_16x16x32_bf16 v[90:93], v[196:199], v[164:167], v[90:93]
	v_mfma_f32_16x16x32_bf16 v[82:85], v[188:191], v[172:175], v[82:85]
	v_mfma_f32_16x16x32_bf16 v[74:77], v[196:199], v[172:175], v[74:77]
	v_mfma_f32_16x16x32_bf16 v[70:73], v[188:191], v[180:183], v[70:73]
	v_mfma_f32_16x16x32_bf16 v[66:69], v[196:199], v[180:183], v[66:69]
	v_mfma_f32_16x16x32_bf16 v[114:117], v[192:195], v[160:163], v[114:117]
	v_mfma_f32_16x16x32_bf16 v[106:109], v[200:203], v[160:163], v[106:109]
	v_mfma_f32_16x16x32_bf16 v[98:101], v[192:195], v[168:171], v[98:101]
	v_mfma_f32_16x16x32_bf16 v[90:93], v[200:203], v[168:171], v[90:93]
	v_mfma_f32_16x16x32_bf16 v[82:85], v[192:195], v[176:179], v[82:85]
	v_mfma_f32_16x16x32_bf16 v[74:77], v[200:203], v[176:179], v[74:77]
	v_mfma_f32_16x16x32_bf16 v[70:73], v[192:195], v[184:187], v[70:73]
	v_mfma_f32_16x16x32_bf16 v[66:69], v[200:203], v[184:187], v[66:69]
	s_barrier
	s_setprio 0
	s_mov_b32 m0, s85
	v_lshl_add_u64 v[206:207], v[204:205], 0, s[34:35]
	ds_read_b128 v[156:159], v136 offset:49152
	ds_read_b128 v[160:163], v136 offset:50176
	ds_read_b128 v[164:167], v136 offset:51200
	ds_read_b128 v[168:171], v136 offset:52224
	ds_read_b128 v[172:175], v136 offset:53248
	ds_read_b128 v[176:179], v136 offset:54272
	ds_read_b128 v[180:183], v136 offset:55296
	ds_read_b128 v[184:187], v136 offset:56320
	global_load_lds_dwordx4 v[206:207], off
	v_lshl_add_u64 v[204:205], v[204:205], 0, s[66:67]
	s_mov_b32 m0, s86
	s_nop 0
	global_load_lds_dwordx4 v[204:205], off
	s_setprio 1
	s_barrier
	s_waitcnt lgkmcnt(0)
	v_mfma_f32_16x16x32_bf16 v[62:65], v[138:141], v[156:159], v[62:65]
	v_mfma_f32_16x16x32_bf16 v[58:61], v[148:151], v[156:159], v[58:61]
	v_mfma_f32_16x16x32_bf16 v[54:57], v[138:141], v[164:167], v[54:57]
	v_mfma_f32_16x16x32_bf16 v[46:49], v[148:151], v[164:167], v[46:49]
	v_mfma_f32_16x16x32_bf16 v[38:41], v[138:141], v[172:175], v[38:41]
	v_mfma_f32_16x16x32_bf16 v[30:33], v[148:151], v[172:175], v[30:33]
	v_mfma_f32_16x16x32_bf16 v[22:25], v[138:141], v[180:183], v[22:25]
	v_mfma_f32_16x16x32_bf16 v[14:17], v[148:151], v[180:183], v[14:17]
	v_mfma_f32_16x16x32_bf16 v[62:65], v[142:145], v[160:163], v[62:65]
	v_mfma_f32_16x16x32_bf16 v[58:61], v[152:155], v[160:163], v[58:61]
	v_mfma_f32_16x16x32_bf16 v[54:57], v[142:145], v[168:171], v[54:57]
	v_mfma_f32_16x16x32_bf16 v[46:49], v[152:155], v[168:171], v[46:49]
	v_mfma_f32_16x16x32_bf16 v[38:41], v[142:145], v[176:179], v[38:41]
	v_mfma_f32_16x16x32_bf16 v[30:33], v[152:155], v[176:179], v[30:33]
	v_mfma_f32_16x16x32_bf16 v[22:25], v[142:145], v[184:187], v[22:25]
	v_mfma_f32_16x16x32_bf16 v[14:17], v[152:155], v[184:187], v[14:17]
	s_barrier
	s_setprio 0
	s_add_i32 s7, s11, s57
	v_lshl_add_u64 v[138:139], v[132:133], 0, s[16:17]
	s_mov_b32 m0, s7
	v_lshl_add_u64 v[132:133], v[132:133], 0, s[80:81]
	global_load_lds_dwordx4 v[138:139], off
	s_add_i32 m0, s7, 0x2000
	s_nop 0
	global_load_lds_dwordx4 v[132:133], off
	s_waitcnt vmcnt(6)
	s_add_i32 s6, s6, 2
	s_add_u32 s8, s8, 0x100
	s_addc_u32 s9, s9, 0
	s_add_u32 s50, s50, 0x100
	s_addc_u32 s51, s51, 0
	s_cmp_gt_u32 s6, 29
	s_cbranch_scc0 .LBB0_97
	s_setprio 1
	s_barrier
	v_mfma_f32_16x16x32_bf16 v[50:53], v[188:191], v[156:159], v[50:53]
	v_mfma_f32_16x16x32_bf16 v[42:45], v[196:199], v[156:159], v[42:45]
	v_mfma_f32_16x16x32_bf16 v[34:37], v[188:191], v[164:167], v[34:37]
	v_mfma_f32_16x16x32_bf16 v[26:29], v[196:199], v[164:167], v[26:29]
	v_mfma_f32_16x16x32_bf16 v[18:21], v[188:191], v[172:175], v[18:21]
	v_mfma_f32_16x16x32_bf16 v[10:13], v[196:199], v[172:175], v[10:13]
	v_mfma_f32_16x16x32_bf16 v[6:9], v[188:191], v[180:183], v[6:9]
	v_mfma_f32_16x16x32_bf16 v[2:5], v[196:199], v[180:183], v[2:5]
	v_mfma_f32_16x16x32_bf16 v[50:53], v[192:195], v[160:163], v[50:53]
	v_mfma_f32_16x16x32_bf16 v[42:45], v[200:203], v[160:163], v[42:45]
	v_mfma_f32_16x16x32_bf16 v[34:37], v[192:195], v[168:171], v[34:37]
	v_mfma_f32_16x16x32_bf16 v[26:29], v[200:203], v[168:171], v[26:29]
	v_mfma_f32_16x16x32_bf16 v[18:21], v[192:195], v[176:179], v[18:21]
	v_mfma_f32_16x16x32_bf16 v[10:13], v[200:203], v[176:179], v[10:13]
	v_mfma_f32_16x16x32_bf16 v[6:9], v[192:195], v[184:187], v[6:9]
	v_mfma_f32_16x16x32_bf16 v[2:5], v[200:203], v[184:187], v[2:5]
	s_barrier
	s_setprio 0
	v_mov_b32_e32 v137, v134
	s_lshl_b32 s6, s88, 8
	v_ashrrev_i32_e32 v132, 2, v137
	s_or_b32 s6, s6, s84
	v_and_b32_e32 v132, -4, v132
	v_add_u32_e32 v132, s6, v132
	s_lshl_b32 s6, s48, 8
	s_add_i32 s6, s6, s63
	v_and_or_b32 v188, v137, 15, s6
	v_ashrrev_i32_e32 v189, 31, v188
	v_ashrrev_i32_e32 v133, 31, v132
	v_lshlrev_b64 v[206:207], 13, v[188:189]
	v_or_b32_e32 v156, 16, v188
	v_or_b32_e32 v172, 32, v188
	v_or_b32_e32 v188, 48, v188
	v_lshlrev_b64 v[132:133], 2, v[132:133]
	v_ashrrev_i32_e32 v157, 31, v156
	v_ashrrev_i32_e32 v173, 31, v172
	v_ashrrev_i32_e32 v189, 31, v188
	v_lshl_add_u64 v[204:205], s[4:5], 0, v[132:133]
	v_lshlrev_b64 v[208:209], 13, v[156:157]
	v_lshlrev_b64 v[210:211], 13, v[172:173]
	v_lshlrev_b64 v[212:213], 13, v[188:189]
	v_lshl_add_u64 v[152:153], v[204:205], 0, v[206:207]
	v_lshl_add_u64 v[168:169], v[204:205], 0, v[208:209]
	v_lshl_add_u64 v[184:185], v[204:205], 0, v[210:211]
	v_lshl_add_u64 v[200:201], v[204:205], 0, v[212:213]
	global_load_dwordx4 v[138:141], v[152:153], off
	global_load_dwordx4 v[142:145], v[152:153], off offset:64
	global_load_dwordx4 v[148:151], v[152:153], off offset:512
	s_nop 0
	global_load_dwordx4 v[152:155], v[152:153], off offset:576
	s_nop 0
	global_load_dwordx4 v[156:159], v[168:169], off
	global_load_dwordx4 v[160:163], v[168:169], off offset:64
	global_load_dwordx4 v[164:167], v[168:169], off offset:512
	s_nop 0
	global_load_dwordx4 v[168:171], v[168:169], off offset:576
	s_nop 0
	global_load_dwordx4 v[172:175], v[184:185], off
	global_load_dwordx4 v[176:179], v[184:185], off offset:64
	global_load_dwordx4 v[180:183], v[184:185], off offset:512
	s_nop 0
	global_load_dwordx4 v[184:187], v[184:185], off offset:576
	s_nop 0
	global_load_dwordx4 v[188:191], v[200:201], off
	global_load_dwordx4 v[192:195], v[200:201], off offset:64
	global_load_dwordx4 v[196:199], v[200:201], off offset:512
	s_nop 0
	global_load_dwordx4 v[200:203], v[200:201], off offset:576
	s_waitcnt vmcnt(0) lgkmcnt(0)
	v_pk_add_f32 v[126:127], v[126:127], v[138:139]
	v_lshl_add_u64 v[138:139], s[4:5], 0, v[206:207]
	v_lshl_add_u64 v[138:139], v[138:139], 0, v[132:133]
	v_pk_add_f32 v[116:117], v[116:117], v[150:151]
	v_pk_add_f32 v[114:115], v[114:115], v[148:149]
	global_store_dwordx4 v[138:139], v[114:117], off offset:512
	v_pk_add_f32 v[100:101], v[100:101], v[166:167]
	v_pk_add_f32 v[98:99], v[98:99], v[164:165]
	v_lshl_add_u64 v[114:115], s[4:5], 0, v[208:209]
	v_lshl_add_u64 v[114:115], v[114:115], 0, v[132:133]
	global_store_dwordx4 v[114:115], v[98:101], off offset:512
	v_pk_add_f32 v[84:85], v[84:85], v[182:183]
	v_pk_add_f32 v[82:83], v[82:83], v[180:181]
	v_lshl_add_u64 v[98:99], s[4:5], 0, v[210:211]
	v_lshl_add_u64 v[98:99], v[98:99], 0, v[132:133]
	v_pk_add_f32 v[108:109], v[108:109], v[154:155]
	v_pk_add_f32 v[106:107], v[106:107], v[152:153]
	v_pk_add_f32 v[92:93], v[92:93], v[170:171]
	v_pk_add_f32 v[90:91], v[90:91], v[168:169]
	global_store_dwordx4 v[98:99], v[82:85], off offset:512
	v_pk_add_f32 v[76:77], v[76:77], v[186:187]
	v_pk_add_f32 v[74:75], v[74:75], v[184:185]
	v_lshl_add_u64 v[82:83], s[4:5], 0, v[212:213]
	global_store_dwordx4 v[138:139], v[106:109], off offset:576
	global_store_dwordx4 v[114:115], v[90:93], off offset:576
	global_store_dwordx4 v[98:99], v[74:77], off offset:576
	v_pk_add_f32 v[108:109], v[120:121], v[158:159]
	v_pk_add_f32 v[106:107], v[118:119], v[156:157]
	v_pk_add_f32 v[92:93], v[104:105], v[174:175]
	v_pk_add_f32 v[90:91], v[102:103], v[172:173]
	v_pk_add_f32 v[76:77], v[88:89], v[190:191]
	v_pk_add_f32 v[74:75], v[86:87], v[188:189]
	v_lshl_add_u64 v[82:83], v[82:83], 0, v[132:133]
	v_pk_add_f32 v[128:129], v[128:129], v[140:141]
	v_pk_add_f32 v[124:125], v[124:125], v[144:145]
	v_pk_add_f32 v[122:123], v[122:123], v[142:143]
	global_store_dwordx4 v[114:115], v[106:109], off
	global_store_dwordx4 v[98:99], v[90:93], off
	global_store_dwordx4 v[82:83], v[74:77], off
	v_pk_add_f32 v[108:109], v[112:113], v[162:163]
	v_pk_add_f32 v[106:107], v[110:111], v[160:161]
	v_pk_add_f32 v[92:93], v[96:97], v[178:179]
	v_pk_add_f32 v[90:91], v[94:95], v[176:177]
	v_pk_add_f32 v[76:77], v[80:81], v[194:195]
	v_pk_add_f32 v[74:75], v[78:79], v[192:193]
	v_pk_add_f32 v[72:73], v[72:73], v[198:199]
	v_pk_add_f32 v[70:71], v[70:71], v[196:197]
	v_pk_add_f32 v[68:69], v[68:69], v[202:203]
	v_pk_add_f32 v[66:67], v[66:67], v[200:201]
	global_store_dwordx4 v[138:139], v[126:129], off
	global_store_dwordx4 v[138:139], v[122:125], off offset:64
	global_store_dwordx4 v[114:115], v[106:109], off offset:64
	global_store_dwordx4 v[98:99], v[90:93], off offset:64
	global_store_dwordx4 v[82:83], v[74:77], off offset:64
	global_store_dwordx4 v[82:83], v[70:73], off offset:512
	global_store_dwordx4 v[82:83], v[66:69], off offset:576
	s_mov_b64 s[6:7], 0x120000
	v_lshl_add_u64 v[140:141], v[206:207], 0, s[6:7]
	s_mov_b64 s[6:7], 0x140000
	v_lshl_add_u64 v[138:139], v[206:207], 0, s[0:1]
	v_lshl_add_u64 v[142:143], v[206:207], 0, s[6:7]
	v_lshl_add_u64 v[144:145], v[206:207], 0, s[28:29]
	v_lshl_add_u64 v[78:79], v[204:205], 0, v[138:139]
	v_lshl_add_u64 v[94:95], v[204:205], 0, v[140:141]
	v_lshl_add_u64 v[110:111], v[204:205], 0, v[142:143]
	v_lshl_add_u64 v[126:127], v[204:205], 0, v[144:145]
	global_load_dwordx4 v[66:69], v[78:79], off
	global_load_dwordx4 v[70:73], v[78:79], off offset:64
	global_load_dwordx4 v[74:77], v[78:79], off offset:512
	s_nop 0
	global_load_dwordx4 v[78:81], v[78:79], off offset:576
	s_nop 0
	global_load_dwordx4 v[82:85], v[94:95], off
	global_load_dwordx4 v[86:89], v[94:95], off offset:64
	global_load_dwordx4 v[90:93], v[94:95], off offset:512
	s_nop 0
	global_load_dwordx4 v[94:97], v[94:95], off offset:576
	s_nop 0
	global_load_dwordx4 v[98:101], v[110:111], off
	global_load_dwordx4 v[102:105], v[110:111], off offset:64
	global_load_dwordx4 v[106:109], v[110:111], off offset:512
	s_nop 0
	global_load_dwordx4 v[110:113], v[110:111], off offset:576
	s_nop 0
	global_load_dwordx4 v[114:117], v[126:127], off
	global_load_dwordx4 v[118:121], v[126:127], off offset:64
	global_load_dwordx4 v[122:125], v[126:127], off offset:512
	s_nop 0
	global_load_dwordx4 v[126:129], v[126:127], off offset:576
	s_waitcnt vmcnt(0) lgkmcnt(0)
	v_pk_add_f32 v[62:63], v[62:63], v[66:67]
	v_lshl_add_u64 v[66:67], s[4:5], 0, v[138:139]
	v_lshl_add_u64 v[66:67], v[66:67], 0, v[132:133]
	v_pk_add_f32 v[52:53], v[52:53], v[76:77]
	v_pk_add_f32 v[50:51], v[50:51], v[74:75]
	global_store_dwordx4 v[66:67], v[50:53], off offset:512
	v_pk_add_f32 v[36:37], v[36:37], v[92:93]
	v_pk_add_f32 v[34:35], v[34:35], v[90:91]
	v_lshl_add_u64 v[50:51], s[4:5], 0, v[140:141]
	v_lshl_add_u64 v[50:51], v[50:51], 0, v[132:133]
	global_store_dwordx4 v[50:51], v[34:37], off offset:512
	v_pk_add_f32 v[20:21], v[20:21], v[108:109]
	v_pk_add_f32 v[18:19], v[18:19], v[106:107]
	v_lshl_add_u64 v[34:35], s[4:5], 0, v[142:143]
	v_lshl_add_u64 v[34:35], v[34:35], 0, v[132:133]
	v_pk_add_f32 v[44:45], v[44:45], v[80:81]
	v_pk_add_f32 v[42:43], v[42:43], v[78:79]
	v_pk_add_f32 v[28:29], v[28:29], v[96:97]
	v_pk_add_f32 v[26:27], v[26:27], v[94:95]
	global_store_dwordx4 v[34:35], v[18:21], off offset:512
	v_pk_add_f32 v[12:13], v[12:13], v[112:113]
	v_pk_add_f32 v[10:11], v[10:11], v[110:111]
	v_lshl_add_u64 v[18:19], s[4:5], 0, v[144:145]
	global_store_dwordx4 v[66:67], v[42:45], off offset:576
	global_store_dwordx4 v[50:51], v[26:29], off offset:576
	global_store_dwordx4 v[34:35], v[10:13], off offset:576
	v_pk_add_f32 v[44:45], v[56:57], v[84:85]
	v_pk_add_f32 v[42:43], v[54:55], v[82:83]
	v_pk_add_f32 v[28:29], v[40:41], v[100:101]
	v_pk_add_f32 v[26:27], v[38:39], v[98:99]
	v_pk_add_f32 v[12:13], v[24:25], v[116:117]
	v_pk_add_f32 v[10:11], v[22:23], v[114:115]
	v_lshl_add_u64 v[18:19], v[18:19], 0, v[132:133]
	v_pk_add_f32 v[64:65], v[64:65], v[68:69]
	v_pk_add_f32 v[60:61], v[60:61], v[72:73]
	v_pk_add_f32 v[58:59], v[58:59], v[70:71]
	global_store_dwordx4 v[50:51], v[42:45], off
	global_store_dwordx4 v[34:35], v[26:29], off
	global_store_dwordx4 v[18:19], v[10:13], off
	v_pk_add_f32 v[44:45], v[48:49], v[88:89]
	v_pk_add_f32 v[42:43], v[46:47], v[86:87]
	v_pk_add_f32 v[28:29], v[32:33], v[104:105]
	v_pk_add_f32 v[26:27], v[30:31], v[102:103]
	v_pk_add_f32 v[12:13], v[16:17], v[120:121]
	v_pk_add_f32 v[10:11], v[14:15], v[118:119]
	v_pk_add_f32 v[8:9], v[8:9], v[124:125]
	v_pk_add_f32 v[6:7], v[6:7], v[122:123]
	v_pk_add_f32 v[4:5], v[4:5], v[128:129]
	v_pk_add_f32 v[2:3], v[2:3], v[126:127]
	global_store_dwordx4 v[66:67], v[62:65], off
	global_store_dwordx4 v[66:67], v[58:61], off offset:64
	global_store_dwordx4 v[50:51], v[42:45], off offset:64
	global_store_dwordx4 v[34:35], v[26:29], off offset:64
	global_store_dwordx4 v[18:19], v[10:13], off offset:64
	global_store_dwordx4 v[18:19], v[6:9], off offset:512
	global_store_dwordx4 v[18:19], v[2:5], off offset:576
	v_readlane_b32 s50, v255, 28
	s_and_b64 vcc, exec, s[40:41]
	s_mov_b32 s48, s42
	s_mov_b32 s88, s10
	s_mov_b64 s[8:9], s[46:47]
	s_mov_b64 s[6:7], s[44:45]
	v_readlane_b32 s51, v255, 29
	s_movk_i32 s91, 0x60
	s_mov_b32 s78, 0x2a000000
	s_mov_b32 s79, 0x3fffe
	s_mov_b32 s90, 0xc0000
	s_cbranch_vccz .LBB0_90
	s_waitcnt vmcnt(0)
	s_cmpk_gt_u32 s52, 0xff
	s_cbranch_scc1 .LBB0_101
	s_barrier

.LBB0_291:
	s_add_u32 s8, s6, 0x100
	v_mov_b32_e32 v2, 0
	s_addc_u32 s9, s7, 0
	s_mov_b32 s10, -2
	v_mov_b32_e32 v3, v2
	v_mov_b32_e32 v4, v2
	v_mov_b32_e32 v5, v2
	v_mov_b32_e32 v6, v2
	v_mov_b32_e32 v7, v2
	v_mov_b32_e32 v8, v2
	v_mov_b32_e32 v9, v2
	v_mov_b32_e32 v18, v2
	v_mov_b32_e32 v19, v2
	v_mov_b32_e32 v20, v2
	v_mov_b32_e32 v21, v2
	v_mov_b32_e32 v22, v2
	v_mov_b32_e32 v23, v2
	v_mov_b32_e32 v24, v2
	v_mov_b32_e32 v25, v2
	v_mov_b32_e32 v34, v2
	v_mov_b32_e32 v35, v2
	v_mov_b32_e32 v36, v2
	v_mov_b32_e32 v37, v2
	v_mov_b32_e32 v38, v2
	v_mov_b32_e32 v39, v2
	v_mov_b32_e32 v40, v2
	v_mov_b32_e32 v41, v2
	v_mov_b32_e32 v50, v2
	v_mov_b32_e32 v51, v2
	v_mov_b32_e32 v52, v2
	v_mov_b32_e32 v53, v2
	v_mov_b32_e32 v54, v2
	v_mov_b32_e32 v55, v2
	v_mov_b32_e32 v56, v2
	v_mov_b32_e32 v57, v2
	v_mov_b32_e32 v10, v2
	v_mov_b32_e32 v11, v2
	v_mov_b32_e32 v12, v2
	v_mov_b32_e32 v13, v2
	v_mov_b32_e32 v14, v2
	v_mov_b32_e32 v15, v2
	v_mov_b32_e32 v16, v2
	v_mov_b32_e32 v17, v2
	v_mov_b32_e32 v26, v2
	v_mov_b32_e32 v27, v2
	v_mov_b32_e32 v28, v2
	v_mov_b32_e32 v29, v2
	v_mov_b32_e32 v30, v2
	v_mov_b32_e32 v31, v2
	v_mov_b32_e32 v32, v2
	v_mov_b32_e32 v33, v2
	v_mov_b32_e32 v42, v2
	v_mov_b32_e32 v43, v2
	v_mov_b32_e32 v44, v2
	v_mov_b32_e32 v45, v2
	v_mov_b32_e32 v46, v2
	v_mov_b32_e32 v47, v2
	v_mov_b32_e32 v48, v2
	v_mov_b32_e32 v49, v2
	v_mov_b32_e32 v58, v2
	v_mov_b32_e32 v59, v2
	v_mov_b32_e32 v60, v2
	v_mov_b32_e32 v61, v2
	v_mov_b32_e32 v62, v2
	v_mov_b32_e32 v63, v2
	v_mov_b32_e32 v64, v2
	v_mov_b32_e32 v65, v2
	v_mov_b32_e32 v66, v2
	v_mov_b32_e32 v67, v2
	v_mov_b32_e32 v68, v2
	v_mov_b32_e32 v69, v2
	v_mov_b32_e32 v70, v2
	v_mov_b32_e32 v71, v2
	v_mov_b32_e32 v72, v2
	v_mov_b32_e32 v73, v2
	v_mov_b32_e32 v82, v2
	v_mov_b32_e32 v83, v2
	v_mov_b32_e32 v84, v2
	v_mov_b32_e32 v85, v2
	v_mov_b32_e32 v86, v2
	v_mov_b32_e32 v87, v2
	v_mov_b32_e32 v88, v2
	v_mov_b32_e32 v89, v2
	v_mov_b32_e32 v98, v2
	v_mov_b32_e32 v99, v2
	v_mov_b32_e32 v100, v2
	v_mov_b32_e32 v101, v2
	v_mov_b32_e32 v102, v2
	v_mov_b32_e32 v103, v2
	v_mov_b32_e32 v104, v2
	v_mov_b32_e32 v105, v2
	v_mov_b32_e32 v114, v2
	v_mov_b32_e32 v115, v2
	v_mov_b32_e32 v116, v2
	v_mov_b32_e32 v117, v2
	v_mov_b32_e32 v118, v2
	v_mov_b32_e32 v119, v2
	v_mov_b32_e32 v120, v2
	v_mov_b32_e32 v121, v2
	v_mov_b32_e32 v74, v2
	v_mov_b32_e32 v75, v2
	v_mov_b32_e32 v76, v2
	v_mov_b32_e32 v77, v2
	v_mov_b32_e32 v78, v2
	v_mov_b32_e32 v79, v2
	v_mov_b32_e32 v80, v2
	v_mov_b32_e32 v81, v2
	v_mov_b32_e32 v90, v2
	v_mov_b32_e32 v91, v2
	v_mov_b32_e32 v92, v2
	v_mov_b32_e32 v93, v2
	v_mov_b32_e32 v94, v2
	v_mov_b32_e32 v95, v2
	v_mov_b32_e32 v96, v2
	v_mov_b32_e32 v97, v2
	v_mov_b32_e32 v106, v2
	v_mov_b32_e32 v107, v2
	v_mov_b32_e32 v108, v2
	v_mov_b32_e32 v109, v2
	v_mov_b32_e32 v110, v2
	v_mov_b32_e32 v111, v2
	v_mov_b32_e32 v112, v2
	v_mov_b32_e32 v113, v2
	v_mov_b32_e32 v122, v2
	v_mov_b32_e32 v123, v2
	v_mov_b32_e32 v124, v2
	v_mov_b32_e32 v125, v2
	v_mov_b32_e32 v126, v2
	v_mov_b32_e32 v127, v2
	v_mov_b32_e32 v128, v2
	v_mov_b32_e32 v129, v2
	s_branch .Lrot_enter_7
.LBB0_292:
	s_setprio 1
	s_barrier
	v_mfma_f32_16x16x32_bf16 v[54:57], v[192:195], v[160:163], v[54:57]
	v_mfma_f32_16x16x32_bf16 v[50:53], v[200:203], v[160:163], v[50:53]
	v_mfma_f32_16x16x32_bf16 v[38:41], v[192:195], v[168:171], v[38:41]
	v_mfma_f32_16x16x32_bf16 v[34:37], v[200:203], v[168:171], v[34:37]
	v_mfma_f32_16x16x32_bf16 v[22:25], v[192:195], v[176:179], v[22:25]
	v_mfma_f32_16x16x32_bf16 v[18:21], v[200:203], v[176:179], v[18:21]
	v_mfma_f32_16x16x32_bf16 v[6:9], v[192:195], v[184:187], v[6:9]
	v_mfma_f32_16x16x32_bf16 v[2:5], v[200:203], v[184:187], v[2:5]
	v_mfma_f32_16x16x32_bf16 v[54:57], v[196:199], v[164:167], v[54:57]
	v_mfma_f32_16x16x32_bf16 v[50:53], v[204:207], v[164:167], v[50:53]
	v_mfma_f32_16x16x32_bf16 v[38:41], v[196:199], v[172:175], v[38:41]
	v_mfma_f32_16x16x32_bf16 v[34:37], v[204:207], v[172:175], v[34:37]
	v_mfma_f32_16x16x32_bf16 v[22:25], v[196:199], v[180:183], v[22:25]
	v_mfma_f32_16x16x32_bf16 v[18:21], v[204:207], v[180:183], v[18:21]
	v_mfma_f32_16x16x32_bf16 v[6:9], v[196:199], v[188:191], v[6:9]
	v_mfma_f32_16x16x32_bf16 v[2:5], v[204:207], v[188:191], v[2:5]
	s_barrier
	s_setprio 0
.Lrot_enter_7:
	s_add_u32 s6, s4, 0x100
	s_addc_u32 s7, s5, 0
	s_add_i32 s11, 0, 0x10000
	v_add_u32_e32 v138, s11, v141
	ds_read_b128 v[130:133], v138
	ds_read_b128 v[148:151], v138 offset:1024
	ds_read_b128 v[152:155], v138 offset:2048
	ds_read_b128 v[156:159], v138 offset:3072
	s_cmp_eq_u32 s10, 28
	s_cselect_b32 s41, s47, s7
	s_cselect_b32 s40, s46, s6
	s_cselect_b32 s93, s49, s9
	s_cselect_b32 s92, s48, s8
	v_lshl_add_u64 v[144:145], s[4:5], 0, v[136:137]
	v_lshl_add_u64 v[192:193], v[144:145], 0, s[16:17]
	s_add_i32 m0, s54, 0xc000
	ds_read_b128 v[160:163], v142
	ds_read_b128 v[164:167], v142 offset:1024
	ds_read_b128 v[168:171], v142 offset:2048
	ds_read_b128 v[172:175], v142 offset:3072
	ds_read_b128 v[176:179], v142 offset:4096
	ds_read_b128 v[180:183], v142 offset:5120
	ds_read_b128 v[184:187], v142 offset:6144
	ds_read_b128 v[188:191], v142 offset:7168
	global_load_lds_dwordx4 v[192:193], off
	v_lshl_add_u64 v[144:145], v[144:145], 0, s[80:81]
	s_add_i32 m0, s54, 0xe000
	s_nop 0
	global_load_lds_dwordx4 v[144:145], off
	s_waitcnt lgkmcnt(8)
	s_setprio 1
	s_barrier
	s_waitcnt lgkmcnt(0)
	v_mfma_f32_16x16x32_bf16 v[126:129], v[130:133], v[160:163], v[126:129]
	v_mfma_f32_16x16x32_bf16 v[122:125], v[152:155], v[160:163], v[122:125]
	v_mfma_f32_16x16x32_bf16 v[110:113], v[130:133], v[168:171], v[110:113]
	v_mfma_f32_16x16x32_bf16 v[106:109], v[152:155], v[168:171], v[106:109]
	v_mfma_f32_16x16x32_bf16 v[94:97], v[130:133], v[176:179], v[94:97]
	v_mfma_f32_16x16x32_bf16 v[90:93], v[152:155], v[176:179], v[90:93]
	v_mfma_f32_16x16x32_bf16 v[78:81], v[130:133], v[184:187], v[78:81]
	v_mfma_f32_16x16x32_bf16 v[74:77], v[152:155], v[184:187], v[74:77]
	v_mfma_f32_16x16x32_bf16 v[126:129], v[148:151], v[164:167], v[126:129]
	v_mfma_f32_16x16x32_bf16 v[122:125], v[156:159], v[164:167], v[122:125]
	v_mfma_f32_16x16x32_bf16 v[110:113], v[148:151], v[172:175], v[110:113]
	v_mfma_f32_16x16x32_bf16 v[106:109], v[156:159], v[172:175], v[106:109]
	v_mfma_f32_16x16x32_bf16 v[94:97], v[148:151], v[180:183], v[94:97]
	v_mfma_f32_16x16x32_bf16 v[90:93], v[156:159], v[180:183], v[90:93]
	v_mfma_f32_16x16x32_bf16 v[78:81], v[148:151], v[188:191], v[78:81]
	v_mfma_f32_16x16x32_bf16 v[74:77], v[156:159], v[188:191], v[74:77]
	s_barrier
	s_setprio 0
	s_add_i32 s4, 0, 0x14000
	s_add_i32 s5, s11, s53
	v_add_u32_e32 v138, s4, v141
	v_lshl_add_u64 v[144:145], s[92:93], 0, v[0:1]
	s_mov_b32 m0, s5
	ds_read_b128 v[192:195], v138
	ds_read_b128 v[196:199], v138 offset:1024
	ds_read_b128 v[200:203], v138 offset:2048
	ds_read_b128 v[204:207], v138 offset:3072
	global_load_lds_dwordx4 v[144:145], off
	v_lshl_add_u64 v[208:209], v[144:145], 0, s[60:61]
	s_add_i32 m0, s5, 0x2000
	s_nop 0
	global_load_lds_dwordx4 v[208:209], off
	s_setprio 1
	s_barrier
	s_waitcnt lgkmcnt(0)
	v_mfma_f32_16x16x32_bf16 v[118:121], v[192:195], v[160:163], v[118:121]
	v_mfma_f32_16x16x32_bf16 v[114:117], v[200:203], v[160:163], v[114:117]
	v_mfma_f32_16x16x32_bf16 v[102:105], v[192:195], v[168:171], v[102:105]
	v_mfma_f32_16x16x32_bf16 v[98:101], v[200:203], v[168:171], v[98:101]
	v_mfma_f32_16x16x32_bf16 v[86:89], v[192:195], v[176:179], v[86:89]
	v_mfma_f32_16x16x32_bf16 v[82:85], v[200:203], v[176:179], v[82:85]
	v_mfma_f32_16x16x32_bf16 v[70:73], v[192:195], v[184:187], v[70:73]
	v_mfma_f32_16x16x32_bf16 v[66:69], v[200:203], v[184:187], v[66:69]
	v_mfma_f32_16x16x32_bf16 v[118:121], v[196:199], v[164:167], v[118:121]
	v_mfma_f32_16x16x32_bf16 v[114:117], v[204:207], v[164:167], v[114:117]
	v_mfma_f32_16x16x32_bf16 v[102:105], v[196:199], v[172:175], v[102:105]
	v_mfma_f32_16x16x32_bf16 v[98:101], v[204:207], v[172:175], v[98:101]
	v_mfma_f32_16x16x32_bf16 v[86:89], v[196:199], v[180:183], v[86:89]
	v_mfma_f32_16x16x32_bf16 v[82:85], v[204:207], v[180:183], v[82:85]
	v_mfma_f32_16x16x32_bf16 v[70:73], v[196:199], v[188:191], v[70:73]
	v_mfma_f32_16x16x32_bf16 v[66:69], v[204:207], v[188:191], v[66:69]
	s_barrier
	s_setprio 0
	s_mov_b32 m0, s54
	v_lshl_add_u64 v[208:209], s[40:41], 0, v[134:135]
	ds_read_b128 v[160:163], v142 offset:16384
	ds_read_b128 v[164:167], v142 offset:17408
	ds_read_b128 v[168:171], v142 offset:18432
	ds_read_b128 v[172:175], v142 offset:19456
	ds_read_b128 v[176:179], v142 offset:20480
	ds_read_b128 v[180:183], v142 offset:21504
	ds_read_b128 v[184:187], v142 offset:22528
	ds_read_b128 v[188:191], v142 offset:23552
	global_load_lds_dwordx4 v[208:209], off
	v_lshl_add_u64 v[210:211], v[208:209], 0, s[60:61]
	s_mov_b32 m0, s55
	s_nop 0
	global_load_lds_dwordx4 v[210:211], off
	s_setprio 1
	s_barrier
	s_waitcnt lgkmcnt(0)
	v_mfma_f32_16x16x32_bf16 v[62:65], v[130:133], v[160:163], v[62:65]
	v_mfma_f32_16x16x32_bf16 v[58:61], v[152:155], v[160:163], v[58:61]
	v_mfma_f32_16x16x32_bf16 v[46:49], v[130:133], v[168:171], v[46:49]
	v_mfma_f32_16x16x32_bf16 v[42:45], v[152:155], v[168:171], v[42:45]
	v_mfma_f32_16x16x32_bf16 v[30:33], v[130:133], v[176:179], v[30:33]
	v_mfma_f32_16x16x32_bf16 v[26:29], v[152:155], v[176:179], v[26:29]
	v_mfma_f32_16x16x32_bf16 v[14:17], v[130:133], v[184:187], v[14:17]
	v_mfma_f32_16x16x32_bf16 v[10:13], v[152:155], v[184:187], v[10:13]
	v_mfma_f32_16x16x32_bf16 v[62:65], v[148:151], v[164:167], v[62:65]
	v_mfma_f32_16x16x32_bf16 v[58:61], v[156:159], v[164:167], v[58:61]
	v_mfma_f32_16x16x32_bf16 v[46:49], v[148:151], v[172:175], v[46:49]
	v_mfma_f32_16x16x32_bf16 v[42:45], v[156:159], v[172:175], v[42:45]
	v_mfma_f32_16x16x32_bf16 v[30:33], v[148:151], v[180:183], v[30:33]
	v_mfma_f32_16x16x32_bf16 v[26:29], v[156:159], v[180:183], v[26:29]
	v_mfma_f32_16x16x32_bf16 v[14:17], v[148:151], v[188:191], v[14:17]
	v_mfma_f32_16x16x32_bf16 v[10:13], v[156:159], v[188:191], v[10:13]
	s_barrier
	s_setprio 0
	s_add_i32 s4, s4, s53
	v_lshl_add_u64 v[130:131], v[144:145], 0, s[20:21]
	s_mov_b32 m0, s4
	s_nop 0
	global_load_lds_dwordx4 v[130:131], off
	v_lshl_add_u64 v[130:131], v[144:145], 0, s[64:65]
	s_add_i32 m0, s4, 0x2000
	s_nop 0
	global_load_lds_dwordx4 v[130:131], off
	v_lshl_add_u64 v[230:231], v[208:209], 0, s[20:21]
	s_mov_b32 m0, s56
	s_nop 0
	global_load_lds_dwordx4 v[230:231], off
	v_lshl_add_u64 v[230:231], v[208:209], 0, s[64:65]
	s_mov_b32 m0, s57
	s_nop 0
	global_load_lds_dwordx4 v[230:231], off
	s_waitcnt vmcnt(8)
	s_setprio 1
	s_barrier
	v_mfma_f32_16x16x32_bf16 v[54:57], v[192:195], v[160:163], v[54:57]
	v_mfma_f32_16x16x32_bf16 v[50:53], v[200:203], v[160:163], v[50:53]
	v_mfma_f32_16x16x32_bf16 v[38:41], v[192:195], v[168:171], v[38:41]
	v_mfma_f32_16x16x32_bf16 v[34:37], v[200:203], v[168:171], v[34:37]
	v_mfma_f32_16x16x32_bf16 v[22:25], v[192:195], v[176:179], v[22:25]
	v_mfma_f32_16x16x32_bf16 v[18:21], v[200:203], v[176:179], v[18:21]
	v_mfma_f32_16x16x32_bf16 v[6:9], v[192:195], v[184:187], v[6:9]
	v_mfma_f32_16x16x32_bf16 v[2:5], v[200:203], v[184:187], v[2:5]
	v_mfma_f32_16x16x32_bf16 v[54:57], v[196:199], v[164:167], v[54:57]
	v_mfma_f32_16x16x32_bf16 v[50:53], v[204:207], v[164:167], v[50:53]
	v_mfma_f32_16x16x32_bf16 v[38:41], v[196:199], v[172:175], v[38:41]
	v_mfma_f32_16x16x32_bf16 v[34:37], v[204:207], v[172:175], v[34:37]
	v_mfma_f32_16x16x32_bf16 v[22:25], v[196:199], v[180:183], v[22:25]
	v_mfma_f32_16x16x32_bf16 v[18:21], v[204:207], v[180:183], v[18:21]
	v_mfma_f32_16x16x32_bf16 v[6:9], v[196:199], v[188:191], v[6:9]
	v_mfma_f32_16x16x32_bf16 v[2:5], v[204:207], v[188:191], v[2:5]
	s_barrier
	s_setprio 0
	s_add_i32 s4, 0, 0x18000
	v_add_u32_e32 v138, s4, v141
	ds_read_b128 v[130:133], v138
	ds_read_b128 v[148:151], v138 offset:1024
	ds_read_b128 v[152:155], v138 offset:2048
	ds_read_b128 v[156:159], v138 offset:3072
	ds_read_b128 v[160:163], v142 offset:32768
	ds_read_b128 v[164:167], v142 offset:33792
	ds_read_b128 v[168:171], v142 offset:34816
	ds_read_b128 v[172:175], v142 offset:35840
	ds_read_b128 v[176:179], v142 offset:36864
	ds_read_b128 v[180:183], v142 offset:37888
	ds_read_b128 v[184:187], v142 offset:38912
	ds_read_b128 v[188:191], v142 offset:39936
	s_waitcnt lgkmcnt(8)
	s_setprio 1
	s_barrier
	s_waitcnt lgkmcnt(0)
	v_mfma_f32_16x16x32_bf16 v[126:129], v[130:133], v[160:163], v[126:129]
	v_mfma_f32_16x16x32_bf16 v[122:125], v[152:155], v[160:163], v[122:125]
	v_mfma_f32_16x16x32_bf16 v[110:113], v[130:133], v[168:171], v[110:113]
	v_mfma_f32_16x16x32_bf16 v[106:109], v[152:155], v[168:171], v[106:109]
	v_mfma_f32_16x16x32_bf16 v[94:97], v[130:133], v[176:179], v[94:97]
	v_mfma_f32_16x16x32_bf16 v[90:93], v[152:155], v[176:179], v[90:93]
	v_mfma_f32_16x16x32_bf16 v[78:81], v[130:133], v[184:187], v[78:81]
	v_mfma_f32_16x16x32_bf16 v[74:77], v[152:155], v[184:187], v[74:77]
	v_mfma_f32_16x16x32_bf16 v[126:129], v[148:151], v[164:167], v[126:129]
	v_mfma_f32_16x16x32_bf16 v[122:125], v[156:159], v[164:167], v[122:125]
	v_mfma_f32_16x16x32_bf16 v[110:113], v[148:151], v[172:175], v[110:113]
	v_mfma_f32_16x16x32_bf16 v[106:109], v[156:159], v[172:175], v[106:109]
	v_mfma_f32_16x16x32_bf16 v[94:97], v[148:151], v[180:183], v[94:97]
	v_mfma_f32_16x16x32_bf16 v[90:93], v[156:159], v[180:183], v[90:93]
	v_mfma_f32_16x16x32_bf16 v[78:81], v[148:151], v[188:191], v[78:81]
	v_mfma_f32_16x16x32_bf16 v[74:77], v[156:159], v[188:191], v[74:77]
	s_barrier
	s_setprio 0
	s_add_i32 s5, 0, 0x1c000
	s_add_i32 s4, s4, s53
	v_add_u32_e32 v138, s5, v141
	v_lshl_add_u64 v[210:211], v[144:145], 0, s[34:35]
	s_mov_b32 m0, s4
	ds_read_b128 v[192:195], v138
	ds_read_b128 v[196:199], v138 offset:1024
	ds_read_b128 v[200:203], v138 offset:2048
	ds_read_b128 v[204:207], v138 offset:3072
	global_load_lds_dwordx4 v[210:211], off
	v_lshl_add_u64 v[210:211], v[144:145], 0, s[66:67]
	s_add_i32 m0, s4, 0x2000
	s_nop 0
	global_load_lds_dwordx4 v[210:211], off
	s_setprio 1
	s_barrier
	s_waitcnt lgkmcnt(0)
	v_mfma_f32_16x16x32_bf16 v[118:121], v[192:195], v[160:163], v[118:121]
	v_mfma_f32_16x16x32_bf16 v[114:117], v[200:203], v[160:163], v[114:117]
	v_mfma_f32_16x16x32_bf16 v[102:105], v[192:195], v[168:171], v[102:105]
	v_mfma_f32_16x16x32_bf16 v[98:101], v[200:203], v[168:171], v[98:101]
	v_mfma_f32_16x16x32_bf16 v[86:89], v[192:195], v[176:179], v[86:89]
	v_mfma_f32_16x16x32_bf16 v[82:85], v[200:203], v[176:179], v[82:85]
	v_mfma_f32_16x16x32_bf16 v[70:73], v[192:195], v[184:187], v[70:73]
	v_mfma_f32_16x16x32_bf16 v[66:69], v[200:203], v[184:187], v[66:69]
	v_mfma_f32_16x16x32_bf16 v[118:121], v[196:199], v[164:167], v[118:121]
	v_mfma_f32_16x16x32_bf16 v[114:117], v[204:207], v[164:167], v[114:117]
	v_mfma_f32_16x16x32_bf16 v[102:105], v[196:199], v[172:175], v[102:105]
	v_mfma_f32_16x16x32_bf16 v[98:101], v[204:207], v[172:175], v[98:101]
	v_mfma_f32_16x16x32_bf16 v[86:89], v[196:199], v[180:183], v[86:89]
	v_mfma_f32_16x16x32_bf16 v[82:85], v[204:207], v[180:183], v[82:85]
	v_mfma_f32_16x16x32_bf16 v[70:73], v[196:199], v[188:191], v[70:73]
	v_mfma_f32_16x16x32_bf16 v[66:69], v[204:207], v[188:191], v[66:69]
	s_barrier
	s_setprio 0
	s_mov_b32 m0, s62
	v_lshl_add_u64 v[210:211], v[208:209], 0, s[34:35]
	ds_read_b128 v[160:163], v142 offset:49152
	ds_read_b128 v[164:167], v142 offset:50176
	ds_read_b128 v[168:171], v142 offset:51200
	ds_read_b128 v[172:175], v142 offset:52224
	ds_read_b128 v[176:179], v142 offset:53248
	ds_read_b128 v[180:183], v142 offset:54272
	ds_read_b128 v[184:187], v142 offset:55296
	ds_read_b128 v[188:191], v142 offset:56320
	global_load_lds_dwordx4 v[210:211], off
	v_lshl_add_u64 v[208:209], v[208:209], 0, s[66:67]
	s_mov_b32 m0, s63
	s_nop 0
	global_load_lds_dwordx4 v[208:209], off
	s_setprio 1
	s_barrier
	s_waitcnt lgkmcnt(0)
	v_mfma_f32_16x16x32_bf16 v[62:65], v[130:133], v[160:163], v[62:65]
	v_mfma_f32_16x16x32_bf16 v[58:61], v[152:155], v[160:163], v[58:61]
	v_mfma_f32_16x16x32_bf16 v[46:49], v[130:133], v[168:171], v[46:49]
	v_mfma_f32_16x16x32_bf16 v[42:45], v[152:155], v[168:171], v[42:45]
	v_mfma_f32_16x16x32_bf16 v[30:33], v[130:133], v[176:179], v[30:33]
	v_mfma_f32_16x16x32_bf16 v[26:29], v[152:155], v[176:179], v[26:29]
	v_mfma_f32_16x16x32_bf16 v[14:17], v[130:133], v[184:187], v[14:17]
	v_mfma_f32_16x16x32_bf16 v[10:13], v[152:155], v[184:187], v[10:13]
	v_mfma_f32_16x16x32_bf16 v[62:65], v[148:151], v[164:167], v[62:65]
	v_mfma_f32_16x16x32_bf16 v[58:61], v[156:159], v[164:167], v[58:61]
	v_mfma_f32_16x16x32_bf16 v[46:49], v[148:151], v[172:175], v[46:49]
	v_mfma_f32_16x16x32_bf16 v[42:45], v[156:159], v[172:175], v[42:45]
	v_mfma_f32_16x16x32_bf16 v[30:33], v[148:151], v[180:183], v[30:33]
	v_mfma_f32_16x16x32_bf16 v[26:29], v[156:159], v[180:183], v[26:29]
	v_mfma_f32_16x16x32_bf16 v[14:17], v[148:151], v[188:191], v[14:17]
	v_mfma_f32_16x16x32_bf16 v[10:13], v[156:159], v[188:191], v[10:13]
	s_barrier
	s_setprio 0
	s_add_i32 s4, s5, s53
	v_lshl_add_u64 v[130:131], v[144:145], 0, s[16:17]
	s_mov_b32 m0, s4
	s_nop 0
	global_load_lds_dwordx4 v[130:131], off
	v_lshl_add_u64 v[130:131], v[144:145], 0, s[80:81]
	s_add_i32 m0, s4, 0x2000
	s_nop 0
	global_load_lds_dwordx4 v[130:131], off
	s_waitcnt vmcnt(6)
	s_add_i32 s10, s10, 2
	s_add_u32 s8, s8, 0x100
	s_addc_u32 s9, s9, 0
	s_cmp_gt_u32 s10, 29
	s_mov_b64 s[4:5], s[6:7]
	s_cbranch_scc0 .LBB0_292
	s_setprio 1
	s_barrier
	v_mfma_f32_16x16x32_bf16 v[54:57], v[192:195], v[160:163], v[54:57]
	v_mfma_f32_16x16x32_bf16 v[50:53], v[200:203], v[160:163], v[50:53]
	v_mfma_f32_16x16x32_bf16 v[38:41], v[192:195], v[168:171], v[38:41]
	v_mfma_f32_16x16x32_bf16 v[34:37], v[200:203], v[168:171], v[34:37]
	v_mfma_f32_16x16x32_bf16 v[22:25], v[192:195], v[176:179], v[22:25]
	v_mfma_f32_16x16x32_bf16 v[18:21], v[200:203], v[176:179], v[18:21]
	v_mfma_f32_16x16x32_bf16 v[6:9], v[192:195], v[184:187], v[6:9]
	v_mfma_f32_16x16x32_bf16 v[2:5], v[200:203], v[184:187], v[2:5]
	v_mfma_f32_16x16x32_bf16 v[54:57], v[196:199], v[164:167], v[54:57]
	v_mfma_f32_16x16x32_bf16 v[50:53], v[204:207], v[164:167], v[50:53]
	v_mfma_f32_16x16x32_bf16 v[38:41], v[196:199], v[172:175], v[38:41]
	v_mfma_f32_16x16x32_bf16 v[34:37], v[204:207], v[172:175], v[34:37]
	v_mfma_f32_16x16x32_bf16 v[22:25], v[196:199], v[180:183], v[22:25]
	v_mfma_f32_16x16x32_bf16 v[18:21], v[204:207], v[180:183], v[18:21]
	v_mfma_f32_16x16x32_bf16 v[6:9], v[196:199], v[188:191], v[6:9]
	v_mfma_f32_16x16x32_bf16 v[2:5], v[204:207], v[188:191], v[2:5]
	s_barrier
	s_setprio 0
	s_cmp_eq_u32 s52, 3
	v_mov_b32_e32 v144, v139
	s_cselect_b64 s[4:5], -1, 0
	s_cmp_lt_i32 s52, 5
	s_cbranch_scc1 .LBB0_295
	s_cmp_eq_u32 s52, 5
	s_cselect_b64 s[6:7], -1, 0
	s_movk_i32 s93, 0xf800
	s_cbranch_execz .LBB0_296
	s_branch .LBB0_297

.Lrot_enter_6:
	s_add_u32 s7, s46, 0xffea0080
	s_addc_u32 s78, s47, -1
	s_add_i32 s79, 0, 0x10000
	v_add_u32_e32 v132, s79, v135
	ds_read_b128 v[138:141], v132
	ds_read_b128 v[142:145], v132 offset:1024
	ds_read_b128 v[148:151], v132 offset:2048
	ds_read_b128 v[152:155], v132 offset:3072
	s_cmpk_eq_i32 s6, 0x54
	s_cselect_b32 s89, s43, s78
	s_cselect_b32 s88, s42, s7
	s_cselect_b32 s91, s45, s9
	s_cselect_b32 s90, s44, s8
	v_lshl_add_u64 v[132:133], s[46:47], 0, v[130:131]
	s_add_i32 m0, s54, 0xc000
	ds_read_b128 v[156:159], v136
	ds_read_b128 v[160:163], v136 offset:1024
	ds_read_b128 v[164:167], v136 offset:2048
	ds_read_b128 v[168:171], v136 offset:3072
	ds_read_b128 v[172:175], v136 offset:4096
	ds_read_b128 v[176:179], v136 offset:5120
	ds_read_b128 v[180:183], v136 offset:6144
	ds_read_b128 v[184:187], v136 offset:7168
	global_load_lds_dwordx4 v[132:133], off
	v_lshl_add_u64 v[132:133], v[132:133], 0, s[26:27]
	s_add_i32 m0, s54, 0xe000
	s_nop 0
	global_load_lds_dwordx4 v[132:133], off
	s_waitcnt lgkmcnt(8)
	s_setprio 1
	s_barrier
	s_waitcnt lgkmcnt(0)
	v_mfma_f32_16x16x32_bf16 v[126:129], v[138:141], v[156:159], v[126:129]
	v_mfma_f32_16x16x32_bf16 v[122:125], v[148:151], v[156:159], v[122:125]
	v_mfma_f32_16x16x32_bf16 v[118:121], v[138:141], v[164:167], v[118:121]
	v_mfma_f32_16x16x32_bf16 v[110:113], v[148:151], v[164:167], v[110:113]
	v_mfma_f32_16x16x32_bf16 v[102:105], v[138:141], v[172:175], v[102:105]
	v_mfma_f32_16x16x32_bf16 v[94:97], v[148:151], v[172:175], v[94:97]
	v_mfma_f32_16x16x32_bf16 v[86:89], v[138:141], v[180:183], v[86:89]
	v_mfma_f32_16x16x32_bf16 v[78:81], v[148:151], v[180:183], v[78:81]
	v_mfma_f32_16x16x32_bf16 v[126:129], v[142:145], v[160:163], v[126:129]
	v_mfma_f32_16x16x32_bf16 v[122:125], v[152:155], v[160:163], v[122:125]
	v_mfma_f32_16x16x32_bf16 v[118:121], v[142:145], v[168:171], v[118:121]
	v_mfma_f32_16x16x32_bf16 v[110:113], v[152:155], v[168:171], v[110:113]
	v_mfma_f32_16x16x32_bf16 v[102:105], v[142:145], v[176:179], v[102:105]
	v_mfma_f32_16x16x32_bf16 v[94:97], v[152:155], v[176:179], v[94:97]
	v_mfma_f32_16x16x32_bf16 v[86:89], v[142:145], v[184:187], v[86:89]
	v_mfma_f32_16x16x32_bf16 v[78:81], v[152:155], v[184:187], v[78:81]
	s_barrier
	s_setprio 0
	s_add_i32 s7, 0, 0x14000
	v_add_u32_e32 v132, s7, v135
	s_add_i32 s78, s79, s53
	ds_read_b128 v[188:191], v132
	ds_read_b128 v[192:195], v132 offset:1024
	ds_read_b128 v[196:199], v132 offset:2048
	ds_read_b128 v[200:203], v132 offset:3072
	v_lshl_add_u64 v[132:133], s[90:91], 0, v[0:1]
	s_mov_b32 m0, s78
	v_lshl_add_u64 v[204:205], v[132:133], 0, s[26:27]
	global_load_lds_dwordx4 v[132:133], off
	s_add_i32 m0, s78, 0x2000
	s_nop 0
	global_load_lds_dwordx4 v[204:205], off
	s_setprio 1
	s_barrier
	s_waitcnt lgkmcnt(0)
	v_mfma_f32_16x16x32_bf16 v[114:117], v[188:191], v[156:159], v[114:117]
	v_mfma_f32_16x16x32_bf16 v[106:109], v[196:199], v[156:159], v[106:109]
	v_mfma_f32_16x16x32_bf16 v[98:101], v[188:191], v[164:167], v[98:101]
	v_mfma_f32_16x16x32_bf16 v[90:93], v[196:199], v[164:167], v[90:93]
	v_mfma_f32_16x16x32_bf16 v[82:85], v[188:191], v[172:175], v[82:85]
	v_mfma_f32_16x16x32_bf16 v[74:77], v[196:199], v[172:175], v[74:77]
	v_mfma_f32_16x16x32_bf16 v[70:73], v[188:191], v[180:183], v[70:73]
	v_mfma_f32_16x16x32_bf16 v[66:69], v[196:199], v[180:183], v[66:69]
	v_mfma_f32_16x16x32_bf16 v[114:117], v[192:195], v[160:163], v[114:117]
	v_mfma_f32_16x16x32_bf16 v[106:109], v[200:203], v[160:163], v[106:109]
	v_mfma_f32_16x16x32_bf16 v[98:101], v[192:195], v[168:171], v[98:101]
	v_mfma_f32_16x16x32_bf16 v[90:93], v[200:203], v[168:171], v[90:93]
	v_mfma_f32_16x16x32_bf16 v[82:85], v[192:195], v[176:179], v[82:85]
	v_mfma_f32_16x16x32_bf16 v[74:77], v[200:203], v[176:179], v[74:77]
	v_mfma_f32_16x16x32_bf16 v[70:73], v[192:195], v[184:187], v[70:73]
	v_mfma_f32_16x16x32_bf16 v[66:69], v[200:203], v[184:187], v[66:69]
	s_barrier
	s_setprio 0
	s_mov_b32 m0, s54
	v_lshl_add_u64 v[204:205], s[88:89], 0, v[0:1]
	ds_read_b128 v[156:159], v136 offset:16384
	ds_read_b128 v[160:163], v136 offset:17408
	ds_read_b128 v[164:167], v136 offset:18432
	ds_read_b128 v[168:171], v136 offset:19456
	ds_read_b128 v[172:175], v136 offset:20480
	ds_read_b128 v[176:179], v136 offset:21504
	ds_read_b128 v[180:183], v136 offset:22528
	ds_read_b128 v[184:187], v136 offset:23552
	global_load_lds_dwordx4 v[204:205], off
	v_lshl_add_u64 v[206:207], v[204:205], 0, s[26:27]
	s_mov_b32 m0, s55
	s_nop 0
	global_load_lds_dwordx4 v[206:207], off
	s_setprio 1
	s_barrier
	s_waitcnt lgkmcnt(0)
	v_mfma_f32_16x16x32_bf16 v[62:65], v[138:141], v[156:159], v[62:65]
	v_mfma_f32_16x16x32_bf16 v[58:61], v[148:151], v[156:159], v[58:61]
	v_mfma_f32_16x16x32_bf16 v[54:57], v[138:141], v[164:167], v[54:57]
	v_mfma_f32_16x16x32_bf16 v[46:49], v[148:151], v[164:167], v[46:49]
	v_mfma_f32_16x16x32_bf16 v[38:41], v[138:141], v[172:175], v[38:41]
	v_mfma_f32_16x16x32_bf16 v[30:33], v[148:151], v[172:175], v[30:33]
	v_mfma_f32_16x16x32_bf16 v[22:25], v[138:141], v[180:183], v[22:25]
	v_mfma_f32_16x16x32_bf16 v[14:17], v[148:151], v[180:183], v[14:17]
	v_mfma_f32_16x16x32_bf16 v[62:65], v[142:145], v[160:163], v[62:65]
	v_mfma_f32_16x16x32_bf16 v[58:61], v[152:155], v[160:163], v[58:61]
	v_mfma_f32_16x16x32_bf16 v[54:57], v[142:145], v[168:171], v[54:57]
	v_mfma_f32_16x16x32_bf16 v[46:49], v[152:155], v[168:171], v[46:49]
	v_mfma_f32_16x16x32_bf16 v[38:41], v[142:145], v[176:179], v[38:41]
	v_mfma_f32_16x16x32_bf16 v[30:33], v[152:155], v[176:179], v[30:33]
	v_mfma_f32_16x16x32_bf16 v[22:25], v[142:145], v[184:187], v[22:25]
	v_mfma_f32_16x16x32_bf16 v[14:17], v[152:155], v[184:187], v[14:17]
	s_barrier
	s_setprio 0
	s_add_i32 s7, s7, s53
	v_lshl_add_u64 v[138:139], v[132:133], 0, s[28:29]
	s_mov_b32 m0, s7
	s_nop 0
	global_load_lds_dwordx4 v[138:139], off
	v_lshl_add_u64 v[138:139], v[132:133], 0, s[30:31]
	s_add_i32 m0, s7, 0x2000
	s_nop 0
	global_load_lds_dwordx4 v[138:139], off
	v_lshl_add_u64 v[230:231], v[204:205], 0, s[28:29]
	s_mov_b32 m0, s56
	s_nop 0
	global_load_lds_dwordx4 v[230:231], off
	v_lshl_add_u64 v[230:231], v[204:205], 0, s[30:31]
	s_mov_b32 m0, s57
	s_nop 0
	global_load_lds_dwordx4 v[230:231], off
	s_waitcnt vmcnt(8)
	s_setprio 1
	s_barrier
	v_mfma_f32_16x16x32_bf16 v[50:53], v[188:191], v[156:159], v[50:53]
	v_mfma_f32_16x16x32_bf16 v[42:45], v[196:199], v[156:159], v[42:45]
	v_mfma_f32_16x16x32_bf16 v[34:37], v[188:191], v[164:167], v[34:37]
	v_mfma_f32_16x16x32_bf16 v[26:29], v[196:199], v[164:167], v[26:29]
	v_mfma_f32_16x16x32_bf16 v[18:21], v[188:191], v[172:175], v[18:21]
	v_mfma_f32_16x16x32_bf16 v[10:13], v[196:199], v[172:175], v[10:13]
	v_mfma_f32_16x16x32_bf16 v[6:9], v[188:191], v[180:183], v[6:9]
	v_mfma_f32_16x16x32_bf16 v[2:5], v[196:199], v[180:183], v[2:5]
	v_mfma_f32_16x16x32_bf16 v[50:53], v[192:195], v[160:163], v[50:53]
	v_mfma_f32_16x16x32_bf16 v[42:45], v[200:203], v[160:163], v[42:45]
	v_mfma_f32_16x16x32_bf16 v[34:37], v[192:195], v[168:171], v[34:37]
	v_mfma_f32_16x16x32_bf16 v[26:29], v[200:203], v[168:171], v[26:29]
	v_mfma_f32_16x16x32_bf16 v[18:21], v[192:195], v[176:179], v[18:21]
	v_mfma_f32_16x16x32_bf16 v[10:13], v[200:203], v[176:179], v[10:13]
	v_mfma_f32_16x16x32_bf16 v[6:9], v[192:195], v[184:187], v[6:9]
	v_mfma_f32_16x16x32_bf16 v[2:5], v[200:203], v[184:187], v[2:5]
	s_barrier
	s_setprio 0
	s_add_i32 s7, 0, 0x18000
	v_add_u32_e32 v137, s7, v135
	ds_read_b128 v[138:141], v137
	ds_read_b128 v[142:145], v137 offset:1024
	ds_read_b128 v[148:151], v137 offset:2048
	ds_read_b128 v[152:155], v137 offset:3072
	ds_read_b128 v[156:159], v136 offset:32768
	ds_read_b128 v[160:163], v136 offset:33792
	ds_read_b128 v[164:167], v136 offset:34816
	ds_read_b128 v[168:171], v136 offset:35840
	ds_read_b128 v[172:175], v136 offset:36864
	ds_read_b128 v[176:179], v136 offset:37888
	ds_read_b128 v[180:183], v136 offset:38912
	ds_read_b128 v[184:187], v136 offset:39936
	s_waitcnt lgkmcnt(8)
	s_setprio 1
	s_barrier
	s_waitcnt lgkmcnt(0)
	v_mfma_f32_16x16x32_bf16 v[126:129], v[138:141], v[156:159], v[126:129]
	v_mfma_f32_16x16x32_bf16 v[122:125], v[148:151], v[156:159], v[122:125]
	v_mfma_f32_16x16x32_bf16 v[118:121], v[138:141], v[164:167], v[118:121]
	v_mfma_f32_16x16x32_bf16 v[110:113], v[148:151], v[164:167], v[110:113]
	v_mfma_f32_16x16x32_bf16 v[102:105], v[138:141], v[172:175], v[102:105]
	v_mfma_f32_16x16x32_bf16 v[94:97], v[148:151], v[172:175], v[94:97]
	v_mfma_f32_16x16x32_bf16 v[86:89], v[138:141], v[180:183], v[86:89]
	v_mfma_f32_16x16x32_bf16 v[78:81], v[148:151], v[180:183], v[78:81]
	v_mfma_f32_16x16x32_bf16 v[126:129], v[142:145], v[160:163], v[126:129]
	v_mfma_f32_16x16x32_bf16 v[122:125], v[152:155], v[160:163], v[122:125]
	v_mfma_f32_16x16x32_bf16 v[118:121], v[142:145], v[168:171], v[118:121]
	v_mfma_f32_16x16x32_bf16 v[110:113], v[152:155], v[168:171], v[110:113]
	v_mfma_f32_16x16x32_bf16 v[102:105], v[142:145], v[176:179], v[102:105]
	v_mfma_f32_16x16x32_bf16 v[94:97], v[152:155], v[176:179], v[94:97]
	v_mfma_f32_16x16x32_bf16 v[86:89], v[142:145], v[184:187], v[86:89]
	v_mfma_f32_16x16x32_bf16 v[78:81], v[152:155], v[184:187], v[78:81]
	s_barrier
	s_setprio 0
	s_add_i32 s78, 0, 0x1c000
	s_add_i32 s7, s7, s53
	v_add_u32_e32 v137, s78, v135
	v_lshl_add_u64 v[206:207], v[132:133], 0, s[34:35]
	s_mov_b32 m0, s7
	ds_read_b128 v[188:191], v137
	ds_read_b128 v[192:195], v137 offset:1024
	ds_read_b128 v[196:199], v137 offset:2048
	ds_read_b128 v[200:203], v137 offset:3072
	global_load_lds_dwordx4 v[206:207], off
	v_lshl_add_u64 v[206:207], v[132:133], 0, s[36:37]
	s_add_i32 m0, s7, 0x2000
	s_nop 0
	global_load_lds_dwordx4 v[206:207], off
	s_setprio 1
	s_barrier
	s_waitcnt lgkmcnt(0)
	v_mfma_f32_16x16x32_bf16 v[114:117], v[188:191], v[156:159], v[114:117]
	v_mfma_f32_16x16x32_bf16 v[106:109], v[196:199], v[156:159], v[106:109]
	v_mfma_f32_16x16x32_bf16 v[98:101], v[188:191], v[164:167], v[98:101]
	v_mfma_f32_16x16x32_bf16 v[90:93], v[196:199], v[164:167], v[90:93]
	v_mfma_f32_16x16x32_bf16 v[82:85], v[188:191], v[172:175], v[82:85]
	v_mfma_f32_16x16x32_bf16 v[74:77], v[196:199], v[172:175], v[74:77]
	v_mfma_f32_16x16x32_bf16 v[70:73], v[188:191], v[180:183], v[70:73]
	v_mfma_f32_16x16x32_bf16 v[66:69], v[196:199], v[180:183], v[66:69]
	v_mfma_f32_16x16x32_bf16 v[114:117], v[192:195], v[160:163], v[114:117]
	v_mfma_f32_16x16x32_bf16 v[106:109], v[200:203], v[160:163], v[106:109]
	v_mfma_f32_16x16x32_bf16 v[98:101], v[192:195], v[168:171], v[98:101]
	v_mfma_f32_16x16x32_bf16 v[90:93], v[200:203], v[168:171], v[90:93]
	v_mfma_f32_16x16x32_bf16 v[82:85], v[192:195], v[176:179], v[82:85]
	v_mfma_f32_16x16x32_bf16 v[74:77], v[200:203], v[176:179], v[74:77]
	v_mfma_f32_16x16x32_bf16 v[70:73], v[192:195], v[184:187], v[70:73]
	v_mfma_f32_16x16x32_bf16 v[66:69], v[200:203], v[184:187], v[66:69]
	s_barrier
	s_setprio 0
	s_mov_b32 m0, s62
	v_lshl_add_u64 v[206:207], v[204:205], 0, s[34:35]
	ds_read_b128 v[156:159], v136 offset:49152
	ds_read_b128 v[160:163], v136 offset:50176
	ds_read_b128 v[164:167], v136 offset:51200
	ds_read_b128 v[168:171], v136 offset:52224
	ds_read_b128 v[172:175], v136 offset:53248
	ds_read_b128 v[176:179], v136 offset:54272
	ds_read_b128 v[180:183], v136 offset:55296
	ds_read_b128 v[184:187], v136 offset:56320
	global_load_lds_dwordx4 v[206:207], off
	v_lshl_add_u64 v[204:205], v[204:205], 0, s[36:37]
	s_mov_b32 m0, s63
	s_nop 0
	global_load_lds_dwordx4 v[204:205], off
	s_setprio 1
	s_barrier
	s_waitcnt lgkmcnt(0)
	v_mfma_f32_16x16x32_bf16 v[62:65], v[138:141], v[156:159], v[62:65]
	v_mfma_f32_16x16x32_bf16 v[58:61], v[148:151], v[156:159], v[58:61]
	v_mfma_f32_16x16x32_bf16 v[54:57], v[138:141], v[164:167], v[54:57]
	v_mfma_f32_16x16x32_bf16 v[46:49], v[148:151], v[164:167], v[46:49]
	v_mfma_f32_16x16x32_bf16 v[38:41], v[138:141], v[172:175], v[38:41]
	v_mfma_f32_16x16x32_bf16 v[30:33], v[148:151], v[172:175], v[30:33]
	v_mfma_f32_16x16x32_bf16 v[22:25], v[138:141], v[180:183], v[22:25]
	v_mfma_f32_16x16x32_bf16 v[14:17], v[148:151], v[180:183], v[14:17]
	v_mfma_f32_16x16x32_bf16 v[62:65], v[142:145], v[160:163], v[62:65]
	v_mfma_f32_16x16x32_bf16 v[58:61], v[152:155], v[160:163], v[58:61]
	v_mfma_f32_16x16x32_bf16 v[54:57], v[142:145], v[168:171], v[54:57]
	v_mfma_f32_16x16x32_bf16 v[46:49], v[152:155], v[168:171], v[46:49]
	v_mfma_f32_16x16x32_bf16 v[38:41], v[142:145], v[176:179], v[38:41]
	v_mfma_f32_16x16x32_bf16 v[30:33], v[152:155], v[176:179], v[30:33]
	v_mfma_f32_16x16x32_bf16 v[22:25], v[142:145], v[184:187], v[22:25]
	v_mfma_f32_16x16x32_bf16 v[14:17], v[152:155], v[184:187], v[14:17]
	s_barrier
	s_setprio 0
	s_add_i32 s7, s78, s53
	v_lshl_add_u64 v[138:139], v[132:133], 0, s[18:19]
	s_mov_b32 m0, s7
	v_lshl_add_u64 v[132:133], v[132:133], 0, s[14:15]
	global_load_lds_dwordx4 v[138:139], off
	s_add_i32 m0, s7, 0x2000
	s_nop 0
	global_load_lds_dwordx4 v[132:133], off
	s_waitcnt vmcnt(6)
	s_add_i32 s6, s6, 2
	s_add_u32 s8, s8, 0x100
	s_addc_u32 s9, s9, 0
	s_add_u32 s46, s46, 0x100
	s_addc_u32 s47, s47, 0
	s_cmpk_gt_u32 s6, 0x55
	s_cbranch_scc0 .LBB0_485
	s_setprio 1
	s_barrier
	v_mfma_f32_16x16x32_bf16 v[50:53], v[188:191], v[156:159], v[50:53]
	v_mfma_f32_16x16x32_bf16 v[42:45], v[196:199], v[156:159], v[42:45]
	v_mfma_f32_16x16x32_bf16 v[34:37], v[188:191], v[164:167], v[34:37]
	v_mfma_f32_16x16x32_bf16 v[26:29], v[196:199], v[164:167], v[26:29]
	v_mfma_f32_16x16x32_bf16 v[18:21], v[188:191], v[172:175], v[18:21]
	v_mfma_f32_16x16x32_bf16 v[10:13], v[196:199], v[172:175], v[10:13]
	v_mfma_f32_16x16x32_bf16 v[6:9], v[188:191], v[180:183], v[6:9]
	v_mfma_f32_16x16x32_bf16 v[2:5], v[196:199], v[180:183], v[2:5]
	v_mfma_f32_16x16x32_bf16 v[50:53], v[192:195], v[160:163], v[50:53]
	v_mfma_f32_16x16x32_bf16 v[42:45], v[200:203], v[160:163], v[42:45]
	v_mfma_f32_16x16x32_bf16 v[34:37], v[192:195], v[168:171], v[34:37]
	v_mfma_f32_16x16x32_bf16 v[26:29], v[200:203], v[168:171], v[26:29]
	v_mfma_f32_16x16x32_bf16 v[18:21], v[192:195], v[176:179], v[18:21]
	v_mfma_f32_16x16x32_bf16 v[10:13], v[200:203], v[176:179], v[10:13]
	v_mfma_f32_16x16x32_bf16 v[6:9], v[192:195], v[184:187], v[6:9]
	v_mfma_f32_16x16x32_bf16 v[2:5], v[200:203], v[184:187], v[2:5]
	s_barrier
	s_setprio 0
	v_mov_b32_e32 v137, v134
	s_lshl_b32 s6, s86, 8
	v_ashrrev_i32_e32 v132, 2, v137
	s_or_b32 s6, s6, s59
	v_and_b32_e32 v132, -4, v132
	v_add_u32_e32 v132, s6, v132
	s_lshl_b32 s6, s85, 8
	s_add_i32 s6, s6, s58
	v_and_or_b32 v188, v137, 15, s6
	v_ashrrev_i32_e32 v189, 31, v188
	v_ashrrev_i32_e32 v133, 31, v132
	v_lshlrev_b64 v[206:207], 13, v[188:189]
	v_or_b32_e32 v156, 16, v188
	v_or_b32_e32 v172, 32, v188
	v_or_b32_e32 v188, 48, v188
	v_lshlrev_b64 v[132:133], 2, v[132:133]
	v_ashrrev_i32_e32 v157, 31, v156
	v_ashrrev_i32_e32 v173, 31, v172
	v_ashrrev_i32_e32 v189, 31, v188
	v_lshl_add_u64 v[204:205], s[4:5], 0, v[132:133]
	v_lshlrev_b64 v[208:209], 13, v[156:157]
	v_lshlrev_b64 v[210:211], 13, v[172:173]
	v_lshlrev_b64 v[212:213], 13, v[188:189]
	v_lshl_add_u64 v[152:153], v[204:205], 0, v[206:207]
	v_lshl_add_u64 v[168:169], v[204:205], 0, v[208:209]
	v_lshl_add_u64 v[184:185], v[204:205], 0, v[210:211]
	v_lshl_add_u64 v[200:201], v[204:205], 0, v[212:213]
	global_load_dwordx4 v[138:141], v[152:153], off
	global_load_dwordx4 v[142:145], v[152:153], off offset:64
	global_load_dwordx4 v[148:151], v[152:153], off offset:512
	s_nop 0
	global_load_dwordx4 v[152:155], v[152:153], off offset:576
	s_nop 0
	global_load_dwordx4 v[156:159], v[168:169], off
	global_load_dwordx4 v[160:163], v[168:169], off offset:64
	global_load_dwordx4 v[164:167], v[168:169], off offset:512
	s_nop 0
	global_load_dwordx4 v[168:171], v[168:169], off offset:576
	s_nop 0
	global_load_dwordx4 v[172:175], v[184:185], off
	global_load_dwordx4 v[176:179], v[184:185], off offset:64
	global_load_dwordx4 v[180:183], v[184:185], off offset:512
	s_nop 0
	global_load_dwordx4 v[184:187], v[184:185], off offset:576
	s_nop 0
	global_load_dwordx4 v[188:191], v[200:201], off
	global_load_dwordx4 v[192:195], v[200:201], off offset:64
	global_load_dwordx4 v[196:199], v[200:201], off offset:512
	s_nop 0
	global_load_dwordx4 v[200:203], v[200:201], off offset:576
	s_waitcnt vmcnt(0) lgkmcnt(0)
	v_pk_fma_f32 v[126:127], v[126:127], 0.5, v[138:139] op_sel_hi:[1,0,1]
	v_lshl_add_u64 v[138:139], s[4:5], 0, v[206:207]
	v_lshl_add_u64 v[138:139], v[138:139], 0, v[132:133]
	v_pk_fma_f32 v[116:117], v[116:117], 0.5, v[150:151] op_sel_hi:[1,0,1]
	v_pk_fma_f32 v[114:115], v[114:115], 0.5, v[148:149] op_sel_hi:[1,0,1]
	global_store_dwordx4 v[138:139], v[114:117], off offset:512
	v_pk_fma_f32 v[100:101], v[100:101], 0.5, v[166:167] op_sel_hi:[1,0,1]
	v_pk_fma_f32 v[98:99], v[98:99], 0.5, v[164:165] op_sel_hi:[1,0,1]
	v_lshl_add_u64 v[114:115], s[4:5], 0, v[208:209]
	v_lshl_add_u64 v[114:115], v[114:115], 0, v[132:133]
	global_store_dwordx4 v[114:115], v[98:101], off offset:512
	v_pk_fma_f32 v[84:85], v[84:85], 0.5, v[182:183] op_sel_hi:[1,0,1]
	v_pk_fma_f32 v[82:83], v[82:83], 0.5, v[180:181] op_sel_hi:[1,0,1]
	v_lshl_add_u64 v[98:99], s[4:5], 0, v[210:211]
	v_lshl_add_u64 v[98:99], v[98:99], 0, v[132:133]
	v_pk_fma_f32 v[108:109], v[108:109], 0.5, v[154:155] op_sel_hi:[1,0,1]
	v_pk_fma_f32 v[106:107], v[106:107], 0.5, v[152:153] op_sel_hi:[1,0,1]
	v_pk_fma_f32 v[92:93], v[92:93], 0.5, v[170:171] op_sel_hi:[1,0,1]
	v_pk_fma_f32 v[90:91], v[90:91], 0.5, v[168:169] op_sel_hi:[1,0,1]
	global_store_dwordx4 v[98:99], v[82:85], off offset:512
	v_pk_fma_f32 v[76:77], v[76:77], 0.5, v[186:187] op_sel_hi:[1,0,1]
	v_pk_fma_f32 v[74:75], v[74:75], 0.5, v[184:185] op_sel_hi:[1,0,1]
	v_lshl_add_u64 v[82:83], s[4:5], 0, v[212:213]
	global_store_dwordx4 v[138:139], v[106:109], off offset:576
	global_store_dwordx4 v[114:115], v[90:93], off offset:576
	global_store_dwordx4 v[98:99], v[74:77], off offset:576
	v_pk_fma_f32 v[108:109], v[120:121], 0.5, v[158:159] op_sel_hi:[1,0,1]
	v_pk_fma_f32 v[106:107], v[118:119], 0.5, v[156:157] op_sel_hi:[1,0,1]
	v_pk_fma_f32 v[92:93], v[104:105], 0.5, v[174:175] op_sel_hi:[1,0,1]
	v_pk_fma_f32 v[90:91], v[102:103], 0.5, v[172:173] op_sel_hi:[1,0,1]
	v_pk_fma_f32 v[76:77], v[88:89], 0.5, v[190:191] op_sel_hi:[1,0,1]
	v_pk_fma_f32 v[74:75], v[86:87], 0.5, v[188:189] op_sel_hi:[1,0,1]
	v_lshl_add_u64 v[82:83], v[82:83], 0, v[132:133]
	v_pk_fma_f32 v[128:129], v[128:129], 0.5, v[140:141] op_sel_hi:[1,0,1]
	v_pk_fma_f32 v[124:125], v[124:125], 0.5, v[144:145] op_sel_hi:[1,0,1]
	v_pk_fma_f32 v[122:123], v[122:123], 0.5, v[142:143] op_sel_hi:[1,0,1]
	global_store_dwordx4 v[114:115], v[106:109], off
	global_store_dwordx4 v[98:99], v[90:93], off
	global_store_dwordx4 v[82:83], v[74:77], off
	v_pk_fma_f32 v[108:109], v[112:113], 0.5, v[162:163] op_sel_hi:[1,0,1]
	v_pk_fma_f32 v[106:107], v[110:111], 0.5, v[160:161] op_sel_hi:[1,0,1]
	v_pk_fma_f32 v[92:93], v[96:97], 0.5, v[178:179] op_sel_hi:[1,0,1]
	v_pk_fma_f32 v[90:91], v[94:95], 0.5, v[176:177] op_sel_hi:[1,0,1]
	v_pk_fma_f32 v[76:77], v[80:81], 0.5, v[194:195] op_sel_hi:[1,0,1]
	v_pk_fma_f32 v[74:75], v[78:79], 0.5, v[192:193] op_sel_hi:[1,0,1]
	v_pk_fma_f32 v[72:73], v[72:73], 0.5, v[198:199] op_sel_hi:[1,0,1]
	v_pk_fma_f32 v[70:71], v[70:71], 0.5, v[196:197] op_sel_hi:[1,0,1]
	v_pk_fma_f32 v[68:69], v[68:69], 0.5, v[202:203] op_sel_hi:[1,0,1]
	v_pk_fma_f32 v[66:67], v[66:67], 0.5, v[200:201] op_sel_hi:[1,0,1]
	global_store_dwordx4 v[138:139], v[126:129], off
	global_store_dwordx4 v[138:139], v[122:125], off offset:64
	global_store_dwordx4 v[114:115], v[106:109], off offset:64
	global_store_dwordx4 v[98:99], v[90:93], off offset:64
	global_store_dwordx4 v[82:83], v[74:77], off offset:64
	global_store_dwordx4 v[82:83], v[70:73], off offset:512
	global_store_dwordx4 v[82:83], v[66:69], off offset:576
	s_mov_b64 s[6:7], 0x120000
	v_lshl_add_u64 v[140:141], v[206:207], 0, s[6:7]
	s_mov_b64 s[6:7], 0x140000
	v_lshl_add_u64 v[138:139], v[206:207], 0, s[0:1]
	v_lshl_add_u64 v[142:143], v[206:207], 0, s[6:7]
	v_lshl_add_u64 v[144:145], v[206:207], 0, s[28:29]
	v_lshl_add_u64 v[78:79], v[204:205], 0, v[138:139]
	v_lshl_add_u64 v[94:95], v[204:205], 0, v[140:141]
	v_lshl_add_u64 v[110:111], v[204:205], 0, v[142:143]
	v_lshl_add_u64 v[126:127], v[204:205], 0, v[144:145]
	global_load_dwordx4 v[66:69], v[78:79], off
	global_load_dwordx4 v[70:73], v[78:79], off offset:64
	global_load_dwordx4 v[74:77], v[78:79], off offset:512
	s_nop 0
	global_load_dwordx4 v[78:81], v[78:79], off offset:576
	s_nop 0
	global_load_dwordx4 v[82:85], v[94:95], off
	global_load_dwordx4 v[86:89], v[94:95], off offset:64
	global_load_dwordx4 v[90:93], v[94:95], off offset:512
	s_nop 0
	global_load_dwordx4 v[94:97], v[94:95], off offset:576
	s_nop 0
	global_load_dwordx4 v[98:101], v[110:111], off
	global_load_dwordx4 v[102:105], v[110:111], off offset:64
	global_load_dwordx4 v[106:109], v[110:111], off offset:512
	s_nop 0
	global_load_dwordx4 v[110:113], v[110:111], off offset:576
	s_nop 0
	global_load_dwordx4 v[114:117], v[126:127], off
	global_load_dwordx4 v[118:121], v[126:127], off offset:64
	global_load_dwordx4 v[122:125], v[126:127], off offset:512
	s_nop 0
	global_load_dwordx4 v[126:129], v[126:127], off offset:576
	s_waitcnt vmcnt(0) lgkmcnt(0)
	v_pk_fma_f32 v[62:63], v[62:63], 0.5, v[66:67] op_sel_hi:[1,0,1]
	v_lshl_add_u64 v[66:67], s[4:5], 0, v[138:139]
	v_lshl_add_u64 v[66:67], v[66:67], 0, v[132:133]
	v_pk_fma_f32 v[52:53], v[52:53], 0.5, v[76:77] op_sel_hi:[1,0,1]
	v_pk_fma_f32 v[50:51], v[50:51], 0.5, v[74:75] op_sel_hi:[1,0,1]
	global_store_dwordx4 v[66:67], v[50:53], off offset:512
	v_pk_fma_f32 v[36:37], v[36:37], 0.5, v[92:93] op_sel_hi:[1,0,1]
	v_pk_fma_f32 v[34:35], v[34:35], 0.5, v[90:91] op_sel_hi:[1,0,1]
	v_lshl_add_u64 v[50:51], s[4:5], 0, v[140:141]
	v_lshl_add_u64 v[50:51], v[50:51], 0, v[132:133]
	global_store_dwordx4 v[50:51], v[34:37], off offset:512
	v_pk_fma_f32 v[20:21], v[20:21], 0.5, v[108:109] op_sel_hi:[1,0,1]
	v_pk_fma_f32 v[18:19], v[18:19], 0.5, v[106:107] op_sel_hi:[1,0,1]
	v_lshl_add_u64 v[34:35], s[4:5], 0, v[142:143]
	v_lshl_add_u64 v[34:35], v[34:35], 0, v[132:133]
	v_pk_fma_f32 v[44:45], v[44:45], 0.5, v[80:81] op_sel_hi:[1,0,1]
	v_pk_fma_f32 v[42:43], v[42:43], 0.5, v[78:79] op_sel_hi:[1,0,1]
	v_pk_fma_f32 v[28:29], v[28:29], 0.5, v[96:97] op_sel_hi:[1,0,1]
	v_pk_fma_f32 v[26:27], v[26:27], 0.5, v[94:95] op_sel_hi:[1,0,1]
	global_store_dwordx4 v[34:35], v[18:21], off offset:512
	v_pk_fma_f32 v[12:13], v[12:13], 0.5, v[112:113] op_sel_hi:[1,0,1]
	v_pk_fma_f32 v[10:11], v[10:11], 0.5, v[110:111] op_sel_hi:[1,0,1]
	v_lshl_add_u64 v[18:19], s[4:5], 0, v[144:145]
	global_store_dwordx4 v[66:67], v[42:45], off offset:576
	global_store_dwordx4 v[50:51], v[26:29], off offset:576
	global_store_dwordx4 v[34:35], v[10:13], off offset:576
	v_pk_fma_f32 v[44:45], v[56:57], 0.5, v[84:85] op_sel_hi:[1,0,1]
	v_pk_fma_f32 v[42:43], v[54:55], 0.5, v[82:83] op_sel_hi:[1,0,1]
	v_pk_fma_f32 v[28:29], v[40:41], 0.5, v[100:101] op_sel_hi:[1,0,1]
	v_pk_fma_f32 v[26:27], v[38:39], 0.5, v[98:99] op_sel_hi:[1,0,1]
	v_pk_fma_f32 v[12:13], v[24:25], 0.5, v[116:117] op_sel_hi:[1,0,1]
	v_pk_fma_f32 v[10:11], v[22:23], 0.5, v[114:115] op_sel_hi:[1,0,1]
	v_lshl_add_u64 v[18:19], v[18:19], 0, v[132:133]
	v_pk_fma_f32 v[64:65], v[64:65], 0.5, v[68:69] op_sel_hi:[1,0,1]
	v_pk_fma_f32 v[60:61], v[60:61], 0.5, v[72:73] op_sel_hi:[1,0,1]
	v_pk_fma_f32 v[58:59], v[58:59], 0.5, v[70:71] op_sel_hi:[1,0,1]
	global_store_dwordx4 v[50:51], v[42:45], off
	global_store_dwordx4 v[34:35], v[26:29], off
	global_store_dwordx4 v[18:19], v[10:13], off
	v_pk_fma_f32 v[44:45], v[48:49], 0.5, v[88:89] op_sel_hi:[1,0,1]
	v_pk_fma_f32 v[42:43], v[46:47], 0.5, v[86:87] op_sel_hi:[1,0,1]
	v_pk_fma_f32 v[28:29], v[32:33], 0.5, v[104:105] op_sel_hi:[1,0,1]
	v_pk_fma_f32 v[26:27], v[30:31], 0.5, v[102:103] op_sel_hi:[1,0,1]
	v_pk_fma_f32 v[12:13], v[16:17], 0.5, v[120:121] op_sel_hi:[1,0,1]
	v_pk_fma_f32 v[10:11], v[14:15], 0.5, v[118:119] op_sel_hi:[1,0,1]
	v_pk_fma_f32 v[8:9], v[8:9], 0.5, v[124:125] op_sel_hi:[1,0,1]
	v_pk_fma_f32 v[6:7], v[6:7], 0.5, v[122:123] op_sel_hi:[1,0,1]
	v_pk_fma_f32 v[4:5], v[4:5], 0.5, v[128:129] op_sel_hi:[1,0,1]
	v_pk_fma_f32 v[2:3], v[2:3], 0.5, v[126:127] op_sel_hi:[1,0,1]
	global_store_dwordx4 v[66:67], v[62:65], off
	global_store_dwordx4 v[66:67], v[58:61], off offset:64
	global_store_dwordx4 v[50:51], v[42:45], off offset:64
	global_store_dwordx4 v[34:35], v[26:29], off offset:64
	global_store_dwordx4 v[18:19], v[10:13], off offset:64
	global_store_dwordx4 v[18:19], v[6:9], off offset:512
	global_store_dwordx4 v[18:19], v[2:5], off offset:576
	s_and_b64 vcc, exec, s[40:41]
	s_mov_b32 s85, s10
	s_mov_b32 s86, s11
	s_mov_b64 s[8:9], s[44:45]
	s_mov_b64 s[6:7], s[42:43]
	s_movk_i32 s89, 0x37ff
	s_mov_b32 s88, 0x16000
	s_movk_i32 s91, 0x60
	s_mov_b32 s78, 0x2a000000
	s_mov_b32 s79, 0x3fffe
	s_mov_b32 s90, 0xc0000
	s_cbranch_vccz .LBB0_478
	s_waitcnt vmcnt(0)
	s_cmpk_gt_u32 s48, 0xff
	s_cbranch_scc1 .LBB0_489
	s_barrier

.Lrot_enter_5:
	s_add_u32 s8, s6, 0x100
	s_addc_u32 s9, s7, 0
	s_add_i32 s78, 0, 0x10000
	v_add_u32_e32 v134, s78, v137
	ds_read_b128 v[140:143], v134
	ds_read_b128 v[148:151], v134 offset:1024
	ds_read_b128 v[152:155], v134 offset:2048
	ds_read_b128 v[156:159], v134 offset:3072
	s_cmp_eq_u32 s87, 28
	s_cselect_b32 s89, s43, s9
	s_cselect_b32 s88, s42, s8
	s_cselect_b32 s91, s47, s86
	s_cselect_b32 s90, s46, s41
	v_lshl_add_u64 v[134:135], s[6:7], 0, v[132:133]
	v_lshl_add_u64 v[144:145], v[134:135], 0, s[16:17]
	s_add_i32 m0, s49, 0xc000
	ds_read_b128 v[160:163], v138
	ds_read_b128 v[164:167], v138 offset:1024
	ds_read_b128 v[168:171], v138 offset:2048
	ds_read_b128 v[172:175], v138 offset:3072
	ds_read_b128 v[176:179], v138 offset:4096
	ds_read_b128 v[180:183], v138 offset:5120
	ds_read_b128 v[184:187], v138 offset:6144
	ds_read_b128 v[188:191], v138 offset:7168
	global_load_lds_dwordx4 v[144:145], off
	v_lshl_add_u64 v[134:135], v[134:135], 0, s[80:81]
	s_add_i32 m0, s49, 0xe000
	s_nop 0
	global_load_lds_dwordx4 v[134:135], off
	s_waitcnt lgkmcnt(8)
	s_setprio 1
	s_barrier
	s_waitcnt lgkmcnt(0)
	v_mfma_f32_16x16x32_bf16 v[126:129], v[140:143], v[160:163], v[126:129]
	v_mfma_f32_16x16x32_bf16 v[118:121], v[152:155], v[160:163], v[118:121]
	v_mfma_f32_16x16x32_bf16 v[110:113], v[140:143], v[168:171], v[110:113]
	v_mfma_f32_16x16x32_bf16 v[102:105], v[152:155], v[168:171], v[102:105]
	v_mfma_f32_16x16x32_bf16 v[94:97], v[140:143], v[176:179], v[94:97]
	v_mfma_f32_16x16x32_bf16 v[86:89], v[152:155], v[176:179], v[86:89]
	v_mfma_f32_16x16x32_bf16 v[78:81], v[140:143], v[184:187], v[78:81]
	v_mfma_f32_16x16x32_bf16 v[70:73], v[152:155], v[184:187], v[70:73]
	v_mfma_f32_16x16x32_bf16 v[126:129], v[148:151], v[164:167], v[126:129]
	v_mfma_f32_16x16x32_bf16 v[118:121], v[156:159], v[164:167], v[118:121]
	v_mfma_f32_16x16x32_bf16 v[110:113], v[148:151], v[172:175], v[110:113]
	v_mfma_f32_16x16x32_bf16 v[102:105], v[156:159], v[172:175], v[102:105]
	v_mfma_f32_16x16x32_bf16 v[94:97], v[148:151], v[180:183], v[94:97]
	v_mfma_f32_16x16x32_bf16 v[86:89], v[156:159], v[180:183], v[86:89]
	v_mfma_f32_16x16x32_bf16 v[78:81], v[148:151], v[188:191], v[78:81]
	v_mfma_f32_16x16x32_bf16 v[70:73], v[156:159], v[188:191], v[70:73]
	s_barrier
	s_setprio 0
	s_add_i32 s6, 0, 0x14000
	v_add_u32_e32 v134, s6, v137
	s_add_i32 s7, s78, s54
	ds_read_b128 v[192:195], v134
	ds_read_b128 v[196:199], v134 offset:1024
	ds_read_b128 v[200:203], v134 offset:2048
	ds_read_b128 v[204:207], v134 offset:3072
	v_lshl_add_u64 v[134:135], s[90:91], 0, v[0:1]
	s_mov_b32 m0, s7
	v_lshl_add_u64 v[144:145], v[134:135], 0, s[60:61]
	global_load_lds_dwordx4 v[134:135], off
	s_add_i32 m0, s7, 0x2000
	s_nop 0
	global_load_lds_dwordx4 v[144:145], off
	s_setprio 1
	s_barrier
	s_waitcnt lgkmcnt(0)
	v_mfma_f32_16x16x32_bf16 v[122:125], v[192:195], v[160:163], v[122:125]
	v_mfma_f32_16x16x32_bf16 v[114:117], v[200:203], v[160:163], v[114:117]
	v_mfma_f32_16x16x32_bf16 v[106:109], v[192:195], v[168:171], v[106:109]
	v_mfma_f32_16x16x32_bf16 v[98:101], v[200:203], v[168:171], v[98:101]
	v_mfma_f32_16x16x32_bf16 v[90:93], v[192:195], v[176:179], v[90:93]
	v_mfma_f32_16x16x32_bf16 v[82:85], v[200:203], v[176:179], v[82:85]
	v_mfma_f32_16x16x32_bf16 v[74:77], v[192:195], v[184:187], v[74:77]
	v_mfma_f32_16x16x32_bf16 v[66:69], v[200:203], v[184:187], v[66:69]
	v_mfma_f32_16x16x32_bf16 v[122:125], v[196:199], v[164:167], v[122:125]
	v_mfma_f32_16x16x32_bf16 v[114:117], v[204:207], v[164:167], v[114:117]
	v_mfma_f32_16x16x32_bf16 v[106:109], v[196:199], v[172:175], v[106:109]
	v_mfma_f32_16x16x32_bf16 v[98:101], v[204:207], v[172:175], v[98:101]
	v_mfma_f32_16x16x32_bf16 v[90:93], v[196:199], v[180:183], v[90:93]
	v_mfma_f32_16x16x32_bf16 v[82:85], v[204:207], v[180:183], v[82:85]
	v_mfma_f32_16x16x32_bf16 v[74:77], v[196:199], v[188:191], v[74:77]
	v_mfma_f32_16x16x32_bf16 v[66:69], v[204:207], v[188:191], v[66:69]
	s_barrier
	s_setprio 0
	s_mov_b32 m0, s49
	v_lshl_add_u64 v[144:145], s[88:89], 0, v[130:131]
	ds_read_b128 v[160:163], v138 offset:16384
	ds_read_b128 v[164:167], v138 offset:17408
	ds_read_b128 v[168:171], v138 offset:18432
	ds_read_b128 v[172:175], v138 offset:19456
	ds_read_b128 v[176:179], v138 offset:20480
	ds_read_b128 v[180:183], v138 offset:21504
	ds_read_b128 v[184:187], v138 offset:22528
	ds_read_b128 v[188:191], v138 offset:23552
	global_load_lds_dwordx4 v[144:145], off
	v_lshl_add_u64 v[208:209], v[144:145], 0, s[60:61]
	s_mov_b32 m0, s55
	s_nop 0
	global_load_lds_dwordx4 v[208:209], off
	s_setprio 1
	s_barrier
	s_waitcnt lgkmcnt(0)
	v_mfma_f32_16x16x32_bf16 v[62:65], v[140:143], v[160:163], v[62:65]
	v_mfma_f32_16x16x32_bf16 v[54:57], v[152:155], v[160:163], v[54:57]
	v_mfma_f32_16x16x32_bf16 v[46:49], v[140:143], v[168:171], v[46:49]
	v_mfma_f32_16x16x32_bf16 v[38:41], v[152:155], v[168:171], v[38:41]
	v_mfma_f32_16x16x32_bf16 v[30:33], v[140:143], v[176:179], v[30:33]
	v_mfma_f32_16x16x32_bf16 v[22:25], v[152:155], v[176:179], v[22:25]
	v_mfma_f32_16x16x32_bf16 v[14:17], v[140:143], v[184:187], v[14:17]
	v_mfma_f32_16x16x32_bf16 v[6:9], v[152:155], v[184:187], v[6:9]
	v_mfma_f32_16x16x32_bf16 v[62:65], v[148:151], v[164:167], v[62:65]
	v_mfma_f32_16x16x32_bf16 v[54:57], v[156:159], v[164:167], v[54:57]
	v_mfma_f32_16x16x32_bf16 v[46:49], v[148:151], v[172:175], v[46:49]
	v_mfma_f32_16x16x32_bf16 v[38:41], v[156:159], v[172:175], v[38:41]
	v_mfma_f32_16x16x32_bf16 v[30:33], v[148:151], v[180:183], v[30:33]
	v_mfma_f32_16x16x32_bf16 v[22:25], v[156:159], v[180:183], v[22:25]
	v_mfma_f32_16x16x32_bf16 v[14:17], v[148:151], v[188:191], v[14:17]
	v_mfma_f32_16x16x32_bf16 v[6:9], v[156:159], v[188:191], v[6:9]
	s_barrier
	s_setprio 0
	s_add_i32 s6, s6, s54
	v_lshl_add_u64 v[140:141], v[134:135], 0, s[20:21]
	s_mov_b32 m0, s6
	s_nop 0
	global_load_lds_dwordx4 v[140:141], off
	v_lshl_add_u64 v[140:141], v[134:135], 0, s[64:65]
	s_add_i32 m0, s6, 0x2000
	s_nop 0
	global_load_lds_dwordx4 v[140:141], off
	v_lshl_add_u64 v[230:231], v[144:145], 0, s[20:21]
	s_mov_b32 m0, s56
	s_nop 0
	global_load_lds_dwordx4 v[230:231], off
	v_lshl_add_u64 v[230:231], v[144:145], 0, s[64:65]
	s_mov_b32 m0, s57
	s_nop 0
	global_load_lds_dwordx4 v[230:231], off
	s_waitcnt vmcnt(8)
	s_setprio 1
	s_barrier
	v_mfma_f32_16x16x32_bf16 v[58:61], v[192:195], v[160:163], v[58:61]
	v_mfma_f32_16x16x32_bf16 v[50:53], v[200:203], v[160:163], v[50:53]
	v_mfma_f32_16x16x32_bf16 v[42:45], v[192:195], v[168:171], v[42:45]
	v_mfma_f32_16x16x32_bf16 v[34:37], v[200:203], v[168:171], v[34:37]
	v_mfma_f32_16x16x32_bf16 v[26:29], v[192:195], v[176:179], v[26:29]
	v_mfma_f32_16x16x32_bf16 v[18:21], v[200:203], v[176:179], v[18:21]
	v_mfma_f32_16x16x32_bf16 v[10:13], v[192:195], v[184:187], v[10:13]
	v_mfma_f32_16x16x32_bf16 v[2:5], v[200:203], v[184:187], v[2:5]
	v_mfma_f32_16x16x32_bf16 v[58:61], v[196:199], v[164:167], v[58:61]
	v_mfma_f32_16x16x32_bf16 v[50:53], v[204:207], v[164:167], v[50:53]
	v_mfma_f32_16x16x32_bf16 v[42:45], v[196:199], v[172:175], v[42:45]
	v_mfma_f32_16x16x32_bf16 v[34:37], v[204:207], v[172:175], v[34:37]
	v_mfma_f32_16x16x32_bf16 v[26:29], v[196:199], v[180:183], v[26:29]
	v_mfma_f32_16x16x32_bf16 v[18:21], v[204:207], v[180:183], v[18:21]
	v_mfma_f32_16x16x32_bf16 v[10:13], v[196:199], v[188:191], v[10:13]
	v_mfma_f32_16x16x32_bf16 v[2:5], v[204:207], v[188:191], v[2:5]
	s_barrier
	s_setprio 0
	s_add_i32 s6, 0, 0x18000
	v_add_u32_e32 v139, s6, v137
	ds_read_b128 v[140:143], v139
	ds_read_b128 v[148:151], v139 offset:1024
	ds_read_b128 v[152:155], v139 offset:2048
	ds_read_b128 v[156:159], v139 offset:3072
	ds_read_b128 v[160:163], v138 offset:32768
	ds_read_b128 v[164:167], v138 offset:33792
	ds_read_b128 v[168:171], v138 offset:34816
	ds_read_b128 v[172:175], v138 offset:35840
	ds_read_b128 v[176:179], v138 offset:36864
	ds_read_b128 v[180:183], v138 offset:37888
	ds_read_b128 v[184:187], v138 offset:38912
	ds_read_b128 v[188:191], v138 offset:39936
	s_waitcnt lgkmcnt(8)
	s_setprio 1
	s_barrier
	s_waitcnt lgkmcnt(0)
	v_mfma_f32_16x16x32_bf16 v[126:129], v[140:143], v[160:163], v[126:129]
	v_mfma_f32_16x16x32_bf16 v[118:121], v[152:155], v[160:163], v[118:121]
	v_mfma_f32_16x16x32_bf16 v[110:113], v[140:143], v[168:171], v[110:113]
	v_mfma_f32_16x16x32_bf16 v[102:105], v[152:155], v[168:171], v[102:105]
	v_mfma_f32_16x16x32_bf16 v[94:97], v[140:143], v[176:179], v[94:97]
	v_mfma_f32_16x16x32_bf16 v[86:89], v[152:155], v[176:179], v[86:89]
	v_mfma_f32_16x16x32_bf16 v[78:81], v[140:143], v[184:187], v[78:81]
	v_mfma_f32_16x16x32_bf16 v[70:73], v[152:155], v[184:187], v[70:73]
	v_mfma_f32_16x16x32_bf16 v[126:129], v[148:151], v[164:167], v[126:129]
	v_mfma_f32_16x16x32_bf16 v[118:121], v[156:159], v[164:167], v[118:121]
	v_mfma_f32_16x16x32_bf16 v[110:113], v[148:151], v[172:175], v[110:113]
	v_mfma_f32_16x16x32_bf16 v[102:105], v[156:159], v[172:175], v[102:105]
	v_mfma_f32_16x16x32_bf16 v[94:97], v[148:151], v[180:183], v[94:97]
	v_mfma_f32_16x16x32_bf16 v[86:89], v[156:159], v[180:183], v[86:89]
	v_mfma_f32_16x16x32_bf16 v[78:81], v[148:151], v[188:191], v[78:81]
	v_mfma_f32_16x16x32_bf16 v[70:73], v[156:159], v[188:191], v[70:73]
	s_barrier
	s_setprio 0
	s_add_i32 s7, 0, 0x1c000
	s_add_i32 s6, s6, s54
	v_add_u32_e32 v139, s7, v137
	v_lshl_add_u64 v[208:209], v[134:135], 0, s[34:35]
	s_mov_b32 m0, s6
	ds_read_b128 v[192:195], v139
	ds_read_b128 v[196:199], v139 offset:1024
	ds_read_b128 v[200:203], v139 offset:2048
	ds_read_b128 v[204:207], v139 offset:3072
	global_load_lds_dwordx4 v[208:209], off
	v_lshl_add_u64 v[208:209], v[134:135], 0, s[66:67]
	s_add_i32 m0, s6, 0x2000
	s_nop 0
	global_load_lds_dwordx4 v[208:209], off
	s_setprio 1
	s_barrier
	s_waitcnt lgkmcnt(0)
	v_mfma_f32_16x16x32_bf16 v[122:125], v[192:195], v[160:163], v[122:125]
	v_mfma_f32_16x16x32_bf16 v[114:117], v[200:203], v[160:163], v[114:117]
	v_mfma_f32_16x16x32_bf16 v[106:109], v[192:195], v[168:171], v[106:109]
	v_mfma_f32_16x16x32_bf16 v[98:101], v[200:203], v[168:171], v[98:101]
	v_mfma_f32_16x16x32_bf16 v[90:93], v[192:195], v[176:179], v[90:93]
	v_mfma_f32_16x16x32_bf16 v[82:85], v[200:203], v[176:179], v[82:85]
	v_mfma_f32_16x16x32_bf16 v[74:77], v[192:195], v[184:187], v[74:77]
	v_mfma_f32_16x16x32_bf16 v[66:69], v[200:203], v[184:187], v[66:69]
	v_mfma_f32_16x16x32_bf16 v[122:125], v[196:199], v[164:167], v[122:125]
	v_mfma_f32_16x16x32_bf16 v[114:117], v[204:207], v[164:167], v[114:117]
	v_mfma_f32_16x16x32_bf16 v[106:109], v[196:199], v[172:175], v[106:109]
	v_mfma_f32_16x16x32_bf16 v[98:101], v[204:207], v[172:175], v[98:101]
	v_mfma_f32_16x16x32_bf16 v[90:93], v[196:199], v[180:183], v[90:93]
	v_mfma_f32_16x16x32_bf16 v[82:85], v[204:207], v[180:183], v[82:85]
	v_mfma_f32_16x16x32_bf16 v[74:77], v[196:199], v[188:191], v[74:77]
	v_mfma_f32_16x16x32_bf16 v[66:69], v[204:207], v[188:191], v[66:69]
	s_barrier
	s_setprio 0
	s_mov_b32 m0, s59
	v_lshl_add_u64 v[208:209], v[144:145], 0, s[34:35]
	ds_read_b128 v[160:163], v138 offset:49152
	ds_read_b128 v[164:167], v138 offset:50176
	ds_read_b128 v[168:171], v138 offset:51200
	ds_read_b128 v[172:175], v138 offset:52224
	ds_read_b128 v[176:179], v138 offset:53248
	ds_read_b128 v[180:183], v138 offset:54272
	ds_read_b128 v[184:187], v138 offset:55296
	ds_read_b128 v[188:191], v138 offset:56320
	global_load_lds_dwordx4 v[208:209], off
	v_lshl_add_u64 v[144:145], v[144:145], 0, s[66:67]
	s_mov_b32 m0, s62
	s_nop 0
	global_load_lds_dwordx4 v[144:145], off
	s_setprio 1
	s_barrier
	s_waitcnt lgkmcnt(0)
	v_mfma_f32_16x16x32_bf16 v[62:65], v[140:143], v[160:163], v[62:65]
	v_mfma_f32_16x16x32_bf16 v[54:57], v[152:155], v[160:163], v[54:57]
	v_mfma_f32_16x16x32_bf16 v[46:49], v[140:143], v[168:171], v[46:49]
	v_mfma_f32_16x16x32_bf16 v[38:41], v[152:155], v[168:171], v[38:41]
	v_mfma_f32_16x16x32_bf16 v[30:33], v[140:143], v[176:179], v[30:33]
	v_mfma_f32_16x16x32_bf16 v[22:25], v[152:155], v[176:179], v[22:25]
	v_mfma_f32_16x16x32_bf16 v[14:17], v[140:143], v[184:187], v[14:17]
	v_mfma_f32_16x16x32_bf16 v[6:9], v[152:155], v[184:187], v[6:9]
	v_mfma_f32_16x16x32_bf16 v[62:65], v[148:151], v[164:167], v[62:65]
	v_mfma_f32_16x16x32_bf16 v[54:57], v[156:159], v[164:167], v[54:57]
	v_mfma_f32_16x16x32_bf16 v[46:49], v[148:151], v[172:175], v[46:49]
	v_mfma_f32_16x16x32_bf16 v[38:41], v[156:159], v[172:175], v[38:41]
	v_mfma_f32_16x16x32_bf16 v[30:33], v[148:151], v[180:183], v[30:33]
	v_mfma_f32_16x16x32_bf16 v[22:25], v[156:159], v[180:183], v[22:25]
	v_mfma_f32_16x16x32_bf16 v[14:17], v[148:151], v[188:191], v[14:17]
	v_mfma_f32_16x16x32_bf16 v[6:9], v[156:159], v[188:191], v[6:9]
	s_barrier
	s_setprio 0
	s_add_i32 s6, s7, s54
	v_lshl_add_u64 v[140:141], v[134:135], 0, s[16:17]
	s_mov_b32 m0, s6
	v_lshl_add_u64 v[134:135], v[134:135], 0, s[80:81]
	global_load_lds_dwordx4 v[140:141], off
	s_add_i32 m0, s6, 0x2000
	s_nop 0
	global_load_lds_dwordx4 v[134:135], off
	s_waitcnt vmcnt(6)
	s_add_i32 s87, s87, 2
	s_add_u32 s41, s41, 0x100
	s_addc_u32 s86, s86, 0
	s_cmp_gt_u32 s87, 29
	s_mov_b64 s[6:7], s[8:9]
	s_cbranch_scc0 .LBB0_503
	s_setprio 1
	s_barrier
	v_mfma_f32_16x16x32_bf16 v[58:61], v[192:195], v[160:163], v[58:61]
	v_mfma_f32_16x16x32_bf16 v[50:53], v[200:203], v[160:163], v[50:53]
	v_mfma_f32_16x16x32_bf16 v[42:45], v[192:195], v[168:171], v[42:45]
	v_mfma_f32_16x16x32_bf16 v[34:37], v[200:203], v[168:171], v[34:37]
	v_mfma_f32_16x16x32_bf16 v[26:29], v[192:195], v[176:179], v[26:29]
	v_mfma_f32_16x16x32_bf16 v[18:21], v[200:203], v[176:179], v[18:21]
	v_mfma_f32_16x16x32_bf16 v[10:13], v[192:195], v[184:187], v[10:13]
	v_mfma_f32_16x16x32_bf16 v[2:5], v[200:203], v[184:187], v[2:5]
	v_mfma_f32_16x16x32_bf16 v[58:61], v[196:199], v[164:167], v[58:61]
	v_mfma_f32_16x16x32_bf16 v[50:53], v[204:207], v[164:167], v[50:53]
	v_mfma_f32_16x16x32_bf16 v[42:45], v[196:199], v[172:175], v[42:45]
	v_mfma_f32_16x16x32_bf16 v[34:37], v[204:207], v[172:175], v[34:37]
	v_mfma_f32_16x16x32_bf16 v[26:29], v[196:199], v[180:183], v[26:29]
	v_mfma_f32_16x16x32_bf16 v[18:21], v[204:207], v[180:183], v[18:21]
	v_mfma_f32_16x16x32_bf16 v[10:13], v[196:199], v[188:191], v[10:13]
	v_mfma_f32_16x16x32_bf16 v[2:5], v[204:207], v[188:191], v[2:5]
	s_barrier
	s_setprio 0
	v_mul_f32_e32 v144, 0xbfb8aa3b, v126
	v_exp_f32_e32 v144, v144
	v_mov_b32_e32 v134, v136
	s_lshl_b32 s6, s48, 8
	v_add_f32_e32 v144, 1.0, v144
	v_rcp_f32_e32 v144, v144
	s_add_i32 s6, s6, s10
	v_and_or_b32 v139, v134, 15, s6
	s_lshl_b32 s6, s85, 7
	v_mul_f32_e32 v126, v126, v144
	v_mul_f32_e32 v122, v126, v122
	v_mul_f32_e32 v126, 0xbfb8aa3b, v127
	v_exp_f32_e32 v126, v126
	v_ashrrev_i32_e32 v134, 1, v134
	s_or_b32 s6, s6, s58
	v_and_b32_e32 v134, -8, v134
	v_add_f32_e32 v126, 1.0, v126
	v_rcp_f32_e32 v126, v126
	v_add_u32_e32 v140, s6, v134
	v_ashrrev_i32_e32 v141, 31, v140
	v_mov_b64_e32 v[134:135], s[4:5]
	v_mul_f32_e32 v126, v127, v126
	v_mul_f32_e32 v123, v126, v123
	v_mul_f32_e32 v126, 0xbfb8aa3b, v128
	v_exp_f32_e32 v126, v126
	v_mad_i64_i32 v[142:143], s[6:7], v139, s74, v[134:135]
	s_and_b64 vcc, exec, s[44:45]
	v_add_f32_e32 v126, 1.0, v126
	v_rcp_f32_e32 v126, v126
	s_mov_b32 s48, s40
	s_mov_b32 s85, s84
	s_mov_b64 s[8:9], s[46:47]
	v_mul_f32_e32 v126, v128, v126
	v_mul_f32_e32 v124, v126, v124
	v_mul_f32_e32 v126, 0xbfb8aa3b, v129
	v_exp_f32_e32 v126, v126
	s_nop 0
	v_add_f32_e32 v126, 1.0, v126
	v_rcp_f32_e32 v126, v126
	s_nop 0
	v_mul_f32_e32 v126, v129, v126
	v_mul_f32_e32 v125, v126, v125
	v_mul_f32_e32 v126, 0xbfb8aa3b, v118
	v_exp_f32_e32 v126, v126
	s_nop 0
	v_add_f32_e32 v126, 1.0, v126
	v_rcp_f32_e32 v126, v126
	s_nop 0
	v_mul_f32_e32 v118, v118, v126
	v_mul_f32_e32 v118, v118, v114
	v_mul_f32_e32 v114, 0xbfb8aa3b, v119
	v_exp_f32_e32 v114, v114
	s_nop 0
	v_add_f32_e32 v114, 1.0, v114
	v_rcp_f32_e32 v114, v114
	s_nop 0
	v_mul_f32_e32 v114, v119, v114
	v_mul_f32_e32 v119, v114, v115
	v_mul_f32_e32 v114, 0xbfb8aa3b, v120
	v_exp_f32_e32 v114, v114
	s_nop 0
	v_add_f32_e32 v114, 1.0, v114
	v_rcp_f32_e32 v114, v114
	s_nop 0
	v_mul_f32_e32 v114, v120, v114
	v_mul_f32_e32 v126, v114, v116
	v_mul_f32_e32 v114, 0xbfb8aa3b, v121
	v_exp_f32_e32 v114, v114
	v_cvt_pk_bf16_f32 v116, v122, v123
	s_nop 0
	v_add_f32_e32 v114, 1.0, v114
	v_rcp_f32_e32 v114, v114
	s_nop 0
	v_mul_f32_e32 v114, v121, v114
	v_mul_f32_e32 v127, v114, v117
	v_lshlrev_b64 v[114:115], 1, v[140:141]
	v_lshl_add_u64 v[120:121], v[142:143], 0, v[114:115]
	v_cvt_pk_bf16_f32 v117, v124, v125
	v_cvt_pk_bf16_f32 v118, v118, v119
	v_cvt_pk_bf16_f32 v119, v126, v127
	global_store_dwordx4 v[120:121], v[116:119], off
	s_nop 1
	v_mul_f32_e32 v118, 0xbfb8aa3b, v110
	v_exp_f32_e32 v118, v118
	v_or_b32_e32 v116, 16, v139
	v_mad_i64_i32 v[116:117], s[6:7], v116, s74, v[134:135]
	v_add_f32_e32 v118, 1.0, v118
	v_rcp_f32_e32 v118, v118
	s_nop 0
	v_mul_f32_e32 v110, v110, v118
	v_mul_f32_e32 v106, v110, v106
	v_mul_f32_e32 v110, 0xbfb8aa3b, v111
	v_exp_f32_e32 v110, v110
	s_nop 0
	v_add_f32_e32 v110, 1.0, v110
	v_rcp_f32_e32 v110, v110
	s_nop 0
	v_mul_f32_e32 v110, v111, v110
	v_mul_f32_e32 v107, v110, v107
	v_mul_f32_e32 v110, 0xbfb8aa3b, v112
	v_exp_f32_e32 v110, v110
	s_nop 0
	v_add_f32_e32 v110, 1.0, v110
	v_rcp_f32_e32 v110, v110
	s_nop 0
	v_mul_f32_e32 v110, v112, v110
	v_mul_f32_e32 v108, v110, v108
	v_mul_f32_e32 v110, 0xbfb8aa3b, v113
	v_exp_f32_e32 v110, v110
	s_nop 0
	v_add_f32_e32 v110, 1.0, v110
	v_rcp_f32_e32 v110, v110
	s_nop 0
	v_mul_f32_e32 v110, v113, v110
	v_mul_f32_e32 v109, v110, v109
	v_mul_f32_e32 v110, 0xbfb8aa3b, v102
	v_exp_f32_e32 v110, v110
	s_nop 0
	v_add_f32_e32 v110, 1.0, v110
	v_rcp_f32_e32 v110, v110
	s_nop 0
	v_mul_f32_e32 v102, v102, v110
	v_mul_f32_e32 v110, v102, v98
	v_mul_f32_e32 v98, 0xbfb8aa3b, v103
	v_exp_f32_e32 v98, v98
	s_nop 0
	v_add_f32_e32 v98, 1.0, v98
	v_rcp_f32_e32 v98, v98
	s_nop 0
	v_mul_f32_e32 v98, v103, v98
	v_mul_f32_e32 v111, v98, v99
	v_mul_f32_e32 v98, 0xbfb8aa3b, v104
	v_exp_f32_e32 v98, v98
	v_lshl_add_u64 v[102:103], v[116:117], 0, v[114:115]
	v_add_f32_e32 v98, 1.0, v98
	v_rcp_f32_e32 v98, v98
	s_nop 0
	v_mul_f32_e32 v98, v104, v98
	v_mul_f32_e32 v104, v98, v100
	v_mul_f32_e32 v98, 0xbfb8aa3b, v105
	v_exp_f32_e32 v98, v98
	s_nop 0
	v_add_f32_e32 v98, 1.0, v98
	v_rcp_f32_e32 v98, v98
	s_nop 0
	v_mul_f32_e32 v98, v105, v98
	v_mul_f32_e32 v101, v98, v101
	v_cvt_pk_bf16_f32 v98, v106, v107
	v_cvt_pk_bf16_f32 v99, v108, v109
	v_cvt_pk_bf16_f32 v100, v110, v111
	v_cvt_pk_bf16_f32 v101, v104, v101
	global_store_dwordx4 v[102:103], v[98:101], off
	s_nop 1
	v_mul_f32_e32 v100, 0xbfb8aa3b, v94
	v_exp_f32_e32 v100, v100
	v_or_b32_e32 v98, 32, v139
	v_mad_i64_i32 v[98:99], s[6:7], v98, s74, v[134:135]
	v_add_f32_e32 v100, 1.0, v100
	v_rcp_f32_e32 v100, v100
	s_nop 0
	v_mul_f32_e32 v94, v94, v100
	v_mul_f32_e32 v90, v94, v90
	v_mul_f32_e32 v94, 0xbfb8aa3b, v95
	v_exp_f32_e32 v94, v94
	s_nop 0
	v_add_f32_e32 v94, 1.0, v94
	v_rcp_f32_e32 v94, v94
	s_nop 0
	v_mul_f32_e32 v94, v95, v94
	v_mul_f32_e32 v91, v94, v91
	v_mul_f32_e32 v94, 0xbfb8aa3b, v96
	v_exp_f32_e32 v94, v94
	s_nop 0
	v_add_f32_e32 v94, 1.0, v94
	v_rcp_f32_e32 v94, v94
	s_nop 0
	v_mul_f32_e32 v94, v96, v94
	v_mul_f32_e32 v92, v94, v92
	v_mul_f32_e32 v94, 0xbfb8aa3b, v97
	v_exp_f32_e32 v94, v94
	s_nop 0
	v_add_f32_e32 v94, 1.0, v94
	v_rcp_f32_e32 v94, v94
	s_nop 0
	v_mul_f32_e32 v94, v97, v94
	v_mul_f32_e32 v93, v94, v93
	v_mul_f32_e32 v94, 0xbfb8aa3b, v86
	v_exp_f32_e32 v94, v94
	s_nop 0
	v_add_f32_e32 v94, 1.0, v94
	v_rcp_f32_e32 v94, v94
	s_nop 0
	v_mul_f32_e32 v86, v86, v94
	v_mul_f32_e32 v94, v86, v82
	v_mul_f32_e32 v82, 0xbfb8aa3b, v87
	v_exp_f32_e32 v82, v82
	s_nop 0
	v_add_f32_e32 v82, 1.0, v82
	v_rcp_f32_e32 v82, v82
	s_nop 0
	v_mul_f32_e32 v82, v87, v82
	v_mul_f32_e32 v95, v82, v83
	v_mul_f32_e32 v82, 0xbfb8aa3b, v88
	v_exp_f32_e32 v82, v82
	v_lshl_add_u64 v[86:87], v[98:99], 0, v[114:115]
	v_add_f32_e32 v82, 1.0, v82
	v_rcp_f32_e32 v82, v82
	s_nop 0
	v_mul_f32_e32 v82, v88, v82
	v_mul_f32_e32 v88, v82, v84
	v_mul_f32_e32 v82, 0xbfb8aa3b, v89
	v_exp_f32_e32 v82, v82
	s_nop 0
	v_add_f32_e32 v82, 1.0, v82
	v_rcp_f32_e32 v82, v82
	s_nop 0
	v_mul_f32_e32 v82, v89, v82
	v_mul_f32_e32 v85, v82, v85
	v_cvt_pk_bf16_f32 v82, v90, v91
	v_cvt_pk_bf16_f32 v83, v92, v93
	v_cvt_pk_bf16_f32 v84, v94, v95
	v_cvt_pk_bf16_f32 v85, v88, v85
	global_store_dwordx4 v[86:87], v[82:85], off
	s_nop 1
	v_mul_f32_e32 v84, 0xbfb8aa3b, v78
	v_exp_f32_e32 v84, v84
	v_or_b32_e32 v82, 48, v139
	v_mad_i64_i32 v[82:83], s[6:7], v82, s74, v[134:135]
	v_add_f32_e32 v84, 1.0, v84
	v_rcp_f32_e32 v84, v84
	s_nop 0
	v_mul_f32_e32 v78, v78, v84
	v_mul_f32_e32 v74, v78, v74
	v_mul_f32_e32 v78, 0xbfb8aa3b, v79
	v_exp_f32_e32 v78, v78
	s_nop 0
	v_add_f32_e32 v78, 1.0, v78
	v_rcp_f32_e32 v78, v78
	s_nop 0
	v_mul_f32_e32 v78, v79, v78
	v_mul_f32_e32 v75, v78, v75
	v_mul_f32_e32 v78, 0xbfb8aa3b, v80
	v_exp_f32_e32 v78, v78
	s_nop 0
	v_add_f32_e32 v78, 1.0, v78
	v_rcp_f32_e32 v78, v78
	s_nop 0
	v_mul_f32_e32 v78, v80, v78
	v_mul_f32_e32 v76, v78, v76
	v_mul_f32_e32 v78, 0xbfb8aa3b, v81
	v_exp_f32_e32 v78, v78
	s_nop 0
	v_add_f32_e32 v78, 1.0, v78
	v_rcp_f32_e32 v78, v78
	s_nop 0
	v_mul_f32_e32 v78, v81, v78
	v_mul_f32_e32 v77, v78, v77
	v_mul_f32_e32 v78, 0xbfb8aa3b, v70
	v_exp_f32_e32 v78, v78
	s_nop 0
	v_add_f32_e32 v78, 1.0, v78
	v_rcp_f32_e32 v78, v78
	s_nop 0
	v_mul_f32_e32 v70, v70, v78
	v_mul_f32_e32 v78, v70, v66
	v_mul_f32_e32 v66, 0xbfb8aa3b, v71
	v_exp_f32_e32 v66, v66
	s_nop 0
	v_add_f32_e32 v66, 1.0, v66
	v_rcp_f32_e32 v66, v66
	s_nop 0
	v_mul_f32_e32 v66, v71, v66
	v_mul_f32_e32 v79, v66, v67
	v_mul_f32_e32 v66, 0xbfb8aa3b, v72
	v_exp_f32_e32 v66, v66
	v_lshl_add_u64 v[70:71], v[82:83], 0, v[114:115]
	v_add_f32_e32 v66, 1.0, v66
	v_rcp_f32_e32 v66, v66
	s_nop 0
	v_mul_f32_e32 v66, v72, v66
	v_mul_f32_e32 v72, v66, v68
	v_mul_f32_e32 v66, 0xbfb8aa3b, v73
	v_exp_f32_e32 v66, v66
	s_nop 0
	v_add_f32_e32 v66, 1.0, v66
	v_rcp_f32_e32 v66, v66
	s_nop 0
	v_mul_f32_e32 v66, v73, v66
	v_mul_f32_e32 v69, v66, v69
	v_cvt_pk_bf16_f32 v66, v74, v75
	v_cvt_pk_bf16_f32 v67, v76, v77
	v_cvt_pk_bf16_f32 v68, v78, v79
	v_cvt_pk_bf16_f32 v69, v72, v69
	global_store_dwordx4 v[70:71], v[66:69], off
	s_nop 1
	v_mul_f32_e32 v68, 0xbfb8aa3b, v62
	v_exp_f32_e32 v68, v68
	v_add_u32_e32 v66, 0x80, v139
	v_mad_i64_i32 v[66:67], s[6:7], v66, s74, v[134:135]
	v_add_f32_e32 v68, 1.0, v68
	v_rcp_f32_e32 v68, v68
	s_nop 0
	v_mul_f32_e32 v62, v62, v68
	v_mul_f32_e32 v58, v62, v58
	v_mul_f32_e32 v62, 0xbfb8aa3b, v63
	v_exp_f32_e32 v62, v62
	s_nop 0
	v_add_f32_e32 v62, 1.0, v62
	v_rcp_f32_e32 v62, v62
	s_nop 0
	v_mul_f32_e32 v62, v63, v62
	v_mul_f32_e32 v59, v62, v59
	v_mul_f32_e32 v62, 0xbfb8aa3b, v64
	v_exp_f32_e32 v62, v62
	s_nop 0
	v_add_f32_e32 v62, 1.0, v62
	v_rcp_f32_e32 v62, v62
	s_nop 0
	v_mul_f32_e32 v62, v64, v62
	v_mul_f32_e32 v60, v62, v60
	v_mul_f32_e32 v62, 0xbfb8aa3b, v65
	v_exp_f32_e32 v62, v62
	s_nop 0
	v_add_f32_e32 v62, 1.0, v62
	v_rcp_f32_e32 v62, v62
	s_nop 0
	v_mul_f32_e32 v62, v65, v62
	v_mul_f32_e32 v61, v62, v61
	v_mul_f32_e32 v62, 0xbfb8aa3b, v54
	v_exp_f32_e32 v62, v62
	s_nop 0
	v_add_f32_e32 v62, 1.0, v62
	v_rcp_f32_e32 v62, v62
	s_nop 0
	v_mul_f32_e32 v54, v54, v62
	v_mul_f32_e32 v62, v54, v50
	v_mul_f32_e32 v50, 0xbfb8aa3b, v55
	v_exp_f32_e32 v50, v50
	s_nop 0
	v_add_f32_e32 v50, 1.0, v50
	v_rcp_f32_e32 v50, v50
	s_nop 0
	v_mul_f32_e32 v50, v55, v50
	v_mul_f32_e32 v63, v50, v51
	v_mul_f32_e32 v50, 0xbfb8aa3b, v56
	v_exp_f32_e32 v50, v50
	v_lshl_add_u64 v[54:55], v[66:67], 0, v[114:115]
	v_add_f32_e32 v50, 1.0, v50
	v_rcp_f32_e32 v50, v50
	s_nop 0
	v_mul_f32_e32 v50, v56, v50
	v_mul_f32_e32 v56, v50, v52
	v_mul_f32_e32 v50, 0xbfb8aa3b, v57
	v_exp_f32_e32 v50, v50
	s_nop 0
	v_add_f32_e32 v50, 1.0, v50
	v_rcp_f32_e32 v50, v50
	s_nop 0
	v_mul_f32_e32 v50, v57, v50
	v_mul_f32_e32 v53, v50, v53
	v_cvt_pk_bf16_f32 v50, v58, v59
	v_cvt_pk_bf16_f32 v51, v60, v61
	v_cvt_pk_bf16_f32 v52, v62, v63
	v_cvt_pk_bf16_f32 v53, v56, v53
	global_store_dwordx4 v[54:55], v[50:53], off
	s_nop 1
	v_mul_f32_e32 v52, 0xbfb8aa3b, v46
	v_exp_f32_e32 v52, v52
	v_add_u32_e32 v50, 0x90, v139
	v_mad_i64_i32 v[50:51], s[6:7], v50, s74, v[134:135]
	v_add_f32_e32 v52, 1.0, v52
	v_rcp_f32_e32 v52, v52
	s_nop 0
	v_mul_f32_e32 v46, v46, v52
	v_mul_f32_e32 v42, v46, v42
	v_mul_f32_e32 v46, 0xbfb8aa3b, v47
	v_exp_f32_e32 v46, v46
	s_nop 0
	v_add_f32_e32 v46, 1.0, v46
	v_rcp_f32_e32 v46, v46
	s_nop 0
	v_mul_f32_e32 v46, v47, v46
	v_mul_f32_e32 v43, v46, v43
	v_mul_f32_e32 v46, 0xbfb8aa3b, v48
	v_exp_f32_e32 v46, v46
	s_nop 0
	v_add_f32_e32 v46, 1.0, v46
	v_rcp_f32_e32 v46, v46
	s_nop 0
	v_mul_f32_e32 v46, v48, v46
	v_mul_f32_e32 v44, v46, v44
	v_mul_f32_e32 v46, 0xbfb8aa3b, v49
	v_exp_f32_e32 v46, v46
	s_nop 0
	v_add_f32_e32 v46, 1.0, v46
	v_rcp_f32_e32 v46, v46
	s_nop 0
	v_mul_f32_e32 v46, v49, v46
	v_mul_f32_e32 v45, v46, v45
	v_mul_f32_e32 v46, 0xbfb8aa3b, v38
	v_exp_f32_e32 v46, v46
	s_nop 0
	v_add_f32_e32 v46, 1.0, v46
	v_rcp_f32_e32 v46, v46
	s_nop 0
	v_mul_f32_e32 v38, v38, v46
	v_mul_f32_e32 v46, v38, v34
	v_mul_f32_e32 v34, 0xbfb8aa3b, v39
	v_exp_f32_e32 v34, v34
	s_nop 0
	v_add_f32_e32 v34, 1.0, v34
	v_rcp_f32_e32 v34, v34
	s_nop 0
	v_mul_f32_e32 v34, v39, v34
	v_mul_f32_e32 v47, v34, v35
	v_mul_f32_e32 v34, 0xbfb8aa3b, v40
	v_exp_f32_e32 v34, v34
	v_lshl_add_u64 v[38:39], v[50:51], 0, v[114:115]
	v_add_f32_e32 v34, 1.0, v34
	v_rcp_f32_e32 v34, v34
	s_nop 0
	v_mul_f32_e32 v34, v40, v34
	v_mul_f32_e32 v40, v34, v36
	v_mul_f32_e32 v34, 0xbfb8aa3b, v41
	v_exp_f32_e32 v34, v34
	s_nop 0
	v_add_f32_e32 v34, 1.0, v34
	v_rcp_f32_e32 v34, v34
	s_nop 0
	v_mul_f32_e32 v34, v41, v34
	v_mul_f32_e32 v37, v34, v37
	v_cvt_pk_bf16_f32 v34, v42, v43
	v_cvt_pk_bf16_f32 v35, v44, v45
	v_cvt_pk_bf16_f32 v36, v46, v47
	v_cvt_pk_bf16_f32 v37, v40, v37
	global_store_dwordx4 v[38:39], v[34:37], off
	s_nop 1
	v_mul_f32_e32 v36, 0xbfb8aa3b, v30
	v_exp_f32_e32 v36, v36
	v_add_u32_e32 v34, 0xa0, v139
	v_mad_i64_i32 v[34:35], s[6:7], v34, s74, v[134:135]
	v_add_f32_e32 v36, 1.0, v36
	v_rcp_f32_e32 v36, v36
	s_nop 0
	v_mul_f32_e32 v30, v30, v36
	v_mul_f32_e32 v26, v30, v26
	v_mul_f32_e32 v30, 0xbfb8aa3b, v31
	v_exp_f32_e32 v30, v30
	s_nop 0
	v_add_f32_e32 v30, 1.0, v30
	v_rcp_f32_e32 v30, v30
	s_nop 0
	v_mul_f32_e32 v30, v31, v30
	v_mul_f32_e32 v27, v30, v27
	v_mul_f32_e32 v30, 0xbfb8aa3b, v32
	v_exp_f32_e32 v30, v30
	s_nop 0
	v_add_f32_e32 v30, 1.0, v30
	v_rcp_f32_e32 v30, v30
	s_nop 0
	v_mul_f32_e32 v30, v32, v30
	v_mul_f32_e32 v28, v30, v28
	v_mul_f32_e32 v30, 0xbfb8aa3b, v33
	v_exp_f32_e32 v30, v30
	s_nop 0
	v_add_f32_e32 v30, 1.0, v30
	v_rcp_f32_e32 v30, v30
	s_nop 0
	v_mul_f32_e32 v30, v33, v30
	v_mul_f32_e32 v29, v30, v29
	v_mul_f32_e32 v30, 0xbfb8aa3b, v22
	v_exp_f32_e32 v30, v30
	s_nop 0
	v_add_f32_e32 v30, 1.0, v30
	v_rcp_f32_e32 v30, v30
	s_nop 0
	v_mul_f32_e32 v22, v22, v30
	v_mul_f32_e32 v30, v22, v18
	v_mul_f32_e32 v18, 0xbfb8aa3b, v23
	v_exp_f32_e32 v18, v18
	s_nop 0
	v_add_f32_e32 v18, 1.0, v18
	v_rcp_f32_e32 v18, v18
	s_nop 0
	v_mul_f32_e32 v18, v23, v18
	v_mul_f32_e32 v31, v18, v19
	v_mul_f32_e32 v18, 0xbfb8aa3b, v24
	v_exp_f32_e32 v18, v18
	v_lshl_add_u64 v[22:23], v[34:35], 0, v[114:115]
	v_add_f32_e32 v18, 1.0, v18
	v_rcp_f32_e32 v18, v18
	s_nop 0
	v_mul_f32_e32 v18, v24, v18
	v_mul_f32_e32 v24, v18, v20
	v_mul_f32_e32 v18, 0xbfb8aa3b, v25
	v_exp_f32_e32 v18, v18
	s_nop 0
	v_add_f32_e32 v18, 1.0, v18
	v_rcp_f32_e32 v18, v18
	s_nop 0
	v_mul_f32_e32 v18, v25, v18
	v_mul_f32_e32 v21, v18, v21
	v_cvt_pk_bf16_f32 v18, v26, v27
	v_cvt_pk_bf16_f32 v19, v28, v29
	v_cvt_pk_bf16_f32 v20, v30, v31
	v_cvt_pk_bf16_f32 v21, v24, v21
	global_store_dwordx4 v[22:23], v[18:21], off
	s_nop 1
	v_mul_f32_e32 v20, 0xbfb8aa3b, v14
	v_exp_f32_e32 v20, v20
	v_add_u32_e32 v18, 0xb0, v139
	v_mad_i64_i32 v[18:19], s[6:7], v18, s74, v[134:135]
	v_add_f32_e32 v20, 1.0, v20
	v_rcp_f32_e32 v20, v20
	s_mov_b64 s[6:7], s[42:43]
	v_mul_f32_e32 v14, v14, v20
	v_mul_f32_e32 v10, v14, v10
	v_mul_f32_e32 v14, 0xbfb8aa3b, v15
	v_exp_f32_e32 v14, v14
	s_nop 0
	v_add_f32_e32 v14, 1.0, v14
	v_rcp_f32_e32 v14, v14
	s_nop 0
	v_mul_f32_e32 v14, v15, v14
	v_mul_f32_e32 v11, v14, v11
	v_mul_f32_e32 v14, 0xbfb8aa3b, v16
	v_exp_f32_e32 v14, v14
	s_nop 0
	v_add_f32_e32 v14, 1.0, v14
	v_rcp_f32_e32 v14, v14
	s_nop 0
	v_mul_f32_e32 v14, v16, v14
	v_mul_f32_e32 v12, v14, v12
	v_mul_f32_e32 v14, 0xbfb8aa3b, v17
	v_exp_f32_e32 v14, v14
	s_nop 0
	v_add_f32_e32 v14, 1.0, v14
	v_rcp_f32_e32 v14, v14
	s_nop 0
	v_mul_f32_e32 v14, v17, v14
	v_mul_f32_e32 v13, v14, v13
	v_mul_f32_e32 v14, 0xbfb8aa3b, v6
	v_exp_f32_e32 v14, v14
	s_nop 0
	v_add_f32_e32 v14, 1.0, v14
	v_rcp_f32_e32 v14, v14
	s_nop 0
	v_mul_f32_e32 v6, v6, v14
	v_mul_f32_e32 v14, v6, v2
	v_mul_f32_e32 v2, 0xbfb8aa3b, v7
	v_exp_f32_e32 v2, v2
	s_nop 0
	v_add_f32_e32 v2, 1.0, v2
	v_rcp_f32_e32 v2, v2
	s_nop 0
	v_mul_f32_e32 v2, v7, v2
	v_mul_f32_e32 v15, v2, v3
	v_mul_f32_e32 v2, 0xbfb8aa3b, v8
	v_exp_f32_e32 v2, v2
	v_lshl_add_u64 v[6:7], v[18:19], 0, v[114:115]
	v_add_f32_e32 v2, 1.0, v2
	v_rcp_f32_e32 v2, v2
	s_nop 0
	v_mul_f32_e32 v2, v8, v2
	v_mul_f32_e32 v8, v2, v4
	v_mul_f32_e32 v2, 0xbfb8aa3b, v9
	v_exp_f32_e32 v2, v2
	s_nop 0
	v_add_f32_e32 v2, 1.0, v2
	v_rcp_f32_e32 v2, v2
	s_nop 0
	v_mul_f32_e32 v2, v9, v2
	v_mul_f32_e32 v5, v2, v5
	v_cvt_pk_bf16_f32 v2, v10, v11
	v_cvt_pk_bf16_f32 v3, v12, v13
	v_cvt_pk_bf16_f32 v4, v14, v15
	v_cvt_pk_bf16_f32 v5, v8, v5
	global_store_dwordx4 v[6:7], v[2:5], off
	s_cbranch_vccz .LBB0_500
	s_waitcnt vmcnt(0)
	v_readlane_b32 s0, v255, 8
	v_readlane_b32 s62, v255, 10
	v_readlane_b32 s84, v255, 12
	s_cmpk_gt_u32 s22, 0xff
	v_readlane_b32 s1, v255, 9
	s_mov_b64 s[58:59], s[92:93]
	v_readlane_b32 s63, v255, 11
	v_readlane_b32 s85, v255, 13
	s_cbranch_scc1 .LBB0_507
	s_barrier

.LBB0_577:
	s_add_u32 s8, s8, 0x100
	s_addc_u32 s9, s9, 0
	s_add_u32 s40, s6, 0x80080
	v_mov_b32_e32 v2, 0
	s_mov_b64 vcc, 0x20000
	s_addc_u32 s41, s7, 0
	s_mov_b32 s6, -2
	v_mov_b32_e32 v3, v2
	v_mov_b32_e32 v4, v2
	v_mov_b32_e32 v5, v2
	v_mov_b32_e32 v6, v2
	v_mov_b32_e32 v7, v2
	v_mov_b32_e32 v8, v2
	v_mov_b32_e32 v9, v2
	v_mov_b32_e32 v10, v2
	v_mov_b32_e32 v11, v2
	v_mov_b32_e32 v12, v2
	v_mov_b32_e32 v13, v2
	v_mov_b32_e32 v18, v2
	v_mov_b32_e32 v19, v2
	v_mov_b32_e32 v20, v2
	v_mov_b32_e32 v21, v2
	v_mov_b32_e32 v26, v2
	v_mov_b32_e32 v27, v2
	v_mov_b32_e32 v28, v2
	v_mov_b32_e32 v29, v2
	v_mov_b32_e32 v34, v2
	v_mov_b32_e32 v35, v2
	v_mov_b32_e32 v36, v2
	v_mov_b32_e32 v37, v2
	v_mov_b32_e32 v42, v2
	v_mov_b32_e32 v43, v2
	v_mov_b32_e32 v44, v2
	v_mov_b32_e32 v45, v2
	v_mov_b32_e32 v50, v2
	v_mov_b32_e32 v51, v2
	v_mov_b32_e32 v52, v2
	v_mov_b32_e32 v53, v2
	v_mov_b32_e32 v14, v2
	v_mov_b32_e32 v15, v2
	v_mov_b32_e32 v16, v2
	v_mov_b32_e32 v17, v2
	v_mov_b32_e32 v22, v2
	v_mov_b32_e32 v23, v2
	v_mov_b32_e32 v24, v2
	v_mov_b32_e32 v25, v2
	v_mov_b32_e32 v30, v2
	v_mov_b32_e32 v31, v2
	v_mov_b32_e32 v32, v2
	v_mov_b32_e32 v33, v2
	v_mov_b32_e32 v38, v2
	v_mov_b32_e32 v39, v2
	v_mov_b32_e32 v40, v2
	v_mov_b32_e32 v41, v2
	v_mov_b32_e32 v46, v2
	v_mov_b32_e32 v47, v2
	v_mov_b32_e32 v48, v2
	v_mov_b32_e32 v49, v2
	v_mov_b32_e32 v54, v2
	v_mov_b32_e32 v55, v2
	v_mov_b32_e32 v56, v2
	v_mov_b32_e32 v57, v2
	v_mov_b32_e32 v58, v2
	v_mov_b32_e32 v59, v2
	v_mov_b32_e32 v60, v2
	v_mov_b32_e32 v61, v2
	v_mov_b32_e32 v62, v2
	v_mov_b32_e32 v63, v2
	v_mov_b32_e32 v64, v2
	v_mov_b32_e32 v65, v2
	v_mov_b32_e32 v66, v2
	v_mov_b32_e32 v67, v2
	v_mov_b32_e32 v68, v2
	v_mov_b32_e32 v69, v2
	v_mov_b32_e32 v70, v2
	v_mov_b32_e32 v71, v2
	v_mov_b32_e32 v72, v2
	v_mov_b32_e32 v73, v2
	v_mov_b32_e32 v74, v2
	v_mov_b32_e32 v75, v2
	v_mov_b32_e32 v76, v2
	v_mov_b32_e32 v77, v2
	v_mov_b32_e32 v82, v2
	v_mov_b32_e32 v83, v2
	v_mov_b32_e32 v84, v2
	v_mov_b32_e32 v85, v2
	v_mov_b32_e32 v90, v2
	v_mov_b32_e32 v91, v2
	v_mov_b32_e32 v92, v2
	v_mov_b32_e32 v93, v2
	v_mov_b32_e32 v98, v2
	v_mov_b32_e32 v99, v2
	v_mov_b32_e32 v100, v2
	v_mov_b32_e32 v101, v2
	v_mov_b32_e32 v106, v2
	v_mov_b32_e32 v107, v2
	v_mov_b32_e32 v108, v2
	v_mov_b32_e32 v109, v2
	v_mov_b32_e32 v118, v2
	v_mov_b32_e32 v119, v2
	v_mov_b32_e32 v120, v2
	v_mov_b32_e32 v121, v2
	v_mov_b32_e32 v78, v2
	v_mov_b32_e32 v79, v2
	v_mov_b32_e32 v80, v2
	v_mov_b32_e32 v81, v2
	v_mov_b32_e32 v86, v2
	v_mov_b32_e32 v87, v2
	v_mov_b32_e32 v88, v2
	v_mov_b32_e32 v89, v2
	v_mov_b32_e32 v94, v2
	v_mov_b32_e32 v95, v2
	v_mov_b32_e32 v96, v2
	v_mov_b32_e32 v97, v2
	v_mov_b32_e32 v102, v2
	v_mov_b32_e32 v103, v2
	v_mov_b32_e32 v104, v2
	v_mov_b32_e32 v105, v2
	v_mov_b32_e32 v110, v2
	v_mov_b32_e32 v111, v2
	v_mov_b32_e32 v112, v2
	v_mov_b32_e32 v113, v2
	v_mov_b32_e32 v114, v2
	v_mov_b32_e32 v115, v2
	v_mov_b32_e32 v116, v2
	v_mov_b32_e32 v117, v2
	v_mov_b32_e32 v122, v2
	v_mov_b32_e32 v123, v2
	v_mov_b32_e32 v124, v2
	v_mov_b32_e32 v125, v2
	v_mov_b32_e32 v126, v2
	v_mov_b32_e32 v127, v2
	v_mov_b32_e32 v128, v2
	v_mov_b32_e32 v129, v2
	s_mov_b64 s[78:79], 0x30000
	s_mov_b64 s[72:73], 0x20080
	s_mov_b64 s[38:39], 0x10080
	s_mov_b64 s[68:69], 0x10000
	s_mov_b64 s[56:57], 0x30080
	s_branch .Lrot_enter_2
.LBB0_578:
	s_setprio 1
	s_barrier
	v_mfma_f32_16x16x32_bf16 v[50:53], v[188:191], v[152:155], v[50:53]
	v_mfma_f32_16x16x32_bf16 v[42:45], v[196:199], v[152:155], v[42:45]
	v_mfma_f32_16x16x32_bf16 v[34:37], v[188:191], v[164:167], v[34:37]
	v_mfma_f32_16x16x32_bf16 v[26:29], v[196:199], v[164:167], v[26:29]
	v_mfma_f32_16x16x32_bf16 v[18:21], v[188:191], v[172:175], v[18:21]
	v_mfma_f32_16x16x32_bf16 v[10:13], v[196:199], v[172:175], v[10:13]
	v_mfma_f32_16x16x32_bf16 v[6:9], v[188:191], v[180:183], v[6:9]
	v_mfma_f32_16x16x32_bf16 v[2:5], v[196:199], v[180:183], v[2:5]
	v_mfma_f32_16x16x32_bf16 v[50:53], v[192:195], v[160:163], v[50:53]
	v_mfma_f32_16x16x32_bf16 v[42:45], v[200:203], v[160:163], v[42:45]
	v_mfma_f32_16x16x32_bf16 v[34:37], v[192:195], v[168:171], v[34:37]
	v_mfma_f32_16x16x32_bf16 v[26:29], v[200:203], v[168:171], v[26:29]
	v_mfma_f32_16x16x32_bf16 v[18:21], v[192:195], v[176:179], v[18:21]
	v_mfma_f32_16x16x32_bf16 v[10:13], v[200:203], v[176:179], v[10:13]
	v_mfma_f32_16x16x32_bf16 v[6:9], v[192:195], v[184:187], v[6:9]
	v_mfma_f32_16x16x32_bf16 v[2:5], v[200:203], v[184:187], v[2:5]
	s_barrier
	s_setprio 0
.Lrot_enter_2:
	s_add_u32 s7, s40, 0xfff80080
	s_addc_u32 s11, s41, -1
	s_add_i32 s49, 0, 0x10000
	v_add_u32_e32 v142, s49, v158
	ds_read_b128 v[130:133], v142
	ds_read_b128 v[134:137], v142 offset:1024
	ds_read_b128 v[138:141], v142 offset:2048
	ds_read_b128 v[142:145], v142 offset:3072
	s_cmp_eq_u32 s6, 4
	s_cselect_b32 s95, s51, s11
	s_cselect_b32 s94, s50, s7
	s_cselect_b32 s97, s53, s9
	s_cselect_b32 s96, s52, s8
	v_lshl_add_u64 v[156:157], s[40:41], 0, v[150:151]
	s_add_i32 m0, s55, 0xc000
	ds_read_b128 v[152:155], v159
	ds_read_b128 v[160:163], v159 offset:1024
	ds_read_b128 v[164:167], v159 offset:2048
	ds_read_b128 v[168:171], v159 offset:3072
	ds_read_b128 v[172:175], v159 offset:4096
	ds_read_b128 v[176:179], v159 offset:5120
	ds_read_b128 v[180:183], v159 offset:6144
	ds_read_b128 v[184:187], v159 offset:7168
	global_load_lds_dwordx4 v[156:157], off
	v_lshl_add_u64 v[156:157], v[156:157], 0, s[60:61]
	s_add_i32 m0, s55, 0xe000
	s_nop 0
	global_load_lds_dwordx4 v[156:157], off
	s_waitcnt lgkmcnt(8)
	s_setprio 1
	s_barrier
	s_waitcnt lgkmcnt(0)
	v_mfma_f32_16x16x32_bf16 v[126:129], v[130:133], v[152:155], v[126:129]
	v_mfma_f32_16x16x32_bf16 v[122:125], v[138:141], v[152:155], v[122:125]
	v_mfma_f32_16x16x32_bf16 v[114:117], v[130:133], v[164:167], v[114:117]
	v_mfma_f32_16x16x32_bf16 v[110:113], v[138:141], v[164:167], v[110:113]
	v_mfma_f32_16x16x32_bf16 v[102:105], v[130:133], v[172:175], v[102:105]
	v_mfma_f32_16x16x32_bf16 v[94:97], v[138:141], v[172:175], v[94:97]
	v_mfma_f32_16x16x32_bf16 v[86:89], v[130:133], v[180:183], v[86:89]
	v_mfma_f32_16x16x32_bf16 v[78:81], v[138:141], v[180:183], v[78:81]
	v_mfma_f32_16x16x32_bf16 v[126:129], v[134:137], v[160:163], v[126:129]
	v_mfma_f32_16x16x32_bf16 v[122:125], v[142:145], v[160:163], v[122:125]
	v_mfma_f32_16x16x32_bf16 v[114:117], v[134:137], v[168:171], v[114:117]
	v_mfma_f32_16x16x32_bf16 v[110:113], v[142:145], v[168:171], v[110:113]
	v_mfma_f32_16x16x32_bf16 v[102:105], v[134:137], v[176:179], v[102:105]
	v_mfma_f32_16x16x32_bf16 v[94:97], v[142:145], v[176:179], v[94:97]
	v_mfma_f32_16x16x32_bf16 v[86:89], v[134:137], v[184:187], v[86:89]
	v_mfma_f32_16x16x32_bf16 v[78:81], v[142:145], v[184:187], v[78:81]
	s_barrier
	s_setprio 0
	s_add_i32 s7, 0, 0x14000
	v_add_u32_e32 v156, s7, v158
	s_add_i32 s11, s49, s63
	ds_read_b128 v[188:191], v156
	ds_read_b128 v[192:195], v156 offset:1024
	ds_read_b128 v[196:199], v156 offset:2048
	ds_read_b128 v[200:203], v156 offset:3072
	v_lshl_add_u64 v[156:157], s[96:97], 0, v[0:1]
	s_mov_b32 m0, s11
	v_lshl_add_u64 v[204:205], v[156:157], 0, s[68:69]
	global_load_lds_dwordx4 v[156:157], off
	s_add_i32 m0, s11, 0x2000
	s_nop 0
	global_load_lds_dwordx4 v[204:205], off
	s_setprio 1
	s_barrier
	s_waitcnt lgkmcnt(0)
	v_mfma_f32_16x16x32_bf16 v[118:121], v[188:191], v[152:155], v[118:121]
	v_mfma_f32_16x16x32_bf16 v[106:109], v[196:199], v[152:155], v[106:109]
	v_mfma_f32_16x16x32_bf16 v[98:101], v[188:191], v[164:167], v[98:101]
	v_mfma_f32_16x16x32_bf16 v[90:93], v[196:199], v[164:167], v[90:93]
	v_mfma_f32_16x16x32_bf16 v[82:85], v[188:191], v[172:175], v[82:85]
	v_mfma_f32_16x16x32_bf16 v[74:77], v[196:199], v[172:175], v[74:77]
	v_mfma_f32_16x16x32_bf16 v[70:73], v[188:191], v[180:183], v[70:73]
	v_mfma_f32_16x16x32_bf16 v[66:69], v[196:199], v[180:183], v[66:69]
	v_mfma_f32_16x16x32_bf16 v[118:121], v[192:195], v[160:163], v[118:121]
	v_mfma_f32_16x16x32_bf16 v[106:109], v[200:203], v[160:163], v[106:109]
	v_mfma_f32_16x16x32_bf16 v[98:101], v[192:195], v[168:171], v[98:101]
	v_mfma_f32_16x16x32_bf16 v[90:93], v[200:203], v[168:171], v[90:93]
	v_mfma_f32_16x16x32_bf16 v[82:85], v[192:195], v[176:179], v[82:85]
	v_mfma_f32_16x16x32_bf16 v[74:77], v[200:203], v[176:179], v[74:77]
	v_mfma_f32_16x16x32_bf16 v[70:73], v[192:195], v[184:187], v[70:73]
	v_mfma_f32_16x16x32_bf16 v[66:69], v[200:203], v[184:187], v[66:69]
	s_barrier
	s_setprio 0
	s_mov_b32 m0, s55
	v_lshl_add_u64 v[204:205], s[94:95], 0, v[148:149]
	ds_read_b128 v[152:155], v159 offset:16384
	ds_read_b128 v[160:163], v159 offset:17408
	ds_read_b128 v[164:167], v159 offset:18432
	ds_read_b128 v[168:171], v159 offset:19456
	ds_read_b128 v[172:175], v159 offset:20480
	ds_read_b128 v[176:179], v159 offset:21504
	ds_read_b128 v[180:183], v159 offset:22528
	ds_read_b128 v[184:187], v159 offset:23552
	global_load_lds_dwordx4 v[204:205], off
	v_lshl_add_u64 v[206:207], v[204:205], 0, s[60:61]
	s_mov_b32 m0, s84
	s_nop 0
	global_load_lds_dwordx4 v[206:207], off
	s_setprio 1
	s_barrier
	s_waitcnt lgkmcnt(0)
	v_mfma_f32_16x16x32_bf16 v[62:65], v[130:133], v[152:155], v[62:65]
	v_mfma_f32_16x16x32_bf16 v[58:61], v[138:141], v[152:155], v[58:61]
	v_mfma_f32_16x16x32_bf16 v[54:57], v[130:133], v[164:167], v[54:57]
	v_mfma_f32_16x16x32_bf16 v[46:49], v[138:141], v[164:167], v[46:49]
	v_mfma_f32_16x16x32_bf16 v[38:41], v[130:133], v[172:175], v[38:41]
	v_mfma_f32_16x16x32_bf16 v[30:33], v[138:141], v[172:175], v[30:33]
	v_mfma_f32_16x16x32_bf16 v[22:25], v[130:133], v[180:183], v[22:25]
	v_mfma_f32_16x16x32_bf16 v[14:17], v[138:141], v[180:183], v[14:17]
	v_mfma_f32_16x16x32_bf16 v[62:65], v[134:137], v[160:163], v[62:65]
	v_mfma_f32_16x16x32_bf16 v[58:61], v[142:145], v[160:163], v[58:61]
	v_mfma_f32_16x16x32_bf16 v[54:57], v[134:137], v[168:171], v[54:57]
	v_mfma_f32_16x16x32_bf16 v[46:49], v[142:145], v[168:171], v[46:49]
	v_mfma_f32_16x16x32_bf16 v[38:41], v[134:137], v[176:179], v[38:41]
	v_mfma_f32_16x16x32_bf16 v[30:33], v[142:145], v[176:179], v[30:33]
	v_mfma_f32_16x16x32_bf16 v[22:25], v[134:137], v[184:187], v[22:25]
	v_mfma_f32_16x16x32_bf16 v[14:17], v[142:145], v[184:187], v[14:17]
	s_barrier
	s_setprio 0
	s_add_i32 s7, s7, s63
	v_lshl_add_u64 v[130:131], v[156:157], 0, vcc
	s_mov_b32 m0, s7
	s_nop 0
	global_load_lds_dwordx4 v[130:131], off
	v_lshl_add_u64 v[130:131], v[156:157], 0, s[78:79]
	s_add_i32 m0, s7, 0x2000
	s_nop 0
	global_load_lds_dwordx4 v[130:131], off
	v_lshl_add_u64 v[230:231], v[204:205], 0, s[20:21]
	s_mov_b32 m0, s85
	s_nop 0
	global_load_lds_dwordx4 v[230:231], off
	v_lshl_add_u64 v[230:231], v[204:205], 0, s[64:65]
	s_mov_b32 m0, s86
	s_nop 0
	global_load_lds_dwordx4 v[230:231], off
	s_waitcnt vmcnt(8)
	s_setprio 1
	s_barrier
	v_mfma_f32_16x16x32_bf16 v[50:53], v[188:191], v[152:155], v[50:53]
	v_mfma_f32_16x16x32_bf16 v[42:45], v[196:199], v[152:155], v[42:45]
	v_mfma_f32_16x16x32_bf16 v[34:37], v[188:191], v[164:167], v[34:37]
	v_mfma_f32_16x16x32_bf16 v[26:29], v[196:199], v[164:167], v[26:29]
	v_mfma_f32_16x16x32_bf16 v[18:21], v[188:191], v[172:175], v[18:21]
	v_mfma_f32_16x16x32_bf16 v[10:13], v[196:199], v[172:175], v[10:13]
	v_mfma_f32_16x16x32_bf16 v[6:9], v[188:191], v[180:183], v[6:9]
	v_mfma_f32_16x16x32_bf16 v[2:5], v[196:199], v[180:183], v[2:5]
	v_mfma_f32_16x16x32_bf16 v[50:53], v[192:195], v[160:163], v[50:53]
	v_mfma_f32_16x16x32_bf16 v[42:45], v[200:203], v[160:163], v[42:45]
	v_mfma_f32_16x16x32_bf16 v[34:37], v[192:195], v[168:171], v[34:37]
	v_mfma_f32_16x16x32_bf16 v[26:29], v[200:203], v[168:171], v[26:29]
	v_mfma_f32_16x16x32_bf16 v[18:21], v[192:195], v[176:179], v[18:21]
	v_mfma_f32_16x16x32_bf16 v[10:13], v[200:203], v[176:179], v[10:13]
	v_mfma_f32_16x16x32_bf16 v[6:9], v[192:195], v[184:187], v[6:9]
	v_mfma_f32_16x16x32_bf16 v[2:5], v[200:203], v[184:187], v[2:5]
	s_barrier
	s_setprio 0
	s_add_i32 s7, 0, 0x18000
	v_add_u32_e32 v142, s7, v158
	ds_read_b128 v[130:133], v142
	ds_read_b128 v[134:137], v142 offset:1024
	ds_read_b128 v[138:141], v142 offset:2048
	ds_read_b128 v[142:145], v142 offset:3072
	ds_read_b128 v[152:155], v159 offset:32768
	ds_read_b128 v[160:163], v159 offset:33792
	ds_read_b128 v[164:167], v159 offset:34816
	ds_read_b128 v[168:171], v159 offset:35840
	ds_read_b128 v[172:175], v159 offset:36864
	ds_read_b128 v[176:179], v159 offset:37888
	ds_read_b128 v[180:183], v159 offset:38912
	ds_read_b128 v[184:187], v159 offset:39936
	s_waitcnt lgkmcnt(8)
	s_setprio 1
	s_barrier
	s_waitcnt lgkmcnt(0)
	v_mfma_f32_16x16x32_bf16 v[126:129], v[130:133], v[152:155], v[126:129]
	v_mfma_f32_16x16x32_bf16 v[122:125], v[138:141], v[152:155], v[122:125]
	v_mfma_f32_16x16x32_bf16 v[114:117], v[130:133], v[164:167], v[114:117]
	v_mfma_f32_16x16x32_bf16 v[110:113], v[138:141], v[164:167], v[110:113]
	v_mfma_f32_16x16x32_bf16 v[102:105], v[130:133], v[172:175], v[102:105]
	v_mfma_f32_16x16x32_bf16 v[94:97], v[138:141], v[172:175], v[94:97]
	v_mfma_f32_16x16x32_bf16 v[86:89], v[130:133], v[180:183], v[86:89]
	v_mfma_f32_16x16x32_bf16 v[78:81], v[138:141], v[180:183], v[78:81]
	v_mfma_f32_16x16x32_bf16 v[126:129], v[134:137], v[160:163], v[126:129]
	v_mfma_f32_16x16x32_bf16 v[122:125], v[142:145], v[160:163], v[122:125]
	v_mfma_f32_16x16x32_bf16 v[114:117], v[134:137], v[168:171], v[114:117]
	v_mfma_f32_16x16x32_bf16 v[110:113], v[142:145], v[168:171], v[110:113]
	v_mfma_f32_16x16x32_bf16 v[102:105], v[134:137], v[176:179], v[102:105]
	v_mfma_f32_16x16x32_bf16 v[94:97], v[142:145], v[176:179], v[94:97]
	v_mfma_f32_16x16x32_bf16 v[86:89], v[134:137], v[184:187], v[86:89]
	v_mfma_f32_16x16x32_bf16 v[78:81], v[142:145], v[184:187], v[78:81]
	s_barrier
	s_setprio 0
	s_add_i32 s11, 0, 0x1c000
	s_add_i32 s7, s7, s63
	v_add_u32_e32 v200, s11, v158
	v_lshl_add_u64 v[206:207], v[156:157], 0, s[34:35]
	s_mov_b32 m0, s7
	ds_read_b128 v[188:191], v200
	ds_read_b128 v[192:195], v200 offset:1024
	ds_read_b128 v[196:199], v200 offset:2048
	ds_read_b128 v[200:203], v200 offset:3072
	global_load_lds_dwordx4 v[206:207], off
	v_lshl_add_u64 v[206:207], v[156:157], 0, s[38:39]
	s_add_i32 m0, s7, 0x2000
	s_nop 0
	global_load_lds_dwordx4 v[206:207], off
	s_setprio 1
	s_barrier
	s_waitcnt lgkmcnt(0)
	v_mfma_f32_16x16x32_bf16 v[118:121], v[188:191], v[152:155], v[118:121]
	v_mfma_f32_16x16x32_bf16 v[106:109], v[196:199], v[152:155], v[106:109]
	v_mfma_f32_16x16x32_bf16 v[98:101], v[188:191], v[164:167], v[98:101]
	v_mfma_f32_16x16x32_bf16 v[90:93], v[196:199], v[164:167], v[90:93]
	v_mfma_f32_16x16x32_bf16 v[82:85], v[188:191], v[172:175], v[82:85]
	v_mfma_f32_16x16x32_bf16 v[74:77], v[196:199], v[172:175], v[74:77]
	v_mfma_f32_16x16x32_bf16 v[70:73], v[188:191], v[180:183], v[70:73]
	v_mfma_f32_16x16x32_bf16 v[66:69], v[196:199], v[180:183], v[66:69]
	v_mfma_f32_16x16x32_bf16 v[118:121], v[192:195], v[160:163], v[118:121]
	v_mfma_f32_16x16x32_bf16 v[106:109], v[200:203], v[160:163], v[106:109]
	v_mfma_f32_16x16x32_bf16 v[98:101], v[192:195], v[168:171], v[98:101]
	v_mfma_f32_16x16x32_bf16 v[90:93], v[200:203], v[168:171], v[90:93]
	v_mfma_f32_16x16x32_bf16 v[82:85], v[192:195], v[176:179], v[82:85]
	v_mfma_f32_16x16x32_bf16 v[74:77], v[200:203], v[176:179], v[74:77]
	v_mfma_f32_16x16x32_bf16 v[70:73], v[192:195], v[184:187], v[70:73]
	v_mfma_f32_16x16x32_bf16 v[66:69], v[200:203], v[184:187], v[66:69]
	s_barrier
	s_setprio 0
	s_mov_b32 m0, s89
	v_lshl_add_u64 v[206:207], v[204:205], 0, s[34:35]
	ds_read_b128 v[152:155], v159 offset:49152
	ds_read_b128 v[160:163], v159 offset:50176
	ds_read_b128 v[164:167], v159 offset:51200
	ds_read_b128 v[168:171], v159 offset:52224
	ds_read_b128 v[172:175], v159 offset:53248
	ds_read_b128 v[176:179], v159 offset:54272
	ds_read_b128 v[180:183], v159 offset:55296
	ds_read_b128 v[184:187], v159 offset:56320
	global_load_lds_dwordx4 v[206:207], off
	v_lshl_add_u64 v[204:205], v[204:205], 0, s[66:67]
	s_mov_b32 m0, s90
	s_nop 0
	global_load_lds_dwordx4 v[204:205], off
	s_setprio 1
	s_barrier
	s_waitcnt lgkmcnt(0)
	v_mfma_f32_16x16x32_bf16 v[62:65], v[130:133], v[152:155], v[62:65]
	v_mfma_f32_16x16x32_bf16 v[58:61], v[138:141], v[152:155], v[58:61]
	v_mfma_f32_16x16x32_bf16 v[54:57], v[130:133], v[164:167], v[54:57]
	v_mfma_f32_16x16x32_bf16 v[46:49], v[138:141], v[164:167], v[46:49]
	v_mfma_f32_16x16x32_bf16 v[38:41], v[130:133], v[172:175], v[38:41]
	v_mfma_f32_16x16x32_bf16 v[30:33], v[138:141], v[172:175], v[30:33]
	v_mfma_f32_16x16x32_bf16 v[22:25], v[130:133], v[180:183], v[22:25]
	v_mfma_f32_16x16x32_bf16 v[14:17], v[138:141], v[180:183], v[14:17]
	v_mfma_f32_16x16x32_bf16 v[62:65], v[134:137], v[160:163], v[62:65]
	v_mfma_f32_16x16x32_bf16 v[58:61], v[142:145], v[160:163], v[58:61]
	v_mfma_f32_16x16x32_bf16 v[54:57], v[134:137], v[168:171], v[54:57]
	v_mfma_f32_16x16x32_bf16 v[46:49], v[142:145], v[168:171], v[46:49]
	v_mfma_f32_16x16x32_bf16 v[38:41], v[134:137], v[176:179], v[38:41]
	v_mfma_f32_16x16x32_bf16 v[30:33], v[142:145], v[176:179], v[30:33]
	v_mfma_f32_16x16x32_bf16 v[22:25], v[134:137], v[184:187], v[22:25]
	v_mfma_f32_16x16x32_bf16 v[14:17], v[142:145], v[184:187], v[14:17]
	s_barrier
	s_setprio 0
	s_add_i32 s7, s11, s63
	v_lshl_add_u64 v[130:131], v[156:157], 0, s[72:73]
	s_mov_b32 m0, s7
	s_nop 0
	global_load_lds_dwordx4 v[130:131], off
	v_lshl_add_u64 v[130:131], v[156:157], 0, s[56:57]
	s_add_i32 m0, s7, 0x2000
	s_nop 0
	global_load_lds_dwordx4 v[130:131], off
	s_waitcnt vmcnt(6)
	s_add_i32 s6, s6, 2
	s_add_u32 s8, s8, 0x100
	s_addc_u32 s9, s9, 0
	s_add_u32 s40, s40, 0x100
	s_addc_u32 s41, s41, 0
	s_cmp_gt_u32 s6, 5
	s_cbranch_scc0 .LBB0_578
	s_setprio 1
	s_barrier
	v_mfma_f32_16x16x32_bf16 v[50:53], v[188:191], v[152:155], v[50:53]
	v_mfma_f32_16x16x32_bf16 v[42:45], v[196:199], v[152:155], v[42:45]
	v_mfma_f32_16x16x32_bf16 v[34:37], v[188:191], v[164:167], v[34:37]
	v_mfma_f32_16x16x32_bf16 v[26:29], v[196:199], v[164:167], v[26:29]
	v_mfma_f32_16x16x32_bf16 v[18:21], v[188:191], v[172:175], v[18:21]
	v_mfma_f32_16x16x32_bf16 v[10:13], v[196:199], v[172:175], v[10:13]
	v_mfma_f32_16x16x32_bf16 v[6:9], v[188:191], v[180:183], v[6:9]
	v_mfma_f32_16x16x32_bf16 v[2:5], v[196:199], v[180:183], v[2:5]
	v_mfma_f32_16x16x32_bf16 v[50:53], v[192:195], v[160:163], v[50:53]
	v_mfma_f32_16x16x32_bf16 v[42:45], v[200:203], v[160:163], v[42:45]
	v_mfma_f32_16x16x32_bf16 v[34:37], v[192:195], v[168:171], v[34:37]
	v_mfma_f32_16x16x32_bf16 v[26:29], v[200:203], v[168:171], v[26:29]
	v_mfma_f32_16x16x32_bf16 v[18:21], v[192:195], v[176:179], v[18:21]
	v_mfma_f32_16x16x32_bf16 v[10:13], v[200:203], v[176:179], v[10:13]
	v_mfma_f32_16x16x32_bf16 v[6:9], v[192:195], v[184:187], v[6:9]
	v_mfma_f32_16x16x32_bf16 v[2:5], v[200:203], v[184:187], v[2:5]
	s_barrier
	s_setprio 0
	v_mov_b32_e32 v156, v146
	s_lshl_b32 s6, s92, 8
	v_ashrrev_i32_e32 v130, 2, v156
	s_or_b32 s6, s6, s88
	v_and_b32_e32 v130, -4, v130
	v_add_u32_e32 v152, s6, v130
	v_ashrrev_i32_e32 v153, 31, v152
	v_cndmask_b32_e64 v131, 0, 1, s[44:45]
	v_lshl_add_u64 v[154:155], v[152:153], 2, s[42:43]
	v_mov_b32_e32 v130, 1.0
	v_cmp_ne_u32_e64 s[40:41], 1, v131
	s_andn2_b64 vcc, exec, s[44:45]
	v_mov_b32_e32 v134, 1.0
	v_mov_b32_e32 v135, 1.0
	v_mov_b32_e32 v136, 1.0
	v_mov_b32_e32 v137, 1.0
	s_cbranch_vccnz .LBB0_581
	global_load_dwordx4 v[134:137], v[154:155], off

.LBB0_678:
	s_add_u32 s8, s8, 0x100
	s_addc_u32 s9, s9, 0
	s_add_u32 s48, s6, 0x160080
	v_mov_b32_e32 v2, 0
	s_addc_u32 s49, s7, 0
	s_mov_b32 s6, -2
	v_mov_b32_e32 v3, v2
	v_mov_b32_e32 v4, v2
	v_mov_b32_e32 v5, v2
	v_mov_b32_e32 v6, v2
	v_mov_b32_e32 v7, v2
	v_mov_b32_e32 v8, v2
	v_mov_b32_e32 v9, v2
	v_mov_b32_e32 v10, v2
	v_mov_b32_e32 v11, v2
	v_mov_b32_e32 v12, v2
	v_mov_b32_e32 v13, v2
	v_mov_b32_e32 v18, v2
	v_mov_b32_e32 v19, v2
	v_mov_b32_e32 v20, v2
	v_mov_b32_e32 v21, v2
	v_mov_b32_e32 v26, v2
	v_mov_b32_e32 v27, v2
	v_mov_b32_e32 v28, v2
	v_mov_b32_e32 v29, v2
	v_mov_b32_e32 v34, v2
	v_mov_b32_e32 v35, v2
	v_mov_b32_e32 v36, v2
	v_mov_b32_e32 v37, v2
	v_mov_b32_e32 v42, v2
	v_mov_b32_e32 v43, v2
	v_mov_b32_e32 v44, v2
	v_mov_b32_e32 v45, v2
	v_mov_b32_e32 v50, v2
	v_mov_b32_e32 v51, v2
	v_mov_b32_e32 v52, v2
	v_mov_b32_e32 v53, v2
	v_mov_b32_e32 v14, v2
	v_mov_b32_e32 v15, v2
	v_mov_b32_e32 v16, v2
	v_mov_b32_e32 v17, v2
	v_mov_b32_e32 v22, v2
	v_mov_b32_e32 v23, v2
	v_mov_b32_e32 v24, v2
	v_mov_b32_e32 v25, v2
	v_mov_b32_e32 v30, v2
	v_mov_b32_e32 v31, v2
	v_mov_b32_e32 v32, v2
	v_mov_b32_e32 v33, v2
	v_mov_b32_e32 v38, v2
	v_mov_b32_e32 v39, v2
	v_mov_b32_e32 v40, v2
	v_mov_b32_e32 v41, v2
	v_mov_b32_e32 v46, v2
	v_mov_b32_e32 v47, v2
	v_mov_b32_e32 v48, v2
	v_mov_b32_e32 v49, v2
	v_mov_b32_e32 v54, v2
	v_mov_b32_e32 v55, v2
	v_mov_b32_e32 v56, v2
	v_mov_b32_e32 v57, v2
	v_mov_b32_e32 v58, v2
	v_mov_b32_e32 v59, v2
	v_mov_b32_e32 v60, v2
	v_mov_b32_e32 v61, v2
	v_mov_b32_e32 v62, v2
	v_mov_b32_e32 v63, v2
	v_mov_b32_e32 v64, v2
	v_mov_b32_e32 v65, v2
	v_mov_b32_e32 v66, v2
	v_mov_b32_e32 v67, v2
	v_mov_b32_e32 v68, v2
	v_mov_b32_e32 v69, v2
	v_mov_b32_e32 v70, v2
	v_mov_b32_e32 v71, v2
	v_mov_b32_e32 v72, v2
	v_mov_b32_e32 v73, v2
	v_mov_b32_e32 v74, v2
	v_mov_b32_e32 v75, v2
	v_mov_b32_e32 v76, v2
	v_mov_b32_e32 v77, v2
	v_mov_b32_e32 v82, v2
	v_mov_b32_e32 v83, v2
	v_mov_b32_e32 v84, v2
	v_mov_b32_e32 v85, v2
	v_mov_b32_e32 v90, v2
	v_mov_b32_e32 v91, v2
	v_mov_b32_e32 v92, v2
	v_mov_b32_e32 v93, v2
	v_mov_b32_e32 v98, v2
	v_mov_b32_e32 v99, v2
	v_mov_b32_e32 v100, v2
	v_mov_b32_e32 v101, v2
	v_mov_b32_e32 v106, v2
	v_mov_b32_e32 v107, v2
	v_mov_b32_e32 v108, v2
	v_mov_b32_e32 v109, v2
	v_mov_b32_e32 v114, v2
	v_mov_b32_e32 v115, v2
	v_mov_b32_e32 v116, v2
	v_mov_b32_e32 v117, v2
	v_mov_b32_e32 v78, v2
	v_mov_b32_e32 v79, v2
	v_mov_b32_e32 v80, v2
	v_mov_b32_e32 v81, v2
	v_mov_b32_e32 v86, v2
	v_mov_b32_e32 v87, v2
	v_mov_b32_e32 v88, v2
	v_mov_b32_e32 v89, v2
	v_mov_b32_e32 v94, v2
	v_mov_b32_e32 v95, v2
	v_mov_b32_e32 v96, v2
	v_mov_b32_e32 v97, v2
	v_mov_b32_e32 v102, v2
	v_mov_b32_e32 v103, v2
	v_mov_b32_e32 v104, v2
	v_mov_b32_e32 v105, v2
	v_mov_b32_e32 v110, v2
	v_mov_b32_e32 v111, v2
	v_mov_b32_e32 v112, v2
	v_mov_b32_e32 v113, v2
	v_mov_b32_e32 v118, v2
	v_mov_b32_e32 v119, v2
	v_mov_b32_e32 v120, v2
	v_mov_b32_e32 v121, v2
	v_mov_b32_e32 v122, v2
	v_mov_b32_e32 v123, v2
	v_mov_b32_e32 v124, v2
	v_mov_b32_e32 v125, v2
	v_mov_b32_e32 v126, v2
	v_mov_b32_e32 v127, v2
	v_mov_b32_e32 v128, v2
	v_mov_b32_e32 v129, v2
	s_branch .Lrot_enter_1

.Lrot_enter_1:
	s_add_u32 s7, s48, 0xffea0080
	s_addc_u32 s78, s49, -1
	s_add_i32 s79, 0, 0x10000
	v_add_u32_e32 v132, s79, v135
	ds_read_b128 v[138:141], v132
	ds_read_b128 v[142:145], v132 offset:1024
	ds_read_b128 v[148:151], v132 offset:2048
	ds_read_b128 v[152:155], v132 offset:3072
	s_cmpk_eq_i32 s6, 0x54
	s_cselect_b32 s91, s45, s78
	s_cselect_b32 s90, s44, s7
	s_cselect_b32 s93, s47, s9
	s_cselect_b32 s92, s46, s8
	v_lshl_add_u64 v[132:133], s[48:49], 0, v[130:131]
	s_add_i32 m0, s56, 0xc000
	ds_read_b128 v[156:159], v136
	ds_read_b128 v[160:163], v136 offset:1024
	ds_read_b128 v[164:167], v136 offset:2048
	ds_read_b128 v[168:171], v136 offset:3072
	ds_read_b128 v[172:175], v136 offset:4096
	ds_read_b128 v[176:179], v136 offset:5120
	ds_read_b128 v[180:183], v136 offset:6144
	ds_read_b128 v[184:187], v136 offset:7168
	global_load_lds_dwordx4 v[132:133], off
	v_lshl_add_u64 v[132:133], v[132:133], 0, s[26:27]
	s_add_i32 m0, s56, 0xe000
	s_nop 0
	global_load_lds_dwordx4 v[132:133], off
	s_waitcnt lgkmcnt(8)
	s_setprio 1
	s_barrier
	s_waitcnt lgkmcnt(0)
	v_mfma_f32_16x16x32_bf16 v[126:129], v[138:141], v[156:159], v[126:129]
	v_mfma_f32_16x16x32_bf16 v[122:125], v[148:151], v[156:159], v[122:125]
	v_mfma_f32_16x16x32_bf16 v[118:121], v[138:141], v[164:167], v[118:121]
	v_mfma_f32_16x16x32_bf16 v[110:113], v[148:151], v[164:167], v[110:113]
	v_mfma_f32_16x16x32_bf16 v[102:105], v[138:141], v[172:175], v[102:105]
	v_mfma_f32_16x16x32_bf16 v[94:97], v[148:151], v[172:175], v[94:97]
	v_mfma_f32_16x16x32_bf16 v[86:89], v[138:141], v[180:183], v[86:89]
	v_mfma_f32_16x16x32_bf16 v[78:81], v[148:151], v[180:183], v[78:81]
	v_mfma_f32_16x16x32_bf16 v[126:129], v[142:145], v[160:163], v[126:129]
	v_mfma_f32_16x16x32_bf16 v[122:125], v[152:155], v[160:163], v[122:125]
	v_mfma_f32_16x16x32_bf16 v[118:121], v[142:145], v[168:171], v[118:121]
	v_mfma_f32_16x16x32_bf16 v[110:113], v[152:155], v[168:171], v[110:113]
	v_mfma_f32_16x16x32_bf16 v[102:105], v[142:145], v[176:179], v[102:105]
	v_mfma_f32_16x16x32_bf16 v[94:97], v[152:155], v[176:179], v[94:97]
	v_mfma_f32_16x16x32_bf16 v[86:89], v[142:145], v[184:187], v[86:89]
	v_mfma_f32_16x16x32_bf16 v[78:81], v[152:155], v[184:187], v[78:81]
	s_barrier
	s_setprio 0
	s_add_i32 s7, 0, 0x14000
	v_add_u32_e32 v132, s7, v135
	s_add_i32 s78, s79, s55
	ds_read_b128 v[188:191], v132
	ds_read_b128 v[192:195], v132 offset:1024
	ds_read_b128 v[196:199], v132 offset:2048
	ds_read_b128 v[200:203], v132 offset:3072
	v_lshl_add_u64 v[132:133], s[92:93], 0, v[0:1]
	s_mov_b32 m0, s78
	v_lshl_add_u64 v[204:205], v[132:133], 0, s[26:27]
	global_load_lds_dwordx4 v[132:133], off
	s_add_i32 m0, s78, 0x2000
	s_nop 0
	global_load_lds_dwordx4 v[204:205], off
	s_setprio 1
	s_barrier
	s_waitcnt lgkmcnt(0)
	v_mfma_f32_16x16x32_bf16 v[114:117], v[188:191], v[156:159], v[114:117]
	v_mfma_f32_16x16x32_bf16 v[106:109], v[196:199], v[156:159], v[106:109]
	v_mfma_f32_16x16x32_bf16 v[98:101], v[188:191], v[164:167], v[98:101]
	v_mfma_f32_16x16x32_bf16 v[90:93], v[196:199], v[164:167], v[90:93]
	v_mfma_f32_16x16x32_bf16 v[82:85], v[188:191], v[172:175], v[82:85]
	v_mfma_f32_16x16x32_bf16 v[74:77], v[196:199], v[172:175], v[74:77]
	v_mfma_f32_16x16x32_bf16 v[70:73], v[188:191], v[180:183], v[70:73]
	v_mfma_f32_16x16x32_bf16 v[66:69], v[196:199], v[180:183], v[66:69]
	v_mfma_f32_16x16x32_bf16 v[114:117], v[192:195], v[160:163], v[114:117]
	v_mfma_f32_16x16x32_bf16 v[106:109], v[200:203], v[160:163], v[106:109]
	v_mfma_f32_16x16x32_bf16 v[98:101], v[192:195], v[168:171], v[98:101]
	v_mfma_f32_16x16x32_bf16 v[90:93], v[200:203], v[168:171], v[90:93]
	v_mfma_f32_16x16x32_bf16 v[82:85], v[192:195], v[176:179], v[82:85]
	v_mfma_f32_16x16x32_bf16 v[74:77], v[200:203], v[176:179], v[74:77]
	v_mfma_f32_16x16x32_bf16 v[70:73], v[192:195], v[184:187], v[70:73]
	v_mfma_f32_16x16x32_bf16 v[66:69], v[200:203], v[184:187], v[66:69]
	s_barrier
	s_setprio 0
	s_mov_b32 m0, s56
	v_lshl_add_u64 v[204:205], s[90:91], 0, v[0:1]
	ds_read_b128 v[156:159], v136 offset:16384
	ds_read_b128 v[160:163], v136 offset:17408
	ds_read_b128 v[164:167], v136 offset:18432
	ds_read_b128 v[168:171], v136 offset:19456
	ds_read_b128 v[172:175], v136 offset:20480
	ds_read_b128 v[176:179], v136 offset:21504
	ds_read_b128 v[180:183], v136 offset:22528
	ds_read_b128 v[184:187], v136 offset:23552
	global_load_lds_dwordx4 v[204:205], off
	v_lshl_add_u64 v[206:207], v[204:205], 0, s[26:27]
	s_mov_b32 m0, s57
	s_nop 0
	global_load_lds_dwordx4 v[206:207], off
	s_setprio 1
	s_barrier
	s_waitcnt lgkmcnt(0)
	v_mfma_f32_16x16x32_bf16 v[62:65], v[138:141], v[156:159], v[62:65]
	v_mfma_f32_16x16x32_bf16 v[58:61], v[148:151], v[156:159], v[58:61]
	v_mfma_f32_16x16x32_bf16 v[54:57], v[138:141], v[164:167], v[54:57]
	v_mfma_f32_16x16x32_bf16 v[46:49], v[148:151], v[164:167], v[46:49]
	v_mfma_f32_16x16x32_bf16 v[38:41], v[138:141], v[172:175], v[38:41]
	v_mfma_f32_16x16x32_bf16 v[30:33], v[148:151], v[172:175], v[30:33]
	v_mfma_f32_16x16x32_bf16 v[22:25], v[138:141], v[180:183], v[22:25]
	v_mfma_f32_16x16x32_bf16 v[14:17], v[148:151], v[180:183], v[14:17]
	v_mfma_f32_16x16x32_bf16 v[62:65], v[142:145], v[160:163], v[62:65]
	v_mfma_f32_16x16x32_bf16 v[58:61], v[152:155], v[160:163], v[58:61]
	v_mfma_f32_16x16x32_bf16 v[54:57], v[142:145], v[168:171], v[54:57]
	v_mfma_f32_16x16x32_bf16 v[46:49], v[152:155], v[168:171], v[46:49]
	v_mfma_f32_16x16x32_bf16 v[38:41], v[142:145], v[176:179], v[38:41]
	v_mfma_f32_16x16x32_bf16 v[30:33], v[152:155], v[176:179], v[30:33]
	v_mfma_f32_16x16x32_bf16 v[22:25], v[142:145], v[184:187], v[22:25]
	v_mfma_f32_16x16x32_bf16 v[14:17], v[152:155], v[184:187], v[14:17]
	s_barrier
	s_setprio 0
	s_add_i32 s7, s7, s55
	v_lshl_add_u64 v[138:139], v[132:133], 0, s[28:29]
	s_mov_b32 m0, s7
	s_nop 0
	global_load_lds_dwordx4 v[138:139], off
	v_lshl_add_u64 v[138:139], v[132:133], 0, s[30:31]
	s_add_i32 m0, s7, 0x2000
	s_nop 0
	global_load_lds_dwordx4 v[138:139], off
	v_lshl_add_u64 v[230:231], v[204:205], 0, s[28:29]
	s_mov_b32 m0, s58
	s_nop 0
	global_load_lds_dwordx4 v[230:231], off
	v_lshl_add_u64 v[230:231], v[204:205], 0, s[30:31]
	s_mov_b32 m0, s59
	s_nop 0
	global_load_lds_dwordx4 v[230:231], off
	s_waitcnt vmcnt(8)
	s_setprio 1
	s_barrier
	v_mfma_f32_16x16x32_bf16 v[50:53], v[188:191], v[156:159], v[50:53]
	v_mfma_f32_16x16x32_bf16 v[42:45], v[196:199], v[156:159], v[42:45]
	v_mfma_f32_16x16x32_bf16 v[34:37], v[188:191], v[164:167], v[34:37]
	v_mfma_f32_16x16x32_bf16 v[26:29], v[196:199], v[164:167], v[26:29]
	v_mfma_f32_16x16x32_bf16 v[18:21], v[188:191], v[172:175], v[18:21]
	v_mfma_f32_16x16x32_bf16 v[10:13], v[196:199], v[172:175], v[10:13]
	v_mfma_f32_16x16x32_bf16 v[6:9], v[188:191], v[180:183], v[6:9]
	v_mfma_f32_16x16x32_bf16 v[2:5], v[196:199], v[180:183], v[2:5]
	v_mfma_f32_16x16x32_bf16 v[50:53], v[192:195], v[160:163], v[50:53]
	v_mfma_f32_16x16x32_bf16 v[42:45], v[200:203], v[160:163], v[42:45]
	v_mfma_f32_16x16x32_bf16 v[34:37], v[192:195], v[168:171], v[34:37]
	v_mfma_f32_16x16x32_bf16 v[26:29], v[200:203], v[168:171], v[26:29]
	v_mfma_f32_16x16x32_bf16 v[18:21], v[192:195], v[176:179], v[18:21]
	v_mfma_f32_16x16x32_bf16 v[10:13], v[200:203], v[176:179], v[10:13]
	v_mfma_f32_16x16x32_bf16 v[6:9], v[192:195], v[184:187], v[6:9]
	v_mfma_f32_16x16x32_bf16 v[2:5], v[200:203], v[184:187], v[2:5]
	s_barrier
	s_setprio 0
	s_add_i32 s7, 0, 0x18000
	v_add_u32_e32 v137, s7, v135
	ds_read_b128 v[138:141], v137
	ds_read_b128 v[142:145], v137 offset:1024
	ds_read_b128 v[148:151], v137 offset:2048
	ds_read_b128 v[152:155], v137 offset:3072
	ds_read_b128 v[156:159], v136 offset:32768
	ds_read_b128 v[160:163], v136 offset:33792
	ds_read_b128 v[164:167], v136 offset:34816
	ds_read_b128 v[168:171], v136 offset:35840
	ds_read_b128 v[172:175], v136 offset:36864
	ds_read_b128 v[176:179], v136 offset:37888
	ds_read_b128 v[180:183], v136 offset:38912
	ds_read_b128 v[184:187], v136 offset:39936
	s_waitcnt lgkmcnt(8)
	s_setprio 1
	s_barrier
	s_waitcnt lgkmcnt(0)
	v_mfma_f32_16x16x32_bf16 v[126:129], v[138:141], v[156:159], v[126:129]
	v_mfma_f32_16x16x32_bf16 v[122:125], v[148:151], v[156:159], v[122:125]
	v_mfma_f32_16x16x32_bf16 v[118:121], v[138:141], v[164:167], v[118:121]
	v_mfma_f32_16x16x32_bf16 v[110:113], v[148:151], v[164:167], v[110:113]
	v_mfma_f32_16x16x32_bf16 v[102:105], v[138:141], v[172:175], v[102:105]
	v_mfma_f32_16x16x32_bf16 v[94:97], v[148:151], v[172:175], v[94:97]
	v_mfma_f32_16x16x32_bf16 v[86:89], v[138:141], v[180:183], v[86:89]
	v_mfma_f32_16x16x32_bf16 v[78:81], v[148:151], v[180:183], v[78:81]
	v_mfma_f32_16x16x32_bf16 v[126:129], v[142:145], v[160:163], v[126:129]
	v_mfma_f32_16x16x32_bf16 v[122:125], v[152:155], v[160:163], v[122:125]
	v_mfma_f32_16x16x32_bf16 v[118:121], v[142:145], v[168:171], v[118:121]
	v_mfma_f32_16x16x32_bf16 v[110:113], v[152:155], v[168:171], v[110:113]
	v_mfma_f32_16x16x32_bf16 v[102:105], v[142:145], v[176:179], v[102:105]
	v_mfma_f32_16x16x32_bf16 v[94:97], v[152:155], v[176:179], v[94:97]
	v_mfma_f32_16x16x32_bf16 v[86:89], v[142:145], v[184:187], v[86:89]
	v_mfma_f32_16x16x32_bf16 v[78:81], v[152:155], v[184:187], v[78:81]
	s_barrier
	s_setprio 0
	s_add_i32 s78, 0, 0x1c000
	s_add_i32 s7, s7, s55
	v_add_u32_e32 v137, s78, v135
	v_lshl_add_u64 v[206:207], v[132:133], 0, s[34:35]
	s_mov_b32 m0, s7
	ds_read_b128 v[188:191], v137
	ds_read_b128 v[192:195], v137 offset:1024
	ds_read_b128 v[196:199], v137 offset:2048
	ds_read_b128 v[200:203], v137 offset:3072
	global_load_lds_dwordx4 v[206:207], off
	v_lshl_add_u64 v[206:207], v[132:133], 0, s[36:37]
	s_add_i32 m0, s7, 0x2000
	s_nop 0
	global_load_lds_dwordx4 v[206:207], off
	s_setprio 1
	s_barrier
	s_waitcnt lgkmcnt(0)
	v_mfma_f32_16x16x32_bf16 v[114:117], v[188:191], v[156:159], v[114:117]
	v_mfma_f32_16x16x32_bf16 v[106:109], v[196:199], v[156:159], v[106:109]
	v_mfma_f32_16x16x32_bf16 v[98:101], v[188:191], v[164:167], v[98:101]
	v_mfma_f32_16x16x32_bf16 v[90:93], v[196:199], v[164:167], v[90:93]
	v_mfma_f32_16x16x32_bf16 v[82:85], v[188:191], v[172:175], v[82:85]
	v_mfma_f32_16x16x32_bf16 v[74:77], v[196:199], v[172:175], v[74:77]
	v_mfma_f32_16x16x32_bf16 v[70:73], v[188:191], v[180:183], v[70:73]
	v_mfma_f32_16x16x32_bf16 v[66:69], v[196:199], v[180:183], v[66:69]
	v_mfma_f32_16x16x32_bf16 v[114:117], v[192:195], v[160:163], v[114:117]
	v_mfma_f32_16x16x32_bf16 v[106:109], v[200:203], v[160:163], v[106:109]
	v_mfma_f32_16x16x32_bf16 v[98:101], v[192:195], v[168:171], v[98:101]
	v_mfma_f32_16x16x32_bf16 v[90:93], v[200:203], v[168:171], v[90:93]
	v_mfma_f32_16x16x32_bf16 v[82:85], v[192:195], v[176:179], v[82:85]
	v_mfma_f32_16x16x32_bf16 v[74:77], v[200:203], v[176:179], v[74:77]
	v_mfma_f32_16x16x32_bf16 v[70:73], v[192:195], v[184:187], v[70:73]
	v_mfma_f32_16x16x32_bf16 v[66:69], v[200:203], v[184:187], v[66:69]
	s_barrier
	s_setprio 0
	s_mov_b32 m0, s84
	v_lshl_add_u64 v[206:207], v[204:205], 0, s[34:35]
	ds_read_b128 v[156:159], v136 offset:49152
	ds_read_b128 v[160:163], v136 offset:50176
	ds_read_b128 v[164:167], v136 offset:51200
	ds_read_b128 v[168:171], v136 offset:52224
	ds_read_b128 v[172:175], v136 offset:53248
	ds_read_b128 v[176:179], v136 offset:54272
	ds_read_b128 v[180:183], v136 offset:55296
	ds_read_b128 v[184:187], v136 offset:56320
	global_load_lds_dwordx4 v[206:207], off
	v_lshl_add_u64 v[204:205], v[204:205], 0, s[36:37]
	s_mov_b32 m0, s85
	s_nop 0
	global_load_lds_dwordx4 v[204:205], off
	s_setprio 1
	s_barrier
	s_waitcnt lgkmcnt(0)
	v_mfma_f32_16x16x32_bf16 v[62:65], v[138:141], v[156:159], v[62:65]
	v_mfma_f32_16x16x32_bf16 v[58:61], v[148:151], v[156:159], v[58:61]
	v_mfma_f32_16x16x32_bf16 v[54:57], v[138:141], v[164:167], v[54:57]
	v_mfma_f32_16x16x32_bf16 v[46:49], v[148:151], v[164:167], v[46:49]
	v_mfma_f32_16x16x32_bf16 v[38:41], v[138:141], v[172:175], v[38:41]
	v_mfma_f32_16x16x32_bf16 v[30:33], v[148:151], v[172:175], v[30:33]
	v_mfma_f32_16x16x32_bf16 v[22:25], v[138:141], v[180:183], v[22:25]
	v_mfma_f32_16x16x32_bf16 v[14:17], v[148:151], v[180:183], v[14:17]
	v_mfma_f32_16x16x32_bf16 v[62:65], v[142:145], v[160:163], v[62:65]
	v_mfma_f32_16x16x32_bf16 v[58:61], v[152:155], v[160:163], v[58:61]
	v_mfma_f32_16x16x32_bf16 v[54:57], v[142:145], v[168:171], v[54:57]
	v_mfma_f32_16x16x32_bf16 v[46:49], v[152:155], v[168:171], v[46:49]
	v_mfma_f32_16x16x32_bf16 v[38:41], v[142:145], v[176:179], v[38:41]
	v_mfma_f32_16x16x32_bf16 v[30:33], v[152:155], v[176:179], v[30:33]
	v_mfma_f32_16x16x32_bf16 v[22:25], v[142:145], v[184:187], v[22:25]
	v_mfma_f32_16x16x32_bf16 v[14:17], v[152:155], v[184:187], v[14:17]
	s_barrier
	s_setprio 0
	s_add_i32 s7, s78, s55
	v_lshl_add_u64 v[138:139], v[132:133], 0, s[18:19]
	s_mov_b32 m0, s7
	v_lshl_add_u64 v[132:133], v[132:133], 0, s[14:15]
	global_load_lds_dwordx4 v[138:139], off
	s_add_i32 m0, s7, 0x2000
	s_nop 0
	global_load_lds_dwordx4 v[132:133], off
	s_waitcnt vmcnt(6)
	s_add_i32 s6, s6, 2
	s_add_u32 s8, s8, 0x100
	s_addc_u32 s9, s9, 0
	s_add_u32 s48, s48, 0x100
	s_addc_u32 s49, s49, 0
	s_cmpk_gt_u32 s6, 0x55
	s_cbranch_scc0 .LBB0_679
	s_setprio 1
	s_barrier
	v_mfma_f32_16x16x32_bf16 v[50:53], v[188:191], v[156:159], v[50:53]
	v_mfma_f32_16x16x32_bf16 v[42:45], v[196:199], v[156:159], v[42:45]
	v_mfma_f32_16x16x32_bf16 v[34:37], v[188:191], v[164:167], v[34:37]
	v_mfma_f32_16x16x32_bf16 v[26:29], v[196:199], v[164:167], v[26:29]
	v_mfma_f32_16x16x32_bf16 v[18:21], v[188:191], v[172:175], v[18:21]
	v_mfma_f32_16x16x32_bf16 v[10:13], v[196:199], v[172:175], v[10:13]
	v_mfma_f32_16x16x32_bf16 v[6:9], v[188:191], v[180:183], v[6:9]
	v_mfma_f32_16x16x32_bf16 v[2:5], v[196:199], v[180:183], v[2:5]
	v_mfma_f32_16x16x32_bf16 v[50:53], v[192:195], v[160:163], v[50:53]
	v_mfma_f32_16x16x32_bf16 v[42:45], v[200:203], v[160:163], v[42:45]
	v_mfma_f32_16x16x32_bf16 v[34:37], v[192:195], v[168:171], v[34:37]
	v_mfma_f32_16x16x32_bf16 v[26:29], v[200:203], v[168:171], v[26:29]
	v_mfma_f32_16x16x32_bf16 v[18:21], v[192:195], v[176:179], v[18:21]
	v_mfma_f32_16x16x32_bf16 v[10:13], v[200:203], v[176:179], v[10:13]
	v_mfma_f32_16x16x32_bf16 v[6:9], v[192:195], v[184:187], v[6:9]
	v_mfma_f32_16x16x32_bf16 v[2:5], v[200:203], v[184:187], v[2:5]
	s_barrier
	s_setprio 0
	v_mov_b32_e32 v137, v134
	s_lshl_b32 s6, s88, 8
	v_ashrrev_i32_e32 v132, 2, v137
	s_or_b32 s6, s6, s63
	v_and_b32_e32 v132, -4, v132
	v_add_u32_e32 v132, s6, v132
	s_lshl_b32 s6, s87, 8
	s_add_i32 s6, s6, s62
	v_and_or_b32 v188, v137, 15, s6
	v_ashrrev_i32_e32 v189, 31, v188
	v_ashrrev_i32_e32 v133, 31, v132
	v_lshlrev_b64 v[206:207], 13, v[188:189]
	v_or_b32_e32 v156, 16, v188
	v_or_b32_e32 v172, 32, v188
	v_or_b32_e32 v188, 48, v188
	v_lshlrev_b64 v[132:133], 2, v[132:133]
	v_ashrrev_i32_e32 v157, 31, v156
	v_ashrrev_i32_e32 v173, 31, v172
	v_ashrrev_i32_e32 v189, 31, v188
	v_lshl_add_u64 v[204:205], s[40:41], 0, v[132:133]
	v_lshlrev_b64 v[208:209], 13, v[156:157]
	v_lshlrev_b64 v[210:211], 13, v[172:173]
	v_lshlrev_b64 v[212:213], 13, v[188:189]
	v_lshl_add_u64 v[152:153], v[204:205], 0, v[206:207]
	v_lshl_add_u64 v[168:169], v[204:205], 0, v[208:209]
	v_lshl_add_u64 v[184:185], v[204:205], 0, v[210:211]
	v_lshl_add_u64 v[200:201], v[204:205], 0, v[212:213]
	global_load_dwordx4 v[138:141], v[152:153], off
	global_load_dwordx4 v[142:145], v[152:153], off offset:64
	global_load_dwordx4 v[148:151], v[152:153], off offset:512
	s_nop 0
	global_load_dwordx4 v[152:155], v[152:153], off offset:576
	s_nop 0
	global_load_dwordx4 v[156:159], v[168:169], off
	global_load_dwordx4 v[160:163], v[168:169], off offset:64
	global_load_dwordx4 v[164:167], v[168:169], off offset:512
	s_nop 0
	global_load_dwordx4 v[168:171], v[168:169], off offset:576
	s_nop 0
	global_load_dwordx4 v[172:175], v[184:185], off
	global_load_dwordx4 v[176:179], v[184:185], off offset:64
	global_load_dwordx4 v[180:183], v[184:185], off offset:512
	s_nop 0
	global_load_dwordx4 v[184:187], v[184:185], off offset:576
	s_nop 0
	global_load_dwordx4 v[188:191], v[200:201], off
	global_load_dwordx4 v[192:195], v[200:201], off offset:64
	global_load_dwordx4 v[196:199], v[200:201], off offset:512
	s_nop 0
	global_load_dwordx4 v[200:203], v[200:201], off offset:576
	s_waitcnt vmcnt(0)
	v_pk_fma_f32 v[126:127], v[126:127], 0.5, v[138:139] op_sel_hi:[1,0,1]
	v_lshl_add_u64 v[138:139], s[4:5], 0, v[206:207]
	v_lshl_add_u64 v[138:139], v[138:139], 0, v[132:133]
	v_pk_fma_f32 v[116:117], v[116:117], 0.5, v[150:151] op_sel_hi:[1,0,1]
	v_pk_fma_f32 v[114:115], v[114:115], 0.5, v[148:149] op_sel_hi:[1,0,1]
	global_store_dwordx4 v[138:139], v[114:117], off offset:512
	v_pk_fma_f32 v[100:101], v[100:101], 0.5, v[166:167] op_sel_hi:[1,0,1]
	v_pk_fma_f32 v[98:99], v[98:99], 0.5, v[164:165] op_sel_hi:[1,0,1]
	v_lshl_add_u64 v[114:115], s[4:5], 0, v[208:209]
	v_lshl_add_u64 v[114:115], v[114:115], 0, v[132:133]
	global_store_dwordx4 v[114:115], v[98:101], off offset:512
	v_pk_fma_f32 v[84:85], v[84:85], 0.5, v[182:183] op_sel_hi:[1,0,1]
	v_pk_fma_f32 v[82:83], v[82:83], 0.5, v[180:181] op_sel_hi:[1,0,1]
	v_lshl_add_u64 v[98:99], s[4:5], 0, v[210:211]
	v_lshl_add_u64 v[98:99], v[98:99], 0, v[132:133]
	v_pk_fma_f32 v[108:109], v[108:109], 0.5, v[154:155] op_sel_hi:[1,0,1]
	v_pk_fma_f32 v[106:107], v[106:107], 0.5, v[152:153] op_sel_hi:[1,0,1]
	v_pk_fma_f32 v[92:93], v[92:93], 0.5, v[170:171] op_sel_hi:[1,0,1]
	v_pk_fma_f32 v[90:91], v[90:91], 0.5, v[168:169] op_sel_hi:[1,0,1]
	global_store_dwordx4 v[98:99], v[82:85], off offset:512
	v_pk_fma_f32 v[76:77], v[76:77], 0.5, v[186:187] op_sel_hi:[1,0,1]
	v_pk_fma_f32 v[74:75], v[74:75], 0.5, v[184:185] op_sel_hi:[1,0,1]
	v_lshl_add_u64 v[82:83], s[4:5], 0, v[212:213]
	global_store_dwordx4 v[138:139], v[106:109], off offset:576
	global_store_dwordx4 v[114:115], v[90:93], off offset:576
	global_store_dwordx4 v[98:99], v[74:77], off offset:576
	v_pk_fma_f32 v[108:109], v[120:121], 0.5, v[158:159] op_sel_hi:[1,0,1]
	v_pk_fma_f32 v[106:107], v[118:119], 0.5, v[156:157] op_sel_hi:[1,0,1]
	v_pk_fma_f32 v[92:93], v[104:105], 0.5, v[174:175] op_sel_hi:[1,0,1]
	v_pk_fma_f32 v[90:91], v[102:103], 0.5, v[172:173] op_sel_hi:[1,0,1]
	v_pk_fma_f32 v[76:77], v[88:89], 0.5, v[190:191] op_sel_hi:[1,0,1]
	v_pk_fma_f32 v[74:75], v[86:87], 0.5, v[188:189] op_sel_hi:[1,0,1]
	v_lshl_add_u64 v[82:83], v[82:83], 0, v[132:133]
	v_pk_fma_f32 v[128:129], v[128:129], 0.5, v[140:141] op_sel_hi:[1,0,1]
	v_pk_fma_f32 v[124:125], v[124:125], 0.5, v[144:145] op_sel_hi:[1,0,1]
	v_pk_fma_f32 v[122:123], v[122:123], 0.5, v[142:143] op_sel_hi:[1,0,1]
	global_store_dwordx4 v[114:115], v[106:109], off
	global_store_dwordx4 v[98:99], v[90:93], off
	global_store_dwordx4 v[82:83], v[74:77], off
	v_pk_fma_f32 v[108:109], v[112:113], 0.5, v[162:163] op_sel_hi:[1,0,1]
	v_pk_fma_f32 v[106:107], v[110:111], 0.5, v[160:161] op_sel_hi:[1,0,1]
	v_pk_fma_f32 v[92:93], v[96:97], 0.5, v[178:179] op_sel_hi:[1,0,1]
	v_pk_fma_f32 v[90:91], v[94:95], 0.5, v[176:177] op_sel_hi:[1,0,1]
	v_pk_fma_f32 v[76:77], v[80:81], 0.5, v[194:195] op_sel_hi:[1,0,1]
	v_pk_fma_f32 v[74:75], v[78:79], 0.5, v[192:193] op_sel_hi:[1,0,1]
	v_pk_fma_f32 v[72:73], v[72:73], 0.5, v[198:199] op_sel_hi:[1,0,1]
	v_pk_fma_f32 v[70:71], v[70:71], 0.5, v[196:197] op_sel_hi:[1,0,1]
	v_pk_fma_f32 v[68:69], v[68:69], 0.5, v[202:203] op_sel_hi:[1,0,1]
	v_pk_fma_f32 v[66:67], v[66:67], 0.5, v[200:201] op_sel_hi:[1,0,1]
	global_store_dwordx4 v[138:139], v[126:129], off
	global_store_dwordx4 v[138:139], v[122:125], off offset:64
	global_store_dwordx4 v[114:115], v[106:109], off offset:64
	global_store_dwordx4 v[98:99], v[90:93], off offset:64
	global_store_dwordx4 v[82:83], v[74:77], off offset:64
	global_store_dwordx4 v[82:83], v[70:73], off offset:512
	global_store_dwordx4 v[82:83], v[66:69], off offset:576
	s_mov_b64 s[6:7], 0x120000
	v_lshl_add_u64 v[140:141], v[206:207], 0, s[6:7]
	s_mov_b64 s[6:7], 0x140000
	v_lshl_add_u64 v[138:139], v[206:207], 0, s[0:1]
	v_lshl_add_u64 v[142:143], v[206:207], 0, s[6:7]
	v_lshl_add_u64 v[144:145], v[206:207], 0, s[28:29]
	v_lshl_add_u64 v[78:79], v[204:205], 0, v[138:139]
	v_lshl_add_u64 v[94:95], v[204:205], 0, v[140:141]
	v_lshl_add_u64 v[110:111], v[204:205], 0, v[142:143]
	v_lshl_add_u64 v[126:127], v[204:205], 0, v[144:145]
	global_load_dwordx4 v[66:69], v[78:79], off
	global_load_dwordx4 v[70:73], v[78:79], off offset:64
	global_load_dwordx4 v[74:77], v[78:79], off offset:512
	s_nop 0
	global_load_dwordx4 v[78:81], v[78:79], off offset:576
	s_nop 0
	global_load_dwordx4 v[82:85], v[94:95], off
	global_load_dwordx4 v[86:89], v[94:95], off offset:64
	global_load_dwordx4 v[90:93], v[94:95], off offset:512
	s_nop 0
	global_load_dwordx4 v[94:97], v[94:95], off offset:576
	s_nop 0
	global_load_dwordx4 v[98:101], v[110:111], off
	global_load_dwordx4 v[102:105], v[110:111], off offset:64
	global_load_dwordx4 v[106:109], v[110:111], off offset:512
	s_nop 0
	global_load_dwordx4 v[110:113], v[110:111], off offset:576
	s_nop 0
	global_load_dwordx4 v[114:117], v[126:127], off
	global_load_dwordx4 v[118:121], v[126:127], off offset:64
	global_load_dwordx4 v[122:125], v[126:127], off offset:512
	s_nop 0
	global_load_dwordx4 v[126:129], v[126:127], off offset:576
	s_waitcnt vmcnt(0)
	v_pk_fma_f32 v[62:63], v[62:63], 0.5, v[66:67] op_sel_hi:[1,0,1]
	v_lshl_add_u64 v[66:67], s[4:5], 0, v[138:139]
	v_lshl_add_u64 v[66:67], v[66:67], 0, v[132:133]
	v_pk_fma_f32 v[52:53], v[52:53], 0.5, v[76:77] op_sel_hi:[1,0,1]
	v_pk_fma_f32 v[50:51], v[50:51], 0.5, v[74:75] op_sel_hi:[1,0,1]
	global_store_dwordx4 v[66:67], v[50:53], off offset:512
	v_pk_fma_f32 v[36:37], v[36:37], 0.5, v[92:93] op_sel_hi:[1,0,1]
	v_pk_fma_f32 v[34:35], v[34:35], 0.5, v[90:91] op_sel_hi:[1,0,1]
	v_lshl_add_u64 v[50:51], s[4:5], 0, v[140:141]
	v_lshl_add_u64 v[50:51], v[50:51], 0, v[132:133]
	global_store_dwordx4 v[50:51], v[34:37], off offset:512
	v_pk_fma_f32 v[20:21], v[20:21], 0.5, v[108:109] op_sel_hi:[1,0,1]
	v_pk_fma_f32 v[18:19], v[18:19], 0.5, v[106:107] op_sel_hi:[1,0,1]
	v_lshl_add_u64 v[34:35], s[4:5], 0, v[142:143]
	v_lshl_add_u64 v[34:35], v[34:35], 0, v[132:133]
	v_pk_fma_f32 v[44:45], v[44:45], 0.5, v[80:81] op_sel_hi:[1,0,1]
	v_pk_fma_f32 v[42:43], v[42:43], 0.5, v[78:79] op_sel_hi:[1,0,1]
	v_pk_fma_f32 v[28:29], v[28:29], 0.5, v[96:97] op_sel_hi:[1,0,1]
	v_pk_fma_f32 v[26:27], v[26:27], 0.5, v[94:95] op_sel_hi:[1,0,1]
	global_store_dwordx4 v[34:35], v[18:21], off offset:512
	v_pk_fma_f32 v[12:13], v[12:13], 0.5, v[112:113] op_sel_hi:[1,0,1]
	v_pk_fma_f32 v[10:11], v[10:11], 0.5, v[110:111] op_sel_hi:[1,0,1]
	v_lshl_add_u64 v[18:19], s[4:5], 0, v[144:145]
	global_store_dwordx4 v[66:67], v[42:45], off offset:576
	global_store_dwordx4 v[50:51], v[26:29], off offset:576
	global_store_dwordx4 v[34:35], v[10:13], off offset:576
	v_pk_fma_f32 v[44:45], v[56:57], 0.5, v[84:85] op_sel_hi:[1,0,1]
	v_pk_fma_f32 v[42:43], v[54:55], 0.5, v[82:83] op_sel_hi:[1,0,1]
	v_pk_fma_f32 v[28:29], v[40:41], 0.5, v[100:101] op_sel_hi:[1,0,1]
	v_pk_fma_f32 v[26:27], v[38:39], 0.5, v[98:99] op_sel_hi:[1,0,1]
	v_pk_fma_f32 v[12:13], v[24:25], 0.5, v[116:117] op_sel_hi:[1,0,1]
	v_pk_fma_f32 v[10:11], v[22:23], 0.5, v[114:115] op_sel_hi:[1,0,1]
	v_lshl_add_u64 v[18:19], v[18:19], 0, v[132:133]
	v_pk_fma_f32 v[64:65], v[64:65], 0.5, v[68:69] op_sel_hi:[1,0,1]
	v_pk_fma_f32 v[60:61], v[60:61], 0.5, v[72:73] op_sel_hi:[1,0,1]
	v_pk_fma_f32 v[58:59], v[58:59], 0.5, v[70:71] op_sel_hi:[1,0,1]
	global_store_dwordx4 v[50:51], v[42:45], off
	global_store_dwordx4 v[34:35], v[26:29], off
	global_store_dwordx4 v[18:19], v[10:13], off
	v_pk_fma_f32 v[44:45], v[48:49], 0.5, v[88:89] op_sel_hi:[1,0,1]
	v_pk_fma_f32 v[42:43], v[46:47], 0.5, v[86:87] op_sel_hi:[1,0,1]
	v_pk_fma_f32 v[28:29], v[32:33], 0.5, v[104:105] op_sel_hi:[1,0,1]
	v_pk_fma_f32 v[26:27], v[30:31], 0.5, v[102:103] op_sel_hi:[1,0,1]
	v_pk_fma_f32 v[12:13], v[16:17], 0.5, v[120:121] op_sel_hi:[1,0,1]
	v_pk_fma_f32 v[10:11], v[14:15], 0.5, v[118:119] op_sel_hi:[1,0,1]
	v_pk_fma_f32 v[8:9], v[8:9], 0.5, v[124:125] op_sel_hi:[1,0,1]
	v_pk_fma_f32 v[6:7], v[6:7], 0.5, v[122:123] op_sel_hi:[1,0,1]
	v_pk_fma_f32 v[4:5], v[4:5], 0.5, v[128:129] op_sel_hi:[1,0,1]
	v_pk_fma_f32 v[2:3], v[2:3], 0.5, v[126:127] op_sel_hi:[1,0,1]
	global_store_dwordx4 v[66:67], v[62:65], off
	global_store_dwordx4 v[66:67], v[58:61], off offset:64
	global_store_dwordx4 v[50:51], v[42:45], off offset:64
	global_store_dwordx4 v[34:35], v[26:29], off offset:64
	global_store_dwordx4 v[18:19], v[10:13], off offset:64
	global_store_dwordx4 v[18:19], v[6:9], off offset:512
	global_store_dwordx4 v[18:19], v[2:5], off offset:576
	s_and_b64 vcc, exec, s[42:43]
	s_mov_b32 s87, s10
	s_mov_b32 s88, s11
	s_mov_b64 s[8:9], s[46:47]
	s_mov_b64 s[6:7], s[44:45]
	s_movk_i32 s92, 0x4000
	s_movk_i32 s93, 0xf800
	s_movk_i32 s91, 0x60
	s_mov_b32 s78, 0x2a000000
	s_mov_b32 s79, 0x3fffe
	s_mov_b32 s90, 0xc0000
	s_cbranch_vccz .LBB0_672
	s_waitcnt vmcnt(0)
	s_cmpk_gt_u32 s50, 0xff
	s_cbranch_scc1 .LBB0_683
	s_barrier

.LBB0_693:
	s_add_u32 s41, s8, 0x100
	v_mov_b32_e32 v2, 0
	s_addc_u32 s86, s9, 0
	s_mov_b32 s87, -2
	v_mov_b32_e32 v3, v2
	v_mov_b32_e32 v4, v2
	v_mov_b32_e32 v5, v2
	v_mov_b32_e32 v6, v2
	v_mov_b32_e32 v7, v2
	v_mov_b32_e32 v8, v2
	v_mov_b32_e32 v9, v2
	v_mov_b32_e32 v18, v2
	v_mov_b32_e32 v19, v2
	v_mov_b32_e32 v20, v2
	v_mov_b32_e32 v21, v2
	v_mov_b32_e32 v22, v2
	v_mov_b32_e32 v23, v2
	v_mov_b32_e32 v24, v2
	v_mov_b32_e32 v25, v2
	v_mov_b32_e32 v34, v2
	v_mov_b32_e32 v35, v2
	v_mov_b32_e32 v36, v2
	v_mov_b32_e32 v37, v2
	v_mov_b32_e32 v38, v2
	v_mov_b32_e32 v39, v2
	v_mov_b32_e32 v40, v2
	v_mov_b32_e32 v41, v2
	v_mov_b32_e32 v50, v2
	v_mov_b32_e32 v51, v2
	v_mov_b32_e32 v52, v2
	v_mov_b32_e32 v53, v2
	v_mov_b32_e32 v54, v2
	v_mov_b32_e32 v55, v2
	v_mov_b32_e32 v56, v2
	v_mov_b32_e32 v57, v2
	v_mov_b32_e32 v10, v2
	v_mov_b32_e32 v11, v2
	v_mov_b32_e32 v12, v2
	v_mov_b32_e32 v13, v2
	v_mov_b32_e32 v14, v2
	v_mov_b32_e32 v15, v2
	v_mov_b32_e32 v16, v2
	v_mov_b32_e32 v17, v2
	v_mov_b32_e32 v26, v2
	v_mov_b32_e32 v27, v2
	v_mov_b32_e32 v28, v2
	v_mov_b32_e32 v29, v2
	v_mov_b32_e32 v30, v2
	v_mov_b32_e32 v31, v2
	v_mov_b32_e32 v32, v2
	v_mov_b32_e32 v33, v2
	v_mov_b32_e32 v42, v2
	v_mov_b32_e32 v43, v2
	v_mov_b32_e32 v44, v2
	v_mov_b32_e32 v45, v2
	v_mov_b32_e32 v46, v2
	v_mov_b32_e32 v47, v2
	v_mov_b32_e32 v48, v2
	v_mov_b32_e32 v49, v2
	v_mov_b32_e32 v58, v2
	v_mov_b32_e32 v59, v2
	v_mov_b32_e32 v60, v2
	v_mov_b32_e32 v61, v2
	v_mov_b32_e32 v62, v2
	v_mov_b32_e32 v63, v2
	v_mov_b32_e32 v64, v2
	v_mov_b32_e32 v65, v2
	v_mov_b32_e32 v66, v2
	v_mov_b32_e32 v67, v2
	v_mov_b32_e32 v68, v2
	v_mov_b32_e32 v69, v2
	v_mov_b32_e32 v70, v2
	v_mov_b32_e32 v71, v2
	v_mov_b32_e32 v72, v2
	v_mov_b32_e32 v73, v2
	v_mov_b32_e32 v82, v2
	v_mov_b32_e32 v83, v2
	v_mov_b32_e32 v84, v2
	v_mov_b32_e32 v85, v2
	v_mov_b32_e32 v86, v2
	v_mov_b32_e32 v87, v2
	v_mov_b32_e32 v88, v2
	v_mov_b32_e32 v89, v2
	v_mov_b32_e32 v98, v2
	v_mov_b32_e32 v99, v2
	v_mov_b32_e32 v100, v2
	v_mov_b32_e32 v101, v2
	v_mov_b32_e32 v102, v2
	v_mov_b32_e32 v103, v2
	v_mov_b32_e32 v104, v2
	v_mov_b32_e32 v105, v2
	v_mov_b32_e32 v114, v2
	v_mov_b32_e32 v115, v2
	v_mov_b32_e32 v116, v2
	v_mov_b32_e32 v117, v2
	v_mov_b32_e32 v118, v2
	v_mov_b32_e32 v119, v2
	v_mov_b32_e32 v120, v2
	v_mov_b32_e32 v121, v2
	v_mov_b32_e32 v74, v2
	v_mov_b32_e32 v75, v2
	v_mov_b32_e32 v76, v2
	v_mov_b32_e32 v77, v2
	v_mov_b32_e32 v78, v2
	v_mov_b32_e32 v79, v2
	v_mov_b32_e32 v80, v2
	v_mov_b32_e32 v81, v2
	v_mov_b32_e32 v90, v2
	v_mov_b32_e32 v91, v2
	v_mov_b32_e32 v92, v2
	v_mov_b32_e32 v93, v2
	v_mov_b32_e32 v94, v2
	v_mov_b32_e32 v95, v2
	v_mov_b32_e32 v96, v2
	v_mov_b32_e32 v97, v2
	v_mov_b32_e32 v106, v2
	v_mov_b32_e32 v107, v2
	v_mov_b32_e32 v108, v2
	v_mov_b32_e32 v109, v2
	v_mov_b32_e32 v110, v2
	v_mov_b32_e32 v111, v2
	v_mov_b32_e32 v112, v2
	v_mov_b32_e32 v113, v2
	v_mov_b32_e32 v122, v2
	v_mov_b32_e32 v123, v2
	v_mov_b32_e32 v124, v2
	v_mov_b32_e32 v125, v2
	v_mov_b32_e32 v126, v2
	v_mov_b32_e32 v127, v2
	v_mov_b32_e32 v128, v2
	v_mov_b32_e32 v129, v2
	s_branch .Lrot_enter_0

.Lrot_enter_0:
	s_add_u32 s8, s6, 0x100
	s_addc_u32 s9, s7, 0
	s_add_i32 s78, 0, 0x10000
	v_add_u32_e32 v134, s78, v137
	ds_read_b128 v[140:143], v134
	ds_read_b128 v[148:151], v134 offset:1024
	ds_read_b128 v[152:155], v134 offset:2048
	ds_read_b128 v[156:159], v134 offset:3072
	s_cmp_eq_u32 s87, 28
	s_cselect_b32 s89, s45, s9
	s_cselect_b32 s88, s44, s8
	s_cselect_b32 s91, s47, s86
	s_cselect_b32 s90, s46, s41
	v_lshl_add_u64 v[134:135], s[6:7], 0, v[132:133]
	v_lshl_add_u64 v[144:145], v[134:135], 0, s[16:17]
	s_add_i32 m0, s49, 0xc000
	ds_read_b128 v[160:163], v138
	ds_read_b128 v[164:167], v138 offset:1024
	ds_read_b128 v[168:171], v138 offset:2048
	ds_read_b128 v[172:175], v138 offset:3072
	ds_read_b128 v[176:179], v138 offset:4096
	ds_read_b128 v[180:183], v138 offset:5120
	ds_read_b128 v[184:187], v138 offset:6144
	ds_read_b128 v[188:191], v138 offset:7168
	global_load_lds_dwordx4 v[144:145], off
	v_lshl_add_u64 v[134:135], v[134:135], 0, s[80:81]
	s_add_i32 m0, s49, 0xe000
	s_nop 0
	global_load_lds_dwordx4 v[134:135], off
	s_waitcnt lgkmcnt(8)
	s_setprio 1
	s_barrier
	s_waitcnt lgkmcnt(0)
	v_mfma_f32_16x16x32_bf16 v[126:129], v[140:143], v[160:163], v[126:129]
	v_mfma_f32_16x16x32_bf16 v[122:125], v[152:155], v[160:163], v[122:125]
	v_mfma_f32_16x16x32_bf16 v[110:113], v[140:143], v[168:171], v[110:113]
	v_mfma_f32_16x16x32_bf16 v[106:109], v[152:155], v[168:171], v[106:109]
	v_mfma_f32_16x16x32_bf16 v[94:97], v[140:143], v[176:179], v[94:97]
	v_mfma_f32_16x16x32_bf16 v[90:93], v[152:155], v[176:179], v[90:93]
	v_mfma_f32_16x16x32_bf16 v[78:81], v[140:143], v[184:187], v[78:81]
	v_mfma_f32_16x16x32_bf16 v[74:77], v[152:155], v[184:187], v[74:77]
	v_mfma_f32_16x16x32_bf16 v[126:129], v[148:151], v[164:167], v[126:129]
	v_mfma_f32_16x16x32_bf16 v[122:125], v[156:159], v[164:167], v[122:125]
	v_mfma_f32_16x16x32_bf16 v[110:113], v[148:151], v[172:175], v[110:113]
	v_mfma_f32_16x16x32_bf16 v[106:109], v[156:159], v[172:175], v[106:109]
	v_mfma_f32_16x16x32_bf16 v[94:97], v[148:151], v[180:183], v[94:97]
	v_mfma_f32_16x16x32_bf16 v[90:93], v[156:159], v[180:183], v[90:93]
	v_mfma_f32_16x16x32_bf16 v[78:81], v[148:151], v[188:191], v[78:81]
	v_mfma_f32_16x16x32_bf16 v[74:77], v[156:159], v[188:191], v[74:77]
	s_barrier
	s_setprio 0
	s_add_i32 s6, 0, 0x14000
	v_add_u32_e32 v134, s6, v137
	s_add_i32 s7, s78, s54
	ds_read_b128 v[192:195], v134
	ds_read_b128 v[196:199], v134 offset:1024
	ds_read_b128 v[200:203], v134 offset:2048
	ds_read_b128 v[204:207], v134 offset:3072
	v_lshl_add_u64 v[134:135], s[90:91], 0, v[0:1]
	s_mov_b32 m0, s7
	v_lshl_add_u64 v[144:145], v[134:135], 0, s[60:61]
	global_load_lds_dwordx4 v[134:135], off
	s_add_i32 m0, s7, 0x2000
	s_nop 0
	global_load_lds_dwordx4 v[144:145], off
	s_setprio 1
	s_barrier
	s_waitcnt lgkmcnt(0)
	v_mfma_f32_16x16x32_bf16 v[118:121], v[192:195], v[160:163], v[118:121]
	v_mfma_f32_16x16x32_bf16 v[114:117], v[200:203], v[160:163], v[114:117]
	v_mfma_f32_16x16x32_bf16 v[102:105], v[192:195], v[168:171], v[102:105]
	v_mfma_f32_16x16x32_bf16 v[98:101], v[200:203], v[168:171], v[98:101]
	v_mfma_f32_16x16x32_bf16 v[86:89], v[192:195], v[176:179], v[86:89]
	v_mfma_f32_16x16x32_bf16 v[82:85], v[200:203], v[176:179], v[82:85]
	v_mfma_f32_16x16x32_bf16 v[70:73], v[192:195], v[184:187], v[70:73]
	v_mfma_f32_16x16x32_bf16 v[66:69], v[200:203], v[184:187], v[66:69]
	v_mfma_f32_16x16x32_bf16 v[118:121], v[196:199], v[164:167], v[118:121]
	v_mfma_f32_16x16x32_bf16 v[114:117], v[204:207], v[164:167], v[114:117]
	v_mfma_f32_16x16x32_bf16 v[102:105], v[196:199], v[172:175], v[102:105]
	v_mfma_f32_16x16x32_bf16 v[98:101], v[204:207], v[172:175], v[98:101]
	v_mfma_f32_16x16x32_bf16 v[86:89], v[196:199], v[180:183], v[86:89]
	v_mfma_f32_16x16x32_bf16 v[82:85], v[204:207], v[180:183], v[82:85]
	v_mfma_f32_16x16x32_bf16 v[70:73], v[196:199], v[188:191], v[70:73]
	v_mfma_f32_16x16x32_bf16 v[66:69], v[204:207], v[188:191], v[66:69]
	s_barrier
	s_setprio 0
	s_mov_b32 m0, s49
	v_lshl_add_u64 v[144:145], s[88:89], 0, v[130:131]
	ds_read_b128 v[160:163], v138 offset:16384
	ds_read_b128 v[164:167], v138 offset:17408
	ds_read_b128 v[168:171], v138 offset:18432
	ds_read_b128 v[172:175], v138 offset:19456
	ds_read_b128 v[176:179], v138 offset:20480
	ds_read_b128 v[180:183], v138 offset:21504
	ds_read_b128 v[184:187], v138 offset:22528
	ds_read_b128 v[188:191], v138 offset:23552
	global_load_lds_dwordx4 v[144:145], off
	v_lshl_add_u64 v[208:209], v[144:145], 0, s[60:61]
	s_mov_b32 m0, s55
	s_nop 0
	global_load_lds_dwordx4 v[208:209], off
	s_setprio 1
	s_barrier
	s_waitcnt lgkmcnt(0)
	v_mfma_f32_16x16x32_bf16 v[62:65], v[140:143], v[160:163], v[62:65]
	v_mfma_f32_16x16x32_bf16 v[58:61], v[152:155], v[160:163], v[58:61]
	v_mfma_f32_16x16x32_bf16 v[46:49], v[140:143], v[168:171], v[46:49]
	v_mfma_f32_16x16x32_bf16 v[42:45], v[152:155], v[168:171], v[42:45]
	v_mfma_f32_16x16x32_bf16 v[30:33], v[140:143], v[176:179], v[30:33]
	v_mfma_f32_16x16x32_bf16 v[26:29], v[152:155], v[176:179], v[26:29]
	v_mfma_f32_16x16x32_bf16 v[14:17], v[140:143], v[184:187], v[14:17]
	v_mfma_f32_16x16x32_bf16 v[10:13], v[152:155], v[184:187], v[10:13]
	v_mfma_f32_16x16x32_bf16 v[62:65], v[148:151], v[164:167], v[62:65]
	v_mfma_f32_16x16x32_bf16 v[58:61], v[156:159], v[164:167], v[58:61]
	v_mfma_f32_16x16x32_bf16 v[46:49], v[148:151], v[172:175], v[46:49]
	v_mfma_f32_16x16x32_bf16 v[42:45], v[156:159], v[172:175], v[42:45]
	v_mfma_f32_16x16x32_bf16 v[30:33], v[148:151], v[180:183], v[30:33]
	v_mfma_f32_16x16x32_bf16 v[26:29], v[156:159], v[180:183], v[26:29]
	v_mfma_f32_16x16x32_bf16 v[14:17], v[148:151], v[188:191], v[14:17]
	v_mfma_f32_16x16x32_bf16 v[10:13], v[156:159], v[188:191], v[10:13]
	s_barrier
	s_setprio 0
	s_add_i32 s6, s6, s54
	v_lshl_add_u64 v[140:141], v[134:135], 0, s[20:21]
	s_mov_b32 m0, s6
	s_nop 0
	global_load_lds_dwordx4 v[140:141], off
	v_lshl_add_u64 v[140:141], v[134:135], 0, s[64:65]
	s_add_i32 m0, s6, 0x2000
	s_nop 0
	global_load_lds_dwordx4 v[140:141], off
	v_lshl_add_u64 v[230:231], v[144:145], 0, s[20:21]
	s_mov_b32 m0, s56
	s_nop 0
	global_load_lds_dwordx4 v[230:231], off
	v_lshl_add_u64 v[230:231], v[144:145], 0, s[64:65]
	s_mov_b32 m0, s57
	s_nop 0
	global_load_lds_dwordx4 v[230:231], off
	s_waitcnt vmcnt(8)
	s_setprio 1
	s_barrier
	v_mfma_f32_16x16x32_bf16 v[54:57], v[192:195], v[160:163], v[54:57]
	v_mfma_f32_16x16x32_bf16 v[50:53], v[200:203], v[160:163], v[50:53]
	v_mfma_f32_16x16x32_bf16 v[38:41], v[192:195], v[168:171], v[38:41]
	v_mfma_f32_16x16x32_bf16 v[34:37], v[200:203], v[168:171], v[34:37]
	v_mfma_f32_16x16x32_bf16 v[22:25], v[192:195], v[176:179], v[22:25]
	v_mfma_f32_16x16x32_bf16 v[18:21], v[200:203], v[176:179], v[18:21]
	v_mfma_f32_16x16x32_bf16 v[6:9], v[192:195], v[184:187], v[6:9]
	v_mfma_f32_16x16x32_bf16 v[2:5], v[200:203], v[184:187], v[2:5]
	v_mfma_f32_16x16x32_bf16 v[54:57], v[196:199], v[164:167], v[54:57]
	v_mfma_f32_16x16x32_bf16 v[50:53], v[204:207], v[164:167], v[50:53]
	v_mfma_f32_16x16x32_bf16 v[38:41], v[196:199], v[172:175], v[38:41]
	v_mfma_f32_16x16x32_bf16 v[34:37], v[204:207], v[172:175], v[34:37]
	v_mfma_f32_16x16x32_bf16 v[22:25], v[196:199], v[180:183], v[22:25]
	v_mfma_f32_16x16x32_bf16 v[18:21], v[204:207], v[180:183], v[18:21]
	v_mfma_f32_16x16x32_bf16 v[6:9], v[196:199], v[188:191], v[6:9]
	v_mfma_f32_16x16x32_bf16 v[2:5], v[204:207], v[188:191], v[2:5]
	s_barrier
	s_setprio 0
	s_add_i32 s6, 0, 0x18000
	v_add_u32_e32 v139, s6, v137
	ds_read_b128 v[140:143], v139
	ds_read_b128 v[148:151], v139 offset:1024
	ds_read_b128 v[152:155], v139 offset:2048
	ds_read_b128 v[156:159], v139 offset:3072
	ds_read_b128 v[160:163], v138 offset:32768
	ds_read_b128 v[164:167], v138 offset:33792
	ds_read_b128 v[168:171], v138 offset:34816
	ds_read_b128 v[172:175], v138 offset:35840
	ds_read_b128 v[176:179], v138 offset:36864
	ds_read_b128 v[180:183], v138 offset:37888
	ds_read_b128 v[184:187], v138 offset:38912
	ds_read_b128 v[188:191], v138 offset:39936
	s_waitcnt lgkmcnt(8)
	s_setprio 1
	s_barrier
	s_waitcnt lgkmcnt(0)
	v_mfma_f32_16x16x32_bf16 v[126:129], v[140:143], v[160:163], v[126:129]
	v_mfma_f32_16x16x32_bf16 v[122:125], v[152:155], v[160:163], v[122:125]
	v_mfma_f32_16x16x32_bf16 v[110:113], v[140:143], v[168:171], v[110:113]
	v_mfma_f32_16x16x32_bf16 v[106:109], v[152:155], v[168:171], v[106:109]
	v_mfma_f32_16x16x32_bf16 v[94:97], v[140:143], v[176:179], v[94:97]
	v_mfma_f32_16x16x32_bf16 v[90:93], v[152:155], v[176:179], v[90:93]
	v_mfma_f32_16x16x32_bf16 v[78:81], v[140:143], v[184:187], v[78:81]
	v_mfma_f32_16x16x32_bf16 v[74:77], v[152:155], v[184:187], v[74:77]
	v_mfma_f32_16x16x32_bf16 v[126:129], v[148:151], v[164:167], v[126:129]
	v_mfma_f32_16x16x32_bf16 v[122:125], v[156:159], v[164:167], v[122:125]
	v_mfma_f32_16x16x32_bf16 v[110:113], v[148:151], v[172:175], v[110:113]
	v_mfma_f32_16x16x32_bf16 v[106:109], v[156:159], v[172:175], v[106:109]
	v_mfma_f32_16x16x32_bf16 v[94:97], v[148:151], v[180:183], v[94:97]
	v_mfma_f32_16x16x32_bf16 v[90:93], v[156:159], v[180:183], v[90:93]
	v_mfma_f32_16x16x32_bf16 v[78:81], v[148:151], v[188:191], v[78:81]
	v_mfma_f32_16x16x32_bf16 v[74:77], v[156:159], v[188:191], v[74:77]
	s_barrier
	s_setprio 0
	s_add_i32 s7, 0, 0x1c000
	s_add_i32 s6, s6, s54
	v_add_u32_e32 v139, s7, v137
	v_lshl_add_u64 v[208:209], v[134:135], 0, s[34:35]
	s_mov_b32 m0, s6
	ds_read_b128 v[192:195], v139
	ds_read_b128 v[196:199], v139 offset:1024
	ds_read_b128 v[200:203], v139 offset:2048
	ds_read_b128 v[204:207], v139 offset:3072
	global_load_lds_dwordx4 v[208:209], off
	v_lshl_add_u64 v[208:209], v[134:135], 0, s[66:67]
	s_add_i32 m0, s6, 0x2000
	s_nop 0
	global_load_lds_dwordx4 v[208:209], off
	s_setprio 1
	s_barrier
	s_waitcnt lgkmcnt(0)
	v_mfma_f32_16x16x32_bf16 v[118:121], v[192:195], v[160:163], v[118:121]
	v_mfma_f32_16x16x32_bf16 v[114:117], v[200:203], v[160:163], v[114:117]
	v_mfma_f32_16x16x32_bf16 v[102:105], v[192:195], v[168:171], v[102:105]
	v_mfma_f32_16x16x32_bf16 v[98:101], v[200:203], v[168:171], v[98:101]
	v_mfma_f32_16x16x32_bf16 v[86:89], v[192:195], v[176:179], v[86:89]
	v_mfma_f32_16x16x32_bf16 v[82:85], v[200:203], v[176:179], v[82:85]
	v_mfma_f32_16x16x32_bf16 v[70:73], v[192:195], v[184:187], v[70:73]
	v_mfma_f32_16x16x32_bf16 v[66:69], v[200:203], v[184:187], v[66:69]
	v_mfma_f32_16x16x32_bf16 v[118:121], v[196:199], v[164:167], v[118:121]
	v_mfma_f32_16x16x32_bf16 v[114:117], v[204:207], v[164:167], v[114:117]
	v_mfma_f32_16x16x32_bf16 v[102:105], v[196:199], v[172:175], v[102:105]
	v_mfma_f32_16x16x32_bf16 v[98:101], v[204:207], v[172:175], v[98:101]
	v_mfma_f32_16x16x32_bf16 v[86:89], v[196:199], v[180:183], v[86:89]
	v_mfma_f32_16x16x32_bf16 v[82:85], v[204:207], v[180:183], v[82:85]
	v_mfma_f32_16x16x32_bf16 v[70:73], v[196:199], v[188:191], v[70:73]
	v_mfma_f32_16x16x32_bf16 v[66:69], v[204:207], v[188:191], v[66:69]
	s_barrier
	s_setprio 0
	s_mov_b32 m0, s58
	v_lshl_add_u64 v[208:209], v[144:145], 0, s[34:35]
	ds_read_b128 v[160:163], v138 offset:49152
	ds_read_b128 v[164:167], v138 offset:50176
	ds_read_b128 v[168:171], v138 offset:51200
	ds_read_b128 v[172:175], v138 offset:52224
	ds_read_b128 v[176:179], v138 offset:53248
	ds_read_b128 v[180:183], v138 offset:54272
	ds_read_b128 v[184:187], v138 offset:55296
	ds_read_b128 v[188:191], v138 offset:56320
	global_load_lds_dwordx4 v[208:209], off
	v_lshl_add_u64 v[144:145], v[144:145], 0, s[66:67]
	s_mov_b32 m0, s59
	s_nop 0
	global_load_lds_dwordx4 v[144:145], off
	s_setprio 1
	s_barrier
	s_waitcnt lgkmcnt(0)
	v_mfma_f32_16x16x32_bf16 v[62:65], v[140:143], v[160:163], v[62:65]
	v_mfma_f32_16x16x32_bf16 v[58:61], v[152:155], v[160:163], v[58:61]
	v_mfma_f32_16x16x32_bf16 v[46:49], v[140:143], v[168:171], v[46:49]
	v_mfma_f32_16x16x32_bf16 v[42:45], v[152:155], v[168:171], v[42:45]
	v_mfma_f32_16x16x32_bf16 v[30:33], v[140:143], v[176:179], v[30:33]
	v_mfma_f32_16x16x32_bf16 v[26:29], v[152:155], v[176:179], v[26:29]
	v_mfma_f32_16x16x32_bf16 v[14:17], v[140:143], v[184:187], v[14:17]
	v_mfma_f32_16x16x32_bf16 v[10:13], v[152:155], v[184:187], v[10:13]
	v_mfma_f32_16x16x32_bf16 v[62:65], v[148:151], v[164:167], v[62:65]
	v_mfma_f32_16x16x32_bf16 v[58:61], v[156:159], v[164:167], v[58:61]
	v_mfma_f32_16x16x32_bf16 v[46:49], v[148:151], v[172:175], v[46:49]
	v_mfma_f32_16x16x32_bf16 v[42:45], v[156:159], v[172:175], v[42:45]
	v_mfma_f32_16x16x32_bf16 v[30:33], v[148:151], v[180:183], v[30:33]
	v_mfma_f32_16x16x32_bf16 v[26:29], v[156:159], v[180:183], v[26:29]
	v_mfma_f32_16x16x32_bf16 v[14:17], v[148:151], v[188:191], v[14:17]
	v_mfma_f32_16x16x32_bf16 v[10:13], v[156:159], v[188:191], v[10:13]
	s_barrier
	s_setprio 0
	s_add_i32 s6, s7, s54
	v_lshl_add_u64 v[140:141], v[134:135], 0, s[16:17]
	s_mov_b32 m0, s6
	v_lshl_add_u64 v[134:135], v[134:135], 0, s[80:81]
	global_load_lds_dwordx4 v[140:141], off
	s_add_i32 m0, s6, 0x2000
	s_nop 0
	global_load_lds_dwordx4 v[134:135], off
	s_waitcnt vmcnt(6)
	s_add_i32 s87, s87, 2
	s_add_u32 s41, s41, 0x100
	s_addc_u32 s86, s86, 0
	s_cmp_gt_u32 s87, 29
	s_mov_b64 s[6:7], s[8:9]
	s_cbranch_scc0 .LBB0_694
	s_setprio 1
	s_barrier
	v_mfma_f32_16x16x32_bf16 v[54:57], v[192:195], v[160:163], v[54:57]
	v_mfma_f32_16x16x32_bf16 v[50:53], v[200:203], v[160:163], v[50:53]
	v_mfma_f32_16x16x32_bf16 v[38:41], v[192:195], v[168:171], v[38:41]
	v_mfma_f32_16x16x32_bf16 v[34:37], v[200:203], v[168:171], v[34:37]
	v_mfma_f32_16x16x32_bf16 v[22:25], v[192:195], v[176:179], v[22:25]
	v_mfma_f32_16x16x32_bf16 v[18:21], v[200:203], v[176:179], v[18:21]
	v_mfma_f32_16x16x32_bf16 v[6:9], v[192:195], v[184:187], v[6:9]
	v_mfma_f32_16x16x32_bf16 v[2:5], v[200:203], v[184:187], v[2:5]
	v_mfma_f32_16x16x32_bf16 v[54:57], v[196:199], v[164:167], v[54:57]
	v_mfma_f32_16x16x32_bf16 v[50:53], v[204:207], v[164:167], v[50:53]
	v_mfma_f32_16x16x32_bf16 v[38:41], v[196:199], v[172:175], v[38:41]
	v_mfma_f32_16x16x32_bf16 v[34:37], v[204:207], v[172:175], v[34:37]
	v_mfma_f32_16x16x32_bf16 v[22:25], v[196:199], v[180:183], v[22:25]
	v_mfma_f32_16x16x32_bf16 v[18:21], v[204:207], v[180:183], v[18:21]
	v_mfma_f32_16x16x32_bf16 v[6:9], v[196:199], v[188:191], v[6:9]
	v_mfma_f32_16x16x32_bf16 v[2:5], v[204:207], v[188:191], v[2:5]
	s_barrier
	s_setprio 0
	v_mov_b32_e32 v134, v136
	s_lshl_b32 s6, s48, 8
	s_add_i32 s6, s6, s10
	v_and_or_b32 v139, v134, 15, s6
	s_lshl_b32 s6, s85, 7
	v_ashrrev_i32_e32 v134, 1, v134
	s_or_b32 s6, s6, s62
	v_and_b32_e32 v134, -8, v134
	v_add_u32_e32 v140, s6, v134
	v_mul_f32_e32 v134, 0xbfb8aa3b, v126
	v_exp_f32_e32 v142, v134
	v_mul_f32_e32 v134, 0xbfb8aa3b, v127
	v_exp_f32_e32 v143, v134
	v_ashrrev_i32_e32 v141, 31, v140
	v_add_f32_e32 v142, 1.0, v142
	v_rcp_f32_e32 v144, v142
	v_add_f32_e32 v142, 1.0, v143
	v_rcp_f32_e32 v145, v142
	v_mov_b64_e32 v[134:135], s[4:5]
	v_mul_f32_e32 v126, v126, v144
	v_mul_f32_e32 v118, v126, v118
	v_mul_f32_e32 v126, v127, v145
	v_mul_f32_e32 v127, 0xbfb8aa3b, v128
	v_exp_f32_e32 v127, v127
	v_mul_f32_e32 v144, 0xbfb8aa3b, v129
	v_exp_f32_e32 v144, v144
	v_mul_f32_e32 v119, v126, v119
	v_add_f32_e32 v126, 1.0, v127
	v_rcp_f32_e32 v126, v126
	v_add_f32_e32 v127, 1.0, v144
	v_mul_f32_e32 v144, 0xbfb8aa3b, v122
	v_rcp_f32_e32 v127, v127
	v_exp_f32_e32 v144, v144
	v_mul_f32_e32 v126, v128, v126
	v_mul_f32_e32 v126, v126, v120
	v_mul_f32_e32 v120, v129, v127
	v_add_f32_e32 v127, 1.0, v144
	v_rcp_f32_e32 v127, v127
	v_mul_f32_e32 v128, 0xbfb8aa3b, v123
	v_mul_f32_e32 v129, v120, v121
	v_exp_f32_e32 v128, v128
	v_mul_f32_e32 v120, v122, v127
	v_mul_f32_e32 v122, v120, v114
	v_mul_f32_e32 v120, 0xbfb8aa3b, v124
	v_exp_f32_e32 v120, v120
	v_mul_f32_e32 v121, 0xbfb8aa3b, v125
	v_exp_f32_e32 v121, v121
	v_add_f32_e32 v114, 1.0, v128
	v_rcp_f32_e32 v114, v114
	v_add_f32_e32 v120, 1.0, v120
	v_rcp_f32_e32 v120, v120
	v_add_f32_e32 v121, 1.0, v121
	v_rcp_f32_e32 v121, v121
	v_mul_f32_e32 v114, v123, v114
	v_mul_f32_e32 v123, v114, v115
	v_mul_f32_e32 v114, v124, v120
	v_mul_f32_e32 v124, v114, v116
	v_mul_f32_e32 v114, v125, v121
	v_mad_i64_i32 v[142:143], s[6:7], v139, s74, v[134:135]
	v_mul_f32_e32 v125, v114, v117
	v_lshlrev_b64 v[114:115], 1, v[140:141]
	v_lshl_add_u64 v[120:121], v[142:143], 0, v[114:115]
	v_cvt_pk_bf16_f32 v116, v118, v119
	v_cvt_pk_bf16_f32 v117, v126, v129
	v_cvt_pk_bf16_f32 v118, v122, v123
	v_cvt_pk_bf16_f32 v119, v124, v125
	global_store_dwordx4 v[120:121], v[116:119], off
	s_and_b64 vcc, exec, s[42:43]
	s_mov_b32 s48, s40
	v_mul_f32_e32 v116, 0xbfb8aa3b, v110
	v_exp_f32_e32 v116, v116
	v_mul_f32_e32 v117, 0xbfb8aa3b, v111
	v_exp_f32_e32 v117, v117
	v_or_b32_e32 v118, 16, v139
	v_add_f32_e32 v116, 1.0, v116
	v_rcp_f32_e32 v119, v116
	v_add_f32_e32 v116, 1.0, v117
	v_rcp_f32_e32 v120, v116
	v_mad_i64_i32 v[116:117], s[6:7], v118, s74, v[134:135]
	v_mul_f32_e32 v110, v110, v119
	v_mul_f32_e32 v110, v110, v102
	v_mul_f32_e32 v102, v111, v120
	v_mul_f32_e32 v111, 0xbfb8aa3b, v112
	v_exp_f32_e32 v111, v111
	v_mul_f32_e32 v118, 0xbfb8aa3b, v113
	v_exp_f32_e32 v118, v118
	v_mul_f32_e32 v119, v102, v103
	v_add_f32_e32 v102, 1.0, v111
	v_rcp_f32_e32 v102, v102
	v_add_f32_e32 v103, 1.0, v118
	v_mul_f32_e32 v111, 0xbfb8aa3b, v106
	v_rcp_f32_e32 v103, v103
	v_exp_f32_e32 v111, v111
	v_mul_f32_e32 v102, v112, v102
	v_mul_f32_e32 v104, v102, v104
	v_mul_f32_e32 v102, v113, v103
	v_add_f32_e32 v103, 1.0, v111
	v_rcp_f32_e32 v103, v103
	v_mul_f32_e32 v111, 0xbfb8aa3b, v107
	v_mul_f32_e32 v105, v102, v105
	v_exp_f32_e32 v111, v111
	v_mul_f32_e32 v102, v106, v103
	v_mul_f32_e32 v106, v102, v98
	v_mul_f32_e32 v102, 0xbfb8aa3b, v108
	v_exp_f32_e32 v102, v102
	v_mul_f32_e32 v103, 0xbfb8aa3b, v109
	v_exp_f32_e32 v103, v103
	v_add_f32_e32 v98, 1.0, v111
	v_rcp_f32_e32 v98, v98
	v_add_f32_e32 v102, 1.0, v102
	v_rcp_f32_e32 v102, v102
	v_add_f32_e32 v103, 1.0, v103
	v_rcp_f32_e32 v103, v103
	v_mul_f32_e32 v98, v107, v98
	v_mul_f32_e32 v107, v98, v99
	v_mul_f32_e32 v98, v108, v102
	v_mul_f32_e32 v108, v98, v100
	v_mul_f32_e32 v98, v109, v103
	v_mul_f32_e32 v101, v98, v101
	v_lshl_add_u64 v[102:103], v[116:117], 0, v[114:115]
	v_cvt_pk_bf16_f32 v98, v110, v119
	v_cvt_pk_bf16_f32 v99, v104, v105
	v_cvt_pk_bf16_f32 v100, v106, v107
	v_cvt_pk_bf16_f32 v101, v108, v101
	global_store_dwordx4 v[102:103], v[98:101], off
	s_mov_b32 s85, s84
	s_mov_b64 s[8:9], s[46:47]
	v_mul_f32_e32 v98, 0xbfb8aa3b, v94
	v_exp_f32_e32 v98, v98
	v_mul_f32_e32 v99, 0xbfb8aa3b, v95
	v_exp_f32_e32 v99, v99
	v_or_b32_e32 v100, 32, v139
	v_add_f32_e32 v98, 1.0, v98
	v_rcp_f32_e32 v101, v98
	v_add_f32_e32 v98, 1.0, v99
	v_rcp_f32_e32 v102, v98
	v_mad_i64_i32 v[98:99], s[6:7], v100, s74, v[134:135]
	v_mul_f32_e32 v94, v94, v101
	v_mul_f32_e32 v94, v94, v86
	v_mul_f32_e32 v86, v95, v102
	v_mul_f32_e32 v95, 0xbfb8aa3b, v96
	v_exp_f32_e32 v95, v95
	v_mul_f32_e32 v100, 0xbfb8aa3b, v97
	v_exp_f32_e32 v100, v100
	v_mul_f32_e32 v101, v86, v87
	v_add_f32_e32 v86, 1.0, v95
	v_rcp_f32_e32 v86, v86
	v_add_f32_e32 v87, 1.0, v100
	v_mul_f32_e32 v95, 0xbfb8aa3b, v90
	v_rcp_f32_e32 v87, v87
	v_exp_f32_e32 v95, v95
	v_mul_f32_e32 v86, v96, v86
	v_mul_f32_e32 v88, v86, v88
	v_mul_f32_e32 v86, v97, v87
	v_add_f32_e32 v87, 1.0, v95
	v_rcp_f32_e32 v87, v87
	v_mul_f32_e32 v95, 0xbfb8aa3b, v91
	v_mul_f32_e32 v89, v86, v89
	v_exp_f32_e32 v95, v95
	v_mul_f32_e32 v86, v90, v87
	v_mul_f32_e32 v90, v86, v82
	v_mul_f32_e32 v86, 0xbfb8aa3b, v92
	v_exp_f32_e32 v86, v86
	v_mul_f32_e32 v87, 0xbfb8aa3b, v93
	v_exp_f32_e32 v87, v87
	v_add_f32_e32 v82, 1.0, v95
	v_rcp_f32_e32 v82, v82
	v_add_f32_e32 v86, 1.0, v86
	v_rcp_f32_e32 v86, v86
	v_add_f32_e32 v87, 1.0, v87
	v_rcp_f32_e32 v87, v87
	v_mul_f32_e32 v82, v91, v82
	v_mul_f32_e32 v91, v82, v83
	v_mul_f32_e32 v82, v92, v86
	v_mul_f32_e32 v92, v82, v84
	v_mul_f32_e32 v82, v93, v87
	v_mul_f32_e32 v85, v82, v85
	v_lshl_add_u64 v[86:87], v[98:99], 0, v[114:115]
	v_cvt_pk_bf16_f32 v82, v94, v101
	v_cvt_pk_bf16_f32 v83, v88, v89
	v_cvt_pk_bf16_f32 v84, v90, v91
	v_cvt_pk_bf16_f32 v85, v92, v85
	global_store_dwordx4 v[86:87], v[82:85], off
	s_nop 1
	v_mul_f32_e32 v82, 0xbfb8aa3b, v78
	v_exp_f32_e32 v82, v82
	v_mul_f32_e32 v83, 0xbfb8aa3b, v79
	v_exp_f32_e32 v83, v83
	v_or_b32_e32 v84, 48, v139
	v_add_f32_e32 v82, 1.0, v82
	v_rcp_f32_e32 v85, v82
	v_add_f32_e32 v82, 1.0, v83
	v_rcp_f32_e32 v86, v82
	v_mad_i64_i32 v[82:83], s[6:7], v84, s74, v[134:135]
	v_mul_f32_e32 v78, v78, v85
	v_mul_f32_e32 v78, v78, v70
	v_mul_f32_e32 v70, v79, v86
	v_mul_f32_e32 v79, 0xbfb8aa3b, v80
	v_exp_f32_e32 v79, v79
	v_mul_f32_e32 v84, 0xbfb8aa3b, v81
	v_exp_f32_e32 v84, v84
	v_mul_f32_e32 v85, v70, v71
	v_add_f32_e32 v70, 1.0, v79
	v_rcp_f32_e32 v70, v70
	v_add_f32_e32 v71, 1.0, v84
	v_mul_f32_e32 v79, 0xbfb8aa3b, v74
	v_rcp_f32_e32 v71, v71
	v_exp_f32_e32 v79, v79
	v_mul_f32_e32 v70, v80, v70
	v_mul_f32_e32 v72, v70, v72
	v_mul_f32_e32 v70, v81, v71
	v_add_f32_e32 v71, 1.0, v79
	v_rcp_f32_e32 v71, v71
	v_mul_f32_e32 v79, 0xbfb8aa3b, v75
	v_mul_f32_e32 v73, v70, v73
	v_exp_f32_e32 v79, v79
	v_mul_f32_e32 v70, v74, v71
	v_mul_f32_e32 v74, v70, v66
	v_mul_f32_e32 v70, 0xbfb8aa3b, v76
	v_exp_f32_e32 v70, v70
	v_mul_f32_e32 v71, 0xbfb8aa3b, v77
	v_exp_f32_e32 v71, v71
	v_add_f32_e32 v66, 1.0, v79
	v_rcp_f32_e32 v66, v66
	v_add_f32_e32 v70, 1.0, v70
	v_rcp_f32_e32 v70, v70
	v_add_f32_e32 v71, 1.0, v71
	v_rcp_f32_e32 v71, v71
	v_mul_f32_e32 v66, v75, v66
	v_mul_f32_e32 v75, v66, v67
	v_mul_f32_e32 v66, v76, v70
	v_mul_f32_e32 v76, v66, v68
	v_mul_f32_e32 v66, v77, v71
	v_mul_f32_e32 v69, v66, v69
	v_lshl_add_u64 v[70:71], v[82:83], 0, v[114:115]
	v_cvt_pk_bf16_f32 v66, v78, v85
	v_cvt_pk_bf16_f32 v67, v72, v73
	v_cvt_pk_bf16_f32 v68, v74, v75
	v_cvt_pk_bf16_f32 v69, v76, v69
	global_store_dwordx4 v[70:71], v[66:69], off
	s_nop 1
	v_mul_f32_e32 v66, 0xbfb8aa3b, v62
	v_exp_f32_e32 v66, v66
	v_mul_f32_e32 v67, 0xbfb8aa3b, v63
	v_exp_f32_e32 v67, v67
	v_add_u32_e32 v68, 0x80, v139
	v_add_f32_e32 v66, 1.0, v66
	v_rcp_f32_e32 v69, v66
	v_add_f32_e32 v66, 1.0, v67
	v_rcp_f32_e32 v70, v66
	v_mad_i64_i32 v[66:67], s[6:7], v68, s74, v[134:135]
	v_mul_f32_e32 v62, v62, v69
	v_mul_f32_e32 v62, v62, v54
	v_mul_f32_e32 v54, v63, v70
	v_mul_f32_e32 v63, 0xbfb8aa3b, v64
	v_exp_f32_e32 v63, v63
	v_mul_f32_e32 v68, 0xbfb8aa3b, v65
	v_exp_f32_e32 v68, v68
	v_mul_f32_e32 v69, v54, v55
	v_add_f32_e32 v54, 1.0, v63
	v_rcp_f32_e32 v54, v54
	v_add_f32_e32 v55, 1.0, v68
	v_mul_f32_e32 v63, 0xbfb8aa3b, v58
	v_rcp_f32_e32 v55, v55
	v_exp_f32_e32 v63, v63
	v_mul_f32_e32 v54, v64, v54
	v_mul_f32_e32 v56, v54, v56
	v_mul_f32_e32 v54, v65, v55
	v_add_f32_e32 v55, 1.0, v63
	v_rcp_f32_e32 v55, v55
	v_mul_f32_e32 v63, 0xbfb8aa3b, v59
	v_mul_f32_e32 v57, v54, v57
	v_exp_f32_e32 v63, v63
	v_mul_f32_e32 v54, v58, v55
	v_mul_f32_e32 v58, v54, v50
	v_mul_f32_e32 v54, 0xbfb8aa3b, v60
	v_exp_f32_e32 v54, v54
	v_mul_f32_e32 v55, 0xbfb8aa3b, v61
	v_exp_f32_e32 v55, v55
	v_add_f32_e32 v50, 1.0, v63
	v_rcp_f32_e32 v50, v50
	v_add_f32_e32 v54, 1.0, v54
	v_rcp_f32_e32 v54, v54
	v_add_f32_e32 v55, 1.0, v55
	v_rcp_f32_e32 v55, v55
	v_mul_f32_e32 v50, v59, v50
	v_mul_f32_e32 v59, v50, v51
	v_mul_f32_e32 v50, v60, v54
	v_mul_f32_e32 v60, v50, v52
	v_mul_f32_e32 v50, v61, v55
	v_mul_f32_e32 v53, v50, v53
	v_lshl_add_u64 v[54:55], v[66:67], 0, v[114:115]
	v_cvt_pk_bf16_f32 v50, v62, v69
	v_cvt_pk_bf16_f32 v51, v56, v57
	v_cvt_pk_bf16_f32 v52, v58, v59
	v_cvt_pk_bf16_f32 v53, v60, v53
	global_store_dwordx4 v[54:55], v[50:53], off
	s_nop 1
	v_mul_f32_e32 v50, 0xbfb8aa3b, v46
	v_exp_f32_e32 v50, v50
	v_mul_f32_e32 v51, 0xbfb8aa3b, v47
	v_exp_f32_e32 v51, v51
	v_add_u32_e32 v52, 0x90, v139
	v_add_f32_e32 v50, 1.0, v50
	v_rcp_f32_e32 v53, v50
	v_add_f32_e32 v50, 1.0, v51
	v_rcp_f32_e32 v54, v50
	v_mad_i64_i32 v[50:51], s[6:7], v52, s74, v[134:135]
	v_mul_f32_e32 v46, v46, v53
	v_mul_f32_e32 v46, v46, v38
	v_mul_f32_e32 v38, v47, v54
	v_mul_f32_e32 v47, 0xbfb8aa3b, v48
	v_exp_f32_e32 v47, v47
	v_mul_f32_e32 v52, 0xbfb8aa3b, v49
	v_exp_f32_e32 v52, v52
	v_mul_f32_e32 v53, v38, v39
	v_add_f32_e32 v38, 1.0, v47
	v_rcp_f32_e32 v38, v38
	v_add_f32_e32 v39, 1.0, v52
	v_mul_f32_e32 v47, 0xbfb8aa3b, v42
	v_rcp_f32_e32 v39, v39
	v_exp_f32_e32 v47, v47
	v_mul_f32_e32 v38, v48, v38
	v_mul_f32_e32 v40, v38, v40
	v_mul_f32_e32 v38, v49, v39
	v_add_f32_e32 v39, 1.0, v47
	v_rcp_f32_e32 v39, v39
	v_mul_f32_e32 v47, 0xbfb8aa3b, v43
	v_mul_f32_e32 v41, v38, v41
	v_exp_f32_e32 v47, v47
	v_mul_f32_e32 v38, v42, v39
	v_mul_f32_e32 v42, v38, v34
	v_mul_f32_e32 v38, 0xbfb8aa3b, v44
	v_exp_f32_e32 v38, v38
	v_mul_f32_e32 v39, 0xbfb8aa3b, v45
	v_exp_f32_e32 v39, v39
	v_add_f32_e32 v34, 1.0, v47
	v_rcp_f32_e32 v34, v34
	v_add_f32_e32 v38, 1.0, v38
	v_rcp_f32_e32 v38, v38
	v_add_f32_e32 v39, 1.0, v39
	v_rcp_f32_e32 v39, v39
	v_mul_f32_e32 v34, v43, v34
	v_mul_f32_e32 v43, v34, v35
	v_mul_f32_e32 v34, v44, v38
	v_mul_f32_e32 v44, v34, v36
	v_mul_f32_e32 v34, v45, v39
	v_mul_f32_e32 v37, v34, v37
	v_lshl_add_u64 v[38:39], v[50:51], 0, v[114:115]
	v_cvt_pk_bf16_f32 v34, v46, v53
	v_cvt_pk_bf16_f32 v35, v40, v41
	v_cvt_pk_bf16_f32 v36, v42, v43
	v_cvt_pk_bf16_f32 v37, v44, v37
	global_store_dwordx4 v[38:39], v[34:37], off
	s_nop 1
	v_mul_f32_e32 v34, 0xbfb8aa3b, v30
	v_exp_f32_e32 v34, v34
	v_mul_f32_e32 v35, 0xbfb8aa3b, v31
	v_exp_f32_e32 v35, v35
	v_add_u32_e32 v36, 0xa0, v139
	v_add_f32_e32 v34, 1.0, v34
	v_rcp_f32_e32 v37, v34
	v_add_f32_e32 v34, 1.0, v35
	v_rcp_f32_e32 v38, v34
	v_mad_i64_i32 v[34:35], s[6:7], v36, s74, v[134:135]
	v_mul_f32_e32 v30, v30, v37
	v_mul_f32_e32 v30, v30, v22
	v_mul_f32_e32 v22, v31, v38
	v_mul_f32_e32 v31, 0xbfb8aa3b, v32
	v_exp_f32_e32 v31, v31
	v_mul_f32_e32 v36, 0xbfb8aa3b, v33
	v_exp_f32_e32 v36, v36
	v_mul_f32_e32 v37, v22, v23
	v_add_f32_e32 v22, 1.0, v31
	v_rcp_f32_e32 v22, v22
	v_add_f32_e32 v23, 1.0, v36
	v_mul_f32_e32 v31, 0xbfb8aa3b, v26
	v_rcp_f32_e32 v23, v23
	v_exp_f32_e32 v31, v31
	v_mul_f32_e32 v22, v32, v22
	v_mul_f32_e32 v24, v22, v24
	v_mul_f32_e32 v22, v33, v23
	v_add_f32_e32 v23, 1.0, v31
	v_rcp_f32_e32 v23, v23
	v_mul_f32_e32 v31, 0xbfb8aa3b, v27
	v_mul_f32_e32 v25, v22, v25
	v_exp_f32_e32 v31, v31
	v_mul_f32_e32 v22, v26, v23
	v_mul_f32_e32 v26, v22, v18
	v_mul_f32_e32 v22, 0xbfb8aa3b, v28
	v_exp_f32_e32 v22, v22
	v_mul_f32_e32 v23, 0xbfb8aa3b, v29
	v_exp_f32_e32 v23, v23
	v_add_f32_e32 v18, 1.0, v31
	v_rcp_f32_e32 v18, v18
	v_add_f32_e32 v22, 1.0, v22
	v_rcp_f32_e32 v22, v22
	v_add_f32_e32 v23, 1.0, v23
	v_rcp_f32_e32 v23, v23
	v_mul_f32_e32 v18, v27, v18
	v_mul_f32_e32 v27, v18, v19
	v_mul_f32_e32 v18, v28, v22
	v_mul_f32_e32 v28, v18, v20
	v_mul_f32_e32 v18, v29, v23
	v_mul_f32_e32 v21, v18, v21
	v_lshl_add_u64 v[22:23], v[34:35], 0, v[114:115]
	v_cvt_pk_bf16_f32 v18, v30, v37
	v_cvt_pk_bf16_f32 v19, v24, v25
	v_cvt_pk_bf16_f32 v20, v26, v27
	v_cvt_pk_bf16_f32 v21, v28, v21
	global_store_dwordx4 v[22:23], v[18:21], off
	s_nop 1
	v_mul_f32_e32 v18, 0xbfb8aa3b, v14
	v_exp_f32_e32 v18, v18
	v_mul_f32_e32 v19, 0xbfb8aa3b, v15
	v_exp_f32_e32 v19, v19
	v_add_u32_e32 v20, 0xb0, v139
	v_add_f32_e32 v18, 1.0, v18
	v_rcp_f32_e32 v21, v18
	v_add_f32_e32 v18, 1.0, v19
	v_rcp_f32_e32 v22, v18
	v_mad_i64_i32 v[18:19], s[6:7], v20, s74, v[134:135]
	v_mul_f32_e32 v14, v14, v21
	v_mul_f32_e32 v14, v14, v6
	v_mul_f32_e32 v6, v15, v22
	v_mul_f32_e32 v15, 0xbfb8aa3b, v16
	v_exp_f32_e32 v15, v15
	v_mul_f32_e32 v20, 0xbfb8aa3b, v17
	v_exp_f32_e32 v20, v20
	v_mul_f32_e32 v21, v6, v7
	v_add_f32_e32 v6, 1.0, v15
	v_rcp_f32_e32 v6, v6
	v_add_f32_e32 v7, 1.0, v20
	v_mul_f32_e32 v15, 0xbfb8aa3b, v10
	v_rcp_f32_e32 v7, v7
	v_exp_f32_e32 v15, v15
	v_mul_f32_e32 v6, v16, v6
	v_mul_f32_e32 v8, v6, v8
	v_mul_f32_e32 v6, v17, v7
	v_add_f32_e32 v7, 1.0, v15
	v_rcp_f32_e32 v7, v7
	v_mul_f32_e32 v15, 0xbfb8aa3b, v11
	v_mul_f32_e32 v9, v6, v9
	v_exp_f32_e32 v15, v15
	v_mul_f32_e32 v6, v10, v7
	v_mul_f32_e32 v10, v6, v2
	v_mul_f32_e32 v6, 0xbfb8aa3b, v12
	v_exp_f32_e32 v6, v6
	v_mul_f32_e32 v7, 0xbfb8aa3b, v13
	v_exp_f32_e32 v7, v7
	v_add_f32_e32 v2, 1.0, v15
	v_rcp_f32_e32 v2, v2
	v_add_f32_e32 v6, 1.0, v6
	v_rcp_f32_e32 v6, v6
	v_add_f32_e32 v7, 1.0, v7
	v_rcp_f32_e32 v7, v7
	v_mul_f32_e32 v2, v11, v2
	v_mul_f32_e32 v11, v2, v3
	v_mul_f32_e32 v2, v12, v6
	v_mul_f32_e32 v12, v2, v4
	v_mul_f32_e32 v2, v13, v7
	v_mul_f32_e32 v5, v2, v5
	v_lshl_add_u64 v[6:7], v[18:19], 0, v[114:115]
	s_mov_b64 s[6:7], s[44:45]
	v_cvt_pk_bf16_f32 v2, v14, v21
	v_cvt_pk_bf16_f32 v3, v8, v9
	v_cvt_pk_bf16_f32 v4, v10, v11
	v_cvt_pk_bf16_f32 v5, v12, v5
	global_store_dwordx4 v[6:7], v[2:5], off
	s_cbranch_vccz .LBB0_691
	s_waitcnt vmcnt(0)
	v_readlane_b32 s0, v255, 8
	v_readlane_b32 s62, v255, 10
	v_readlane_b32 s84, v255, 12
	v_readlane_b32 s44, v255, 26
	s_cmpk_gt_u32 s22, 0xff
	v_readlane_b32 s1, v255, 9
	s_mov_b64 s[58:59], s[92:93]
	v_readlane_b32 s63, v255, 11
	v_readlane_b32 s85, v255, 13
	v_readlane_b32 s45, v255, 27
	s_cbranch_scc1 .LBB0_698
	s_barrier
